# norm phases: rows mapped XCD-locally (waves of blocks with bid&7==x take batch x, the row-blocks the neighbouring GEMM phases process on the same blocks), 3 rows in flight per wave
# speedup vs baseline: 1.0098x; 1.0018x over previous
; DI void modnorm_rows(const Params& p, int l, int which  , bool from_inputs, bool skip_ctx, int w0, int wstride, int lane) {
;   const float* g = (which ? p.norm2_g : p.norm1_g) + l * DM;
;   f32x4 gg[4];
; #pragma unroll
;   for (int i = 0; i < 4; ++i) gg[i] = *(const f32x4*)(g + i * 256 + lane * 4);
;   const int nrows = skip_ctx ? 8 * NLAT : T_TOK;
;   auto rowof = [&](int i) -> int { return skip_ctx ? (i / NLAT) * TB + NCTX + (i % NLAT) : i; };
;   int i = w0;
;   if (i >= nrows) return;
;   f32x4 vn[4];
;   {
;     const int row = rowof(i); const float* src = xsrc_row(p, from_inputs, row / TB, row % TB);
; #pragma unroll
;     for (int q = 0; q < 4; ++q) vn[q] = *(const f32x4*)(src + q * 256 + lane * 4);
;   }
;   for (; i < nrows; i += wstride) {
;     const int row = rowof(i); const int b = row / TB, s = row % TB;
;     f32x4 v[4];
; #pragma unroll
;     for (int q = 0; q < 4; ++q) v[q] = vn[q];
;     if (i + wstride < nrows) {
;       const int rn = rowof(i + wstride); const float* src = xsrc_row(p, from_inputs, rn / TB, rn % TB);
; #pragma unroll
;       for (int q = 0; q < 4; ++q) vn[q] = *(const f32x4*)(src + q * 256 + lane * 4);
;     }
;     const float* mod = p.MOD + (size_t)(l * 9 + (s < NCTX ? 8 : b)) * 6144 + (which ? 3 * 1024 : 0);
;     f32x4 sh[4], sc[4];
; #pragma unroll
;     for (int q = 0; q < 4; ++q) { sh[q] = *(const f32x4*)(mod + q * 256 + lane * 4); sc[q] = *(const f32x4*)(mod + 1024 + q * 256 + lane * 4); }
.LBB0_228:
	s_andn2_b64 vcc, exec, s[0:1]
	s_cbranch_vccnz .LBB0_249
	v_readlane_b32 s0, v252, 9
	s_nop 1
	v_add_u32_e32 v1, s0, v158
	v_readlane_b32 s0, v250, 4
	v_readlane_b32 s1, v250, 5
	s_and_b64 s[0:1], s[0:1], exec
	s_movk_i32 s0, 0x4800
	s_cselect_b32 s26, 0x4000, s0
	v_cmp_gt_i32_e32 vcc, s26, v1
	s_and_saveexec_b64 s[2:3], vcc
	s_cbranch_execz .LBB0_248
	v_readlane_b32 s0, v252, 9
	v_lshlrev_b32_e32 v244, 4, v115
	v_lshlrev_b32_e32 v245, 3, v115
	v_add_u32_e32 v1, s0, v158
	s_nop 1
	v_readfirstlane_b32 s20, v1
	v_readlane_b32 s4, v254, 42
	v_readlane_b32 s5, v254, 43
	v_readlane_b32 s12, v254, 28
	v_readlane_b32 s13, v254, 29
	v_readlane_b32 s14, v254, 32
	v_readlane_b32 s15, v254, 33
	v_readlane_b32 s16, v253, 40
	v_readlane_b32 s17, v253, 41
	v_readlane_b32 s18, v250, 4
	v_readlane_b32 s19, v250, 5
	s_nop 3
	s_lshl_b32 s0, s49, 12
	s_add_u32 s4, s4, s0
	s_addc_u32 s5, s5, 0
	global_load_dwordx4 v[2:5], v244, s[4:5]
	global_load_dwordx4 v[6:9], v244, s[4:5] offset:1024
	global_load_dwordx4 v[10:13], v244, s[4:5] offset:2048
	global_load_dwordx4 v[14:17], v244, s[4:5] offset:3072
	s_mov_b32 s12, s56
	s_mov_b32 s13, s57
	s_mov_b32 s14, s64
	s_mov_b32 s15, s65
	s_cmp_lg_u64 s[18:19], 0
	s_cbranch_scc1 .Lnorm2_last
	s_lshr_b32 s39, s20, 5
	s_lshl_b32 s39, s39, 2
	s_and_b32 s38, s20, 3
	s_or_b32 s39, s39, s38
	s_lshr_b32 s38, s20, 2
	s_and_b32 s38, s38, 7
	s_mul_i32 s37, s38, 0x900
	s_add_i32 s37, s37, s39
	s_add_i32 s21, s37, 0
	s_mul_hi_u32 s7, s21, 0x38e38e39
	s_lshr_b32 s7, s7, 9
	s_mul_i32 s8, s7, 0x900
	s_sub_i32 s8, s21, s8
	s_lshl_b32 s9, s7, 11
	s_add_i32 s9, s9, s8
	s_add_i32 s9, s9, 0xffffff00
	s_lshl_b32 s10, s7, 8
	s_add_i32 s10, s10, s8
	s_cmpk_gt_i32 s8, 0xff
	s_cselect_b32 s9, s9, s10
	s_cselect_b32 s26, s12, s14
	s_cselect_b32 s27, s13, s15
	s_cselect_b32 s10, s7, 8
	s_lshl_b32 s9, s9, 12
	s_add_u32 s26, s26, s9
	s_addc_u32 s27, s27, 0
	s_add_i32 s10, s10, s82
	s_mul_i32 s10, s10, s24
	s_add_u32 s28, s58, s10
	s_addc_u32 s29, s59, 0
	s_add_u32 s28, s28, 0x3000
	s_addc_u32 s29, s29, 0
	s_add_u32 s0, s28, 0x1000
	s_addc_u32 s1, s29, 0
	global_load_dwordx4 v[18:21], v244, s[26:27]
	global_load_dwordx4 v[22:25], v244, s[26:27] offset:1024
	global_load_dwordx4 v[26:29], v244, s[26:27] offset:2048
	global_load_dwordx4 v[30:33], v244, s[26:27] offset:3072
	global_load_dwordx4 v[34:37], v244, s[28:29]
	global_load_dwordx4 v[38:41], v244, s[28:29] offset:1024
	global_load_dwordx4 v[42:45], v244, s[28:29] offset:2048
	global_load_dwordx4 v[46:49], v244, s[28:29] offset:3072
	global_load_dwordx4 v[50:53], v244, s[0:1]
	global_load_dwordx4 v[54:57], v244, s[0:1] offset:1024
	global_load_dwordx4 v[58:61], v244, s[0:1] offset:2048
	global_load_dwordx4 v[62:65], v244, s[0:1] offset:3072
	s_add_i32 s21, s37, 256
	s_mul_hi_u32 s7, s21, 0x38e38e39
	s_lshr_b32 s7, s7, 9
	s_mul_i32 s8, s7, 0x900
	s_sub_i32 s8, s21, s8
	s_lshl_b32 s9, s7, 11
	s_add_i32 s9, s9, s8
	s_add_i32 s9, s9, 0xffffff00
	s_lshl_b32 s10, s7, 8
	s_add_i32 s10, s10, s8
	s_cmpk_gt_i32 s8, 0xff
	s_cselect_b32 s9, s9, s10
	s_cselect_b32 s26, s12, s14
	s_cselect_b32 s27, s13, s15
	s_cselect_b32 s10, s7, 8
	s_lshl_b32 s9, s9, 12
	s_add_u32 s26, s26, s9
	s_addc_u32 s27, s27, 0
	s_add_i32 s10, s10, s82
	s_mul_i32 s10, s10, s24
	s_add_u32 s28, s58, s10
	s_addc_u32 s29, s59, 0
	s_add_u32 s28, s28, 0x3000
	s_addc_u32 s29, s29, 0
	s_add_u32 s0, s28, 0x1000
	s_addc_u32 s1, s29, 0
	global_load_dwordx4 v[66:69], v244, s[26:27]
	global_load_dwordx4 v[70:73], v244, s[26:27] offset:1024
	global_load_dwordx4 v[74:77], v244, s[26:27] offset:2048
	global_load_dwordx4 v[78:81], v244, s[26:27] offset:3072
	global_load_dwordx4 v[82:85], v244, s[28:29]
	global_load_dwordx4 v[86:89], v244, s[28:29] offset:1024
	global_load_dwordx4 v[90:93], v244, s[28:29] offset:2048
	global_load_dwordx4 v[94:97], v244, s[28:29] offset:3072
	global_load_dwordx4 v[98:101], v244, s[0:1]
	global_load_dwordx4 v[102:105], v244, s[0:1] offset:1024
	global_load_dwordx4 v[106:109], v244, s[0:1] offset:2048
	global_load_dwordx4 v[118:121], v244, s[0:1] offset:3072
	s_add_i32 s21, s37, 512
	s_mul_hi_u32 s7, s21, 0x38e38e39
	s_lshr_b32 s7, s7, 9
	s_mul_i32 s8, s7, 0x900
	s_sub_i32 s8, s21, s8
	s_lshl_b32 s9, s7, 11
	s_add_i32 s9, s9, s8
	s_add_i32 s9, s9, 0xffffff00
	s_lshl_b32 s10, s7, 8
	s_add_i32 s10, s10, s8
	s_cmpk_gt_i32 s8, 0xff
	s_cselect_b32 s9, s9, s10
	s_cselect_b32 s26, s12, s14
	s_cselect_b32 s27, s13, s15
	s_cselect_b32 s10, s7, 8
	s_lshl_b32 s9, s9, 12
	s_add_u32 s26, s26, s9
	s_addc_u32 s27, s27, 0
	s_add_i32 s10, s10, s82
	s_mul_i32 s10, s10, s24
	s_add_u32 s28, s58, s10
	s_addc_u32 s29, s59, 0
	s_add_u32 s28, s28, 0x3000
	s_addc_u32 s29, s29, 0
	s_add_u32 s0, s28, 0x1000
	s_addc_u32 s1, s29, 0
	global_load_dwordx4 v[122:125], v244, s[26:27]
	global_load_dwordx4 v[126:129], v244, s[26:27] offset:1024
	global_load_dwordx4 v[130:133], v244, s[26:27] offset:2048
	global_load_dwordx4 v[134:137], v244, s[26:27] offset:3072
	global_load_dwordx4 v[160:163], v244, s[28:29]
	global_load_dwordx4 v[164:167], v244, s[28:29] offset:1024
	global_load_dwordx4 v[168:171], v244, s[28:29] offset:2048
	global_load_dwordx4 v[172:175], v244, s[28:29] offset:3072
	global_load_dwordx4 v[176:179], v244, s[0:1]
	global_load_dwordx4 v[180:183], v244, s[0:1] offset:1024
	global_load_dwordx4 v[184:187], v244, s[0:1] offset:2048
	global_load_dwordx4 v[188:191], v244, s[0:1] offset:3072
	s_waitcnt vmcnt(24)
; DI unsigned pk_bf16(float lo, float hi) { f32x2 v = {lo, hi}; bf16v2 b = __builtin_convertvector(v, bf16v2); return __builtin_bit_cast(unsigned, b); }
; DI float red64(float x) { for (int o = 32; o > 0; o >>= 1) x += __shfl_xor(x, o); return x; }
; DI void modnorm_rows(const Params& p, int l, int which  , bool from_inputs, bool skip_ctx, int w0, int wstride, int lane) {
;     ...
;     const int row = rowof(i); const int b = row / TB, s = row % TB;
;     f32x4 v[4];
; #pragma unroll
;     for (int q = 0; q < 4; ++q) v[q] = vn[q];
;     if (i + wstride < nrows) {
;       const int rn = rowof(i + wstride); const float* src = xsrc_row(p, from_inputs, rn / TB, rn % TB);
; #pragma unroll
;       for (int q = 0; q < 4; ++q) vn[q] = *(const f32x4*)(src + q * 256 + lane * 4);
;     }
;     const float* mod = p.MOD + (size_t)(l * 9 + (s < NCTX ? 8 : b)) * 6144 + (which ? 3 * 1024 : 0);
;     f32x4 sh[4], sc[4];
; #pragma unroll
;     for (int q = 0; q < 4; ++q) { sh[q] = *(const f32x4*)(mod + q * 256 + lane * 4); sc[q] = *(const f32x4*)(mod + 1024 + q * 256 + lane * 4); }
;     float ss = 0.f;
; #pragma unroll
;     for (int q = 0; q < 4; ++q) ss += v[q][0] * v[q][0] + v[q][1] * v[q][1] + v[q][2] * v[q][2] + v[q][3] * v[q][3];
;     ss = red64(ss);
;     const float rs = rsqrtf(ss * (1.f / 1024.f) + EPSF);
;     bf16_t* dst = p.HY + (size_t)row * DM;
; #pragma unroll
;     for (int q = 0; q < 4; ++q) {
;       float o[4];
; #pragma unroll
;       for (int j = 0; j < 4; ++j) o[j] = (v[q][j] * rs * gg[q][j]) * (1.f + sc[q][j]) + sh[q][j];
;       u32x2 w = {pk_bf16(o[0], o[1]), pk_bf16(o[2], o[3])};
;       *(u32x2*)(dst + q * 256 + lane * 4) = w;
;     }
	v_pk_mul_f32 v[246:247], v[18:19], v[18:19]
	v_pk_fma_f32 v[246:247], v[20:21], v[20:21], v[246:247]
	v_pk_fma_f32 v[246:247], v[22:23], v[22:23], v[246:247]
	v_pk_fma_f32 v[246:247], v[24:25], v[24:25], v[246:247]
	v_pk_fma_f32 v[246:247], v[26:27], v[26:27], v[246:247]
	v_pk_fma_f32 v[246:247], v[28:29], v[28:29], v[246:247]
	v_pk_fma_f32 v[246:247], v[30:31], v[30:31], v[246:247]
	v_pk_fma_f32 v[246:247], v[32:33], v[32:33], v[246:247]
	s_nop 0
	v_add_f32_e32 v246, v246, v247
	s_nop 1
	v_add_f32_dpp v246, v246, v246 quad_perm:[1,0,3,2] row_mask:0xf bank_mask:0xf
	s_nop 1
	v_add_f32_dpp v246, v246, v246 quad_perm:[2,3,0,1] row_mask:0xf bank_mask:0xf
	s_nop 1
	v_add_f32_dpp v246, v246, v246 row_half_mirror row_mask:0xf bank_mask:0xf
	s_nop 1
	v_add_f32_dpp v246, v246, v246 row_mirror row_mask:0xf bank_mask:0xf
	s_nop 1
	v_add_f32_dpp v246, v246, v246 row_bcast:15 row_mask:0xa bank_mask:0xf
	s_nop 1
	v_add_f32_dpp v246, v246, v246 row_bcast:31 row_mask:0xc bank_mask:0xf
	s_nop 1
	v_readlane_b32 s0, v246, 63
	s_add_i32 s21, s37, 0
	s_lshl_b32 s21, s21, 11
	s_add_u32 s10, s16, s21
	s_addc_u32 s11, s17, 0
	v_mov_b32_e32 v248, s0
	v_fmamk_f32 v248, v248, 0x3a800000, v143
	v_rsq_f32_e32 v248, v248
	s_nop 0
	v_pk_mul_f32 v[18:19], v[18:19], v[248:249] op_sel_hi:[1,0]
	v_pk_add_f32 v[50:51], v[50:51], 1.0 op_sel_hi:[1,0]
	v_pk_mul_f32 v[18:19], v[2:3], v[18:19]
	v_pk_fma_f32 v[18:19], v[50:51], v[18:19], v[34:35]
	v_pk_mul_f32 v[20:21], v[20:21], v[248:249] op_sel_hi:[1,0]
	v_pk_add_f32 v[52:53], v[52:53], 1.0 op_sel_hi:[1,0]
	v_pk_mul_f32 v[20:21], v[4:5], v[20:21]
	v_pk_fma_f32 v[20:21], v[52:53], v[20:21], v[36:37]
	v_cvt_pk_bf16_f32 v34, v18, v19
	v_cvt_pk_bf16_f32 v35, v20, v21
	global_store_dwordx2 v245, v[34:35], s[10:11]
	v_pk_mul_f32 v[22:23], v[22:23], v[248:249] op_sel_hi:[1,0]
	v_pk_add_f32 v[54:55], v[54:55], 1.0 op_sel_hi:[1,0]
	v_pk_mul_f32 v[22:23], v[6:7], v[22:23]
	v_pk_fma_f32 v[22:23], v[54:55], v[22:23], v[38:39]
	v_pk_mul_f32 v[24:25], v[24:25], v[248:249] op_sel_hi:[1,0]
	v_pk_add_f32 v[56:57], v[56:57], 1.0 op_sel_hi:[1,0]
	v_pk_mul_f32 v[24:25], v[8:9], v[24:25]
	v_pk_fma_f32 v[24:25], v[56:57], v[24:25], v[40:41]
	v_cvt_pk_bf16_f32 v38, v22, v23
	v_cvt_pk_bf16_f32 v39, v24, v25
	global_store_dwordx2 v245, v[38:39], s[10:11] offset:512
	v_pk_mul_f32 v[26:27], v[26:27], v[248:249] op_sel_hi:[1,0]
	v_pk_add_f32 v[58:59], v[58:59], 1.0 op_sel_hi:[1,0]
	v_pk_mul_f32 v[26:27], v[10:11], v[26:27]
	v_pk_fma_f32 v[26:27], v[58:59], v[26:27], v[42:43]
	v_pk_mul_f32 v[28:29], v[28:29], v[248:249] op_sel_hi:[1,0]
	v_pk_add_f32 v[60:61], v[60:61], 1.0 op_sel_hi:[1,0]
	v_pk_mul_f32 v[28:29], v[12:13], v[28:29]
	v_pk_fma_f32 v[28:29], v[60:61], v[28:29], v[44:45]
	v_cvt_pk_bf16_f32 v42, v26, v27
	v_cvt_pk_bf16_f32 v43, v28, v29
	global_store_dwordx2 v245, v[42:43], s[10:11] offset:1024
	v_pk_mul_f32 v[30:31], v[30:31], v[248:249] op_sel_hi:[1,0]
	v_pk_add_f32 v[62:63], v[62:63], 1.0 op_sel_hi:[1,0]
	v_pk_mul_f32 v[30:31], v[14:15], v[30:31]
	v_pk_fma_f32 v[30:31], v[62:63], v[30:31], v[46:47]
	v_pk_mul_f32 v[32:33], v[32:33], v[248:249] op_sel_hi:[1,0]
	v_pk_add_f32 v[64:65], v[64:65], 1.0 op_sel_hi:[1,0]
	v_pk_mul_f32 v[32:33], v[16:17], v[32:33]
	v_pk_fma_f32 v[32:33], v[64:65], v[32:33], v[48:49]
	v_cvt_pk_bf16_f32 v46, v30, v31
	v_cvt_pk_bf16_f32 v47, v32, v33
	global_store_dwordx2 v245, v[46:47], s[10:11] offset:1536
	s_add_i32 s21, s37, 768
	s_mul_hi_u32 s7, s21, 0x38e38e39
	s_lshr_b32 s7, s7, 9
	s_mul_i32 s8, s7, 0x900
	s_sub_i32 s8, s21, s8
	s_lshl_b32 s9, s7, 11
	s_add_i32 s9, s9, s8
	s_add_i32 s9, s9, 0xffffff00
	s_lshl_b32 s10, s7, 8
	s_add_i32 s10, s10, s8
	s_cmpk_gt_i32 s8, 0xff
	s_cselect_b32 s9, s9, s10
	s_cselect_b32 s26, s12, s14
	s_cselect_b32 s27, s13, s15
	s_cselect_b32 s10, s7, 8
	s_lshl_b32 s9, s9, 12
	s_add_u32 s26, s26, s9
	s_addc_u32 s27, s27, 0
	s_add_i32 s10, s10, s82
	s_mul_i32 s10, s10, s24
	s_add_u32 s28, s58, s10
	s_addc_u32 s29, s59, 0
	s_add_u32 s28, s28, 0x3000
	s_addc_u32 s29, s29, 0
	s_add_u32 s0, s28, 0x1000
	s_addc_u32 s1, s29, 0
	global_load_dwordx4 v[18:21], v244, s[26:27]
	global_load_dwordx4 v[22:25], v244, s[26:27] offset:1024
	global_load_dwordx4 v[26:29], v244, s[26:27] offset:2048
	global_load_dwordx4 v[30:33], v244, s[26:27] offset:3072
	global_load_dwordx4 v[34:37], v244, s[28:29]
	global_load_dwordx4 v[38:41], v244, s[28:29] offset:1024
	global_load_dwordx4 v[42:45], v244, s[28:29] offset:2048
	global_load_dwordx4 v[46:49], v244, s[28:29] offset:3072
	global_load_dwordx4 v[50:53], v244, s[0:1]
	global_load_dwordx4 v[54:57], v244, s[0:1] offset:1024
	global_load_dwordx4 v[58:61], v244, s[0:1] offset:2048
	global_load_dwordx4 v[62:65], v244, s[0:1] offset:3072
	s_waitcnt vmcnt(28)
; DI unsigned pk_bf16(float lo, float hi) { f32x2 v = {lo, hi}; bf16v2 b = __builtin_convertvector(v, bf16v2); return __builtin_bit_cast(unsigned, b); }
; DI float red64(float x) { for (int o = 32; o > 0; o >>= 1) x += __shfl_xor(x, o); return x; }
; DI void modnorm_rows(const Params& p, int l, int which  , bool from_inputs, bool skip_ctx, int w0, int wstride, int lane) {
;     ...
;     const int row = rowof(i); const int b = row / TB, s = row % TB;
;     f32x4 v[4];
; #pragma unroll
;     for (int q = 0; q < 4; ++q) v[q] = vn[q];
;     if (i + wstride < nrows) {
;       const int rn = rowof(i + wstride); const float* src = xsrc_row(p, from_inputs, rn / TB, rn % TB);
; #pragma unroll
;       for (int q = 0; q < 4; ++q) vn[q] = *(const f32x4*)(src + q * 256 + lane * 4);
;     }
;     const float* mod = p.MOD + (size_t)(l * 9 + (s < NCTX ? 8 : b)) * 6144 + (which ? 3 * 1024 : 0);
;     f32x4 sh[4], sc[4];
; #pragma unroll
;     for (int q = 0; q < 4; ++q) { sh[q] = *(const f32x4*)(mod + q * 256 + lane * 4); sc[q] = *(const f32x4*)(mod + 1024 + q * 256 + lane * 4); }
;     float ss = 0.f;
; #pragma unroll
;     for (int q = 0; q < 4; ++q) ss += v[q][0] * v[q][0] + v[q][1] * v[q][1] + v[q][2] * v[q][2] + v[q][3] * v[q][3];
;     ss = red64(ss);
;     const float rs = rsqrtf(ss * (1.f / 1024.f) + EPSF);
;     bf16_t* dst = p.HY + (size_t)row * DM;
; #pragma unroll
;     for (int q = 0; q < 4; ++q) {
;       float o[4];
; #pragma unroll
;       for (int j = 0; j < 4; ++j) o[j] = (v[q][j] * rs * gg[q][j]) * (1.f + sc[q][j]) + sh[q][j];
;       u32x2 w = {pk_bf16(o[0], o[1]), pk_bf16(o[2], o[3])};
;       *(u32x2*)(dst + q * 256 + lane * 4) = w;
;     }
	v_pk_mul_f32 v[246:247], v[66:67], v[66:67]
	v_pk_fma_f32 v[246:247], v[68:69], v[68:69], v[246:247]
	v_pk_fma_f32 v[246:247], v[70:71], v[70:71], v[246:247]
	v_pk_fma_f32 v[246:247], v[72:73], v[72:73], v[246:247]
	v_pk_fma_f32 v[246:247], v[74:75], v[74:75], v[246:247]
	v_pk_fma_f32 v[246:247], v[76:77], v[76:77], v[246:247]
	v_pk_fma_f32 v[246:247], v[78:79], v[78:79], v[246:247]
	v_pk_fma_f32 v[246:247], v[80:81], v[80:81], v[246:247]
	s_nop 0
	v_add_f32_e32 v246, v246, v247
	s_nop 1
	v_add_f32_dpp v246, v246, v246 quad_perm:[1,0,3,2] row_mask:0xf bank_mask:0xf
	s_nop 1
	v_add_f32_dpp v246, v246, v246 quad_perm:[2,3,0,1] row_mask:0xf bank_mask:0xf
	s_nop 1
	v_add_f32_dpp v246, v246, v246 row_half_mirror row_mask:0xf bank_mask:0xf
	s_nop 1
	v_add_f32_dpp v246, v246, v246 row_mirror row_mask:0xf bank_mask:0xf
	s_nop 1
	v_add_f32_dpp v246, v246, v246 row_bcast:15 row_mask:0xa bank_mask:0xf
	s_nop 1
	v_add_f32_dpp v246, v246, v246 row_bcast:31 row_mask:0xc bank_mask:0xf
	s_nop 1
	v_readlane_b32 s0, v246, 63
	s_add_i32 s21, s37, 256
	s_lshl_b32 s21, s21, 11
	s_add_u32 s10, s16, s21
	s_addc_u32 s11, s17, 0
	v_mov_b32_e32 v248, s0
	v_fmamk_f32 v248, v248, 0x3a800000, v143
	v_rsq_f32_e32 v248, v248
	s_nop 0
	v_pk_mul_f32 v[66:67], v[66:67], v[248:249] op_sel_hi:[1,0]
	v_pk_add_f32 v[98:99], v[98:99], 1.0 op_sel_hi:[1,0]
	v_pk_mul_f32 v[66:67], v[2:3], v[66:67]
	v_pk_fma_f32 v[66:67], v[98:99], v[66:67], v[82:83]
	v_pk_mul_f32 v[68:69], v[68:69], v[248:249] op_sel_hi:[1,0]
	v_pk_add_f32 v[100:101], v[100:101], 1.0 op_sel_hi:[1,0]
	v_pk_mul_f32 v[68:69], v[4:5], v[68:69]
	v_pk_fma_f32 v[68:69], v[100:101], v[68:69], v[84:85]
	v_cvt_pk_bf16_f32 v82, v66, v67
	v_cvt_pk_bf16_f32 v83, v68, v69
	global_store_dwordx2 v245, v[82:83], s[10:11]
	v_pk_mul_f32 v[70:71], v[70:71], v[248:249] op_sel_hi:[1,0]
	v_pk_add_f32 v[102:103], v[102:103], 1.0 op_sel_hi:[1,0]
	v_pk_mul_f32 v[70:71], v[6:7], v[70:71]
	v_pk_fma_f32 v[70:71], v[102:103], v[70:71], v[86:87]
	v_pk_mul_f32 v[72:73], v[72:73], v[248:249] op_sel_hi:[1,0]
	v_pk_add_f32 v[104:105], v[104:105], 1.0 op_sel_hi:[1,0]
	v_pk_mul_f32 v[72:73], v[8:9], v[72:73]
	v_pk_fma_f32 v[72:73], v[104:105], v[72:73], v[88:89]
	v_cvt_pk_bf16_f32 v86, v70, v71
	v_cvt_pk_bf16_f32 v87, v72, v73
	global_store_dwordx2 v245, v[86:87], s[10:11] offset:512
	v_pk_mul_f32 v[74:75], v[74:75], v[248:249] op_sel_hi:[1,0]
	v_pk_add_f32 v[106:107], v[106:107], 1.0 op_sel_hi:[1,0]
	v_pk_mul_f32 v[74:75], v[10:11], v[74:75]
	v_pk_fma_f32 v[74:75], v[106:107], v[74:75], v[90:91]
	v_pk_mul_f32 v[76:77], v[76:77], v[248:249] op_sel_hi:[1,0]
	v_pk_add_f32 v[108:109], v[108:109], 1.0 op_sel_hi:[1,0]
	v_pk_mul_f32 v[76:77], v[12:13], v[76:77]
	v_pk_fma_f32 v[76:77], v[108:109], v[76:77], v[92:93]
	v_cvt_pk_bf16_f32 v90, v74, v75
	v_cvt_pk_bf16_f32 v91, v76, v77
	global_store_dwordx2 v245, v[90:91], s[10:11] offset:1024
	v_pk_mul_f32 v[78:79], v[78:79], v[248:249] op_sel_hi:[1,0]
	v_pk_add_f32 v[118:119], v[118:119], 1.0 op_sel_hi:[1,0]
	v_pk_mul_f32 v[78:79], v[14:15], v[78:79]
	v_pk_fma_f32 v[78:79], v[118:119], v[78:79], v[94:95]
	v_pk_mul_f32 v[80:81], v[80:81], v[248:249] op_sel_hi:[1,0]
	v_pk_add_f32 v[120:121], v[120:121], 1.0 op_sel_hi:[1,0]
	v_pk_mul_f32 v[80:81], v[16:17], v[80:81]
	v_pk_fma_f32 v[80:81], v[120:121], v[80:81], v[96:97]
	v_cvt_pk_bf16_f32 v94, v78, v79
	v_cvt_pk_bf16_f32 v95, v80, v81
	global_store_dwordx2 v245, v[94:95], s[10:11] offset:1536
	s_add_i32 s21, s37, 1024
	s_mul_hi_u32 s7, s21, 0x38e38e39
	s_lshr_b32 s7, s7, 9
	s_mul_i32 s8, s7, 0x900
	s_sub_i32 s8, s21, s8
	s_lshl_b32 s9, s7, 11
	s_add_i32 s9, s9, s8
	s_add_i32 s9, s9, 0xffffff00
	s_lshl_b32 s10, s7, 8
	s_add_i32 s10, s10, s8
	s_cmpk_gt_i32 s8, 0xff
	s_cselect_b32 s9, s9, s10
	s_cselect_b32 s26, s12, s14
	s_cselect_b32 s27, s13, s15
	s_cselect_b32 s10, s7, 8
	s_lshl_b32 s9, s9, 12
	s_add_u32 s26, s26, s9
	s_addc_u32 s27, s27, 0
	s_add_i32 s10, s10, s82
	s_mul_i32 s10, s10, s24
	s_add_u32 s28, s58, s10
	s_addc_u32 s29, s59, 0
	s_add_u32 s28, s28, 0x3000
	s_addc_u32 s29, s29, 0
	s_add_u32 s0, s28, 0x1000
	s_addc_u32 s1, s29, 0
	global_load_dwordx4 v[66:69], v244, s[26:27]
	global_load_dwordx4 v[70:73], v244, s[26:27] offset:1024
	global_load_dwordx4 v[74:77], v244, s[26:27] offset:2048
	global_load_dwordx4 v[78:81], v244, s[26:27] offset:3072
	global_load_dwordx4 v[82:85], v244, s[28:29]
	global_load_dwordx4 v[86:89], v244, s[28:29] offset:1024
	global_load_dwordx4 v[90:93], v244, s[28:29] offset:2048
	global_load_dwordx4 v[94:97], v244, s[28:29] offset:3072
	global_load_dwordx4 v[98:101], v244, s[0:1]
	global_load_dwordx4 v[102:105], v244, s[0:1] offset:1024
	global_load_dwordx4 v[106:109], v244, s[0:1] offset:2048
	global_load_dwordx4 v[118:121], v244, s[0:1] offset:3072
	s_waitcnt vmcnt(32)
; DI unsigned pk_bf16(float lo, float hi) { f32x2 v = {lo, hi}; bf16v2 b = __builtin_convertvector(v, bf16v2); return __builtin_bit_cast(unsigned, b); }
; DI float red64(float x) { for (int o = 32; o > 0; o >>= 1) x += __shfl_xor(x, o); return x; }
; DI void modnorm_rows(const Params& p, int l, int which  , bool from_inputs, bool skip_ctx, int w0, int wstride, int lane) {
;     ...
;     const int row = rowof(i); const int b = row / TB, s = row % TB;
;     f32x4 v[4];
; #pragma unroll
;     for (int q = 0; q < 4; ++q) v[q] = vn[q];
;     if (i + wstride < nrows) {
;       const int rn = rowof(i + wstride); const float* src = xsrc_row(p, from_inputs, rn / TB, rn % TB);
; #pragma unroll
;       for (int q = 0; q < 4; ++q) vn[q] = *(const f32x4*)(src + q * 256 + lane * 4);
;     }
;     const float* mod = p.MOD + (size_t)(l * 9 + (s < NCTX ? 8 : b)) * 6144 + (which ? 3 * 1024 : 0);
;     f32x4 sh[4], sc[4];
; #pragma unroll
;     for (int q = 0; q < 4; ++q) { sh[q] = *(const f32x4*)(mod + q * 256 + lane * 4); sc[q] = *(const f32x4*)(mod + 1024 + q * 256 + lane * 4); }
;     float ss = 0.f;
; #pragma unroll
;     for (int q = 0; q < 4; ++q) ss += v[q][0] * v[q][0] + v[q][1] * v[q][1] + v[q][2] * v[q][2] + v[q][3] * v[q][3];
;     ss = red64(ss);
;     const float rs = rsqrtf(ss * (1.f / 1024.f) + EPSF);
;     bf16_t* dst = p.HY + (size_t)row * DM;
; #pragma unroll
;     for (int q = 0; q < 4; ++q) {
;       float o[4];
; #pragma unroll
;       for (int j = 0; j < 4; ++j) o[j] = (v[q][j] * rs * gg[q][j]) * (1.f + sc[q][j]) + sh[q][j];
;       u32x2 w = {pk_bf16(o[0], o[1]), pk_bf16(o[2], o[3])};
;       *(u32x2*)(dst + q * 256 + lane * 4) = w;
;     }
	v_pk_mul_f32 v[246:247], v[122:123], v[122:123]
	v_pk_fma_f32 v[246:247], v[124:125], v[124:125], v[246:247]
	v_pk_fma_f32 v[246:247], v[126:127], v[126:127], v[246:247]
	v_pk_fma_f32 v[246:247], v[128:129], v[128:129], v[246:247]
	v_pk_fma_f32 v[246:247], v[130:131], v[130:131], v[246:247]
	v_pk_fma_f32 v[246:247], v[132:133], v[132:133], v[246:247]
	v_pk_fma_f32 v[246:247], v[134:135], v[134:135], v[246:247]
	v_pk_fma_f32 v[246:247], v[136:137], v[136:137], v[246:247]
	s_nop 0
	v_add_f32_e32 v246, v246, v247
	s_nop 1
	v_add_f32_dpp v246, v246, v246 quad_perm:[1,0,3,2] row_mask:0xf bank_mask:0xf
	s_nop 1
	v_add_f32_dpp v246, v246, v246 quad_perm:[2,3,0,1] row_mask:0xf bank_mask:0xf
	s_nop 1
	v_add_f32_dpp v246, v246, v246 row_half_mirror row_mask:0xf bank_mask:0xf
	s_nop 1
	v_add_f32_dpp v246, v246, v246 row_mirror row_mask:0xf bank_mask:0xf
	s_nop 1
	v_add_f32_dpp v246, v246, v246 row_bcast:15 row_mask:0xa bank_mask:0xf
	s_nop 1
	v_add_f32_dpp v246, v246, v246 row_bcast:31 row_mask:0xc bank_mask:0xf
	s_nop 1
	v_readlane_b32 s0, v246, 63
	s_add_i32 s21, s37, 512
	s_lshl_b32 s21, s21, 11
	s_add_u32 s10, s16, s21
	s_addc_u32 s11, s17, 0
	v_mov_b32_e32 v248, s0
	v_fmamk_f32 v248, v248, 0x3a800000, v143
	v_rsq_f32_e32 v248, v248
	s_nop 0
	v_pk_mul_f32 v[122:123], v[122:123], v[248:249] op_sel_hi:[1,0]
	v_pk_add_f32 v[176:177], v[176:177], 1.0 op_sel_hi:[1,0]
	v_pk_mul_f32 v[122:123], v[2:3], v[122:123]
	v_pk_fma_f32 v[122:123], v[176:177], v[122:123], v[160:161]
	v_pk_mul_f32 v[124:125], v[124:125], v[248:249] op_sel_hi:[1,0]
	v_pk_add_f32 v[178:179], v[178:179], 1.0 op_sel_hi:[1,0]
	v_pk_mul_f32 v[124:125], v[4:5], v[124:125]
	v_pk_fma_f32 v[124:125], v[178:179], v[124:125], v[162:163]
	v_cvt_pk_bf16_f32 v160, v122, v123
	v_cvt_pk_bf16_f32 v161, v124, v125
	global_store_dwordx2 v245, v[160:161], s[10:11]
	v_pk_mul_f32 v[126:127], v[126:127], v[248:249] op_sel_hi:[1,0]
	v_pk_add_f32 v[180:181], v[180:181], 1.0 op_sel_hi:[1,0]
	v_pk_mul_f32 v[126:127], v[6:7], v[126:127]
	v_pk_fma_f32 v[126:127], v[180:181], v[126:127], v[164:165]
	v_pk_mul_f32 v[128:129], v[128:129], v[248:249] op_sel_hi:[1,0]
	v_pk_add_f32 v[182:183], v[182:183], 1.0 op_sel_hi:[1,0]
	v_pk_mul_f32 v[128:129], v[8:9], v[128:129]
	v_pk_fma_f32 v[128:129], v[182:183], v[128:129], v[166:167]
	v_cvt_pk_bf16_f32 v164, v126, v127
	v_cvt_pk_bf16_f32 v165, v128, v129
	global_store_dwordx2 v245, v[164:165], s[10:11] offset:512
	v_pk_mul_f32 v[130:131], v[130:131], v[248:249] op_sel_hi:[1,0]
	v_pk_add_f32 v[184:185], v[184:185], 1.0 op_sel_hi:[1,0]
	v_pk_mul_f32 v[130:131], v[10:11], v[130:131]
	v_pk_fma_f32 v[130:131], v[184:185], v[130:131], v[168:169]
	v_pk_mul_f32 v[132:133], v[132:133], v[248:249] op_sel_hi:[1,0]
	v_pk_add_f32 v[186:187], v[186:187], 1.0 op_sel_hi:[1,0]
	v_pk_mul_f32 v[132:133], v[12:13], v[132:133]
	v_pk_fma_f32 v[132:133], v[186:187], v[132:133], v[170:171]
	v_cvt_pk_bf16_f32 v168, v130, v131
	v_cvt_pk_bf16_f32 v169, v132, v133
	global_store_dwordx2 v245, v[168:169], s[10:11] offset:1024
	v_pk_mul_f32 v[134:135], v[134:135], v[248:249] op_sel_hi:[1,0]
	v_pk_add_f32 v[188:189], v[188:189], 1.0 op_sel_hi:[1,0]
	v_pk_mul_f32 v[134:135], v[14:15], v[134:135]
	v_pk_fma_f32 v[134:135], v[188:189], v[134:135], v[172:173]
	v_pk_mul_f32 v[136:137], v[136:137], v[248:249] op_sel_hi:[1,0]
	v_pk_add_f32 v[190:191], v[190:191], 1.0 op_sel_hi:[1,0]
	v_pk_mul_f32 v[136:137], v[16:17], v[136:137]
	v_pk_fma_f32 v[136:137], v[190:191], v[136:137], v[174:175]
	v_cvt_pk_bf16_f32 v172, v134, v135
	v_cvt_pk_bf16_f32 v173, v136, v137
	global_store_dwordx2 v245, v[172:173], s[10:11] offset:1536
	s_add_i32 s21, s37, 1280
	s_mul_hi_u32 s7, s21, 0x38e38e39
	s_lshr_b32 s7, s7, 9
	s_mul_i32 s8, s7, 0x900
	s_sub_i32 s8, s21, s8
	s_lshl_b32 s9, s7, 11
	s_add_i32 s9, s9, s8
	s_add_i32 s9, s9, 0xffffff00
	s_lshl_b32 s10, s7, 8
	s_add_i32 s10, s10, s8
	s_cmpk_gt_i32 s8, 0xff
	s_cselect_b32 s9, s9, s10
	s_cselect_b32 s26, s12, s14
	s_cselect_b32 s27, s13, s15
	s_cselect_b32 s10, s7, 8
	s_lshl_b32 s9, s9, 12
	s_add_u32 s26, s26, s9
	s_addc_u32 s27, s27, 0
	s_add_i32 s10, s10, s82
	s_mul_i32 s10, s10, s24
	s_add_u32 s28, s58, s10
	s_addc_u32 s29, s59, 0
	s_add_u32 s28, s28, 0x3000
	s_addc_u32 s29, s29, 0
	s_add_u32 s0, s28, 0x1000
	s_addc_u32 s1, s29, 0
	global_load_dwordx4 v[122:125], v244, s[26:27]
	global_load_dwordx4 v[126:129], v244, s[26:27] offset:1024
	global_load_dwordx4 v[130:133], v244, s[26:27] offset:2048
	global_load_dwordx4 v[134:137], v244, s[26:27] offset:3072
	global_load_dwordx4 v[160:163], v244, s[28:29]
	global_load_dwordx4 v[164:167], v244, s[28:29] offset:1024
	global_load_dwordx4 v[168:171], v244, s[28:29] offset:2048
	global_load_dwordx4 v[172:175], v244, s[28:29] offset:3072
	global_load_dwordx4 v[176:179], v244, s[0:1]
	global_load_dwordx4 v[180:183], v244, s[0:1] offset:1024
	global_load_dwordx4 v[184:187], v244, s[0:1] offset:2048
	global_load_dwordx4 v[188:191], v244, s[0:1] offset:3072
	s_waitcnt vmcnt(32)
; DI unsigned pk_bf16(float lo, float hi) { f32x2 v = {lo, hi}; bf16v2 b = __builtin_convertvector(v, bf16v2); return __builtin_bit_cast(unsigned, b); }
; DI float red64(float x) { for (int o = 32; o > 0; o >>= 1) x += __shfl_xor(x, o); return x; }
; DI void modnorm_rows(const Params& p, int l, int which  , bool from_inputs, bool skip_ctx, int w0, int wstride, int lane) {
;     ...
;     const int row = rowof(i); const int b = row / TB, s = row % TB;
;     f32x4 v[4];
; #pragma unroll
;     for (int q = 0; q < 4; ++q) v[q] = vn[q];
;     if (i + wstride < nrows) {
;       const int rn = rowof(i + wstride); const float* src = xsrc_row(p, from_inputs, rn / TB, rn % TB);
; #pragma unroll
;       for (int q = 0; q < 4; ++q) vn[q] = *(const f32x4*)(src + q * 256 + lane * 4);
;     }
;     const float* mod = p.MOD + (size_t)(l * 9 + (s < NCTX ? 8 : b)) * 6144 + (which ? 3 * 1024 : 0);
;     f32x4 sh[4], sc[4];
; #pragma unroll
;     for (int q = 0; q < 4; ++q) { sh[q] = *(const f32x4*)(mod + q * 256 + lane * 4); sc[q] = *(const f32x4*)(mod + 1024 + q * 256 + lane * 4); }
;     float ss = 0.f;
; #pragma unroll
;     for (int q = 0; q < 4; ++q) ss += v[q][0] * v[q][0] + v[q][1] * v[q][1] + v[q][2] * v[q][2] + v[q][3] * v[q][3];
;     ss = red64(ss);
;     const float rs = rsqrtf(ss * (1.f / 1024.f) + EPSF);
;     bf16_t* dst = p.HY + (size_t)row * DM;
; #pragma unroll
;     for (int q = 0; q < 4; ++q) {
;       float o[4];
; #pragma unroll
;       for (int j = 0; j < 4; ++j) o[j] = (v[q][j] * rs * gg[q][j]) * (1.f + sc[q][j]) + sh[q][j];
;       u32x2 w = {pk_bf16(o[0], o[1]), pk_bf16(o[2], o[3])};
;       *(u32x2*)(dst + q * 256 + lane * 4) = w;
;     }
	v_pk_mul_f32 v[246:247], v[18:19], v[18:19]
	v_pk_fma_f32 v[246:247], v[20:21], v[20:21], v[246:247]
	v_pk_fma_f32 v[246:247], v[22:23], v[22:23], v[246:247]
	v_pk_fma_f32 v[246:247], v[24:25], v[24:25], v[246:247]
	v_pk_fma_f32 v[246:247], v[26:27], v[26:27], v[246:247]
	v_pk_fma_f32 v[246:247], v[28:29], v[28:29], v[246:247]
	v_pk_fma_f32 v[246:247], v[30:31], v[30:31], v[246:247]
	v_pk_fma_f32 v[246:247], v[32:33], v[32:33], v[246:247]
	s_nop 0
	v_add_f32_e32 v246, v246, v247
	s_nop 1
	v_add_f32_dpp v246, v246, v246 quad_perm:[1,0,3,2] row_mask:0xf bank_mask:0xf
	s_nop 1
	v_add_f32_dpp v246, v246, v246 quad_perm:[2,3,0,1] row_mask:0xf bank_mask:0xf
	s_nop 1
	v_add_f32_dpp v246, v246, v246 row_half_mirror row_mask:0xf bank_mask:0xf
	s_nop 1
	v_add_f32_dpp v246, v246, v246 row_mirror row_mask:0xf bank_mask:0xf
	s_nop 1
	v_add_f32_dpp v246, v246, v246 row_bcast:15 row_mask:0xa bank_mask:0xf
	s_nop 1
	v_add_f32_dpp v246, v246, v246 row_bcast:31 row_mask:0xc bank_mask:0xf
	s_nop 1
	v_readlane_b32 s0, v246, 63
	s_add_i32 s21, s37, 768
	s_lshl_b32 s21, s21, 11
	s_add_u32 s10, s16, s21
	s_addc_u32 s11, s17, 0
	v_mov_b32_e32 v248, s0
	v_fmamk_f32 v248, v248, 0x3a800000, v143
	v_rsq_f32_e32 v248, v248
	s_nop 0
	v_pk_mul_f32 v[18:19], v[18:19], v[248:249] op_sel_hi:[1,0]
	v_pk_add_f32 v[50:51], v[50:51], 1.0 op_sel_hi:[1,0]
	v_pk_mul_f32 v[18:19], v[2:3], v[18:19]
	v_pk_fma_f32 v[18:19], v[50:51], v[18:19], v[34:35]
	v_pk_mul_f32 v[20:21], v[20:21], v[248:249] op_sel_hi:[1,0]
	v_pk_add_f32 v[52:53], v[52:53], 1.0 op_sel_hi:[1,0]
	v_pk_mul_f32 v[20:21], v[4:5], v[20:21]
	v_pk_fma_f32 v[20:21], v[52:53], v[20:21], v[36:37]
	v_cvt_pk_bf16_f32 v34, v18, v19
	v_cvt_pk_bf16_f32 v35, v20, v21
	global_store_dwordx2 v245, v[34:35], s[10:11]
	v_pk_mul_f32 v[22:23], v[22:23], v[248:249] op_sel_hi:[1,0]
	v_pk_add_f32 v[54:55], v[54:55], 1.0 op_sel_hi:[1,0]
	v_pk_mul_f32 v[22:23], v[6:7], v[22:23]
	v_pk_fma_f32 v[22:23], v[54:55], v[22:23], v[38:39]
	v_pk_mul_f32 v[24:25], v[24:25], v[248:249] op_sel_hi:[1,0]
	v_pk_add_f32 v[56:57], v[56:57], 1.0 op_sel_hi:[1,0]
	v_pk_mul_f32 v[24:25], v[8:9], v[24:25]
	v_pk_fma_f32 v[24:25], v[56:57], v[24:25], v[40:41]
	v_cvt_pk_bf16_f32 v38, v22, v23
	v_cvt_pk_bf16_f32 v39, v24, v25
	global_store_dwordx2 v245, v[38:39], s[10:11] offset:512
	v_pk_mul_f32 v[26:27], v[26:27], v[248:249] op_sel_hi:[1,0]
	v_pk_add_f32 v[58:59], v[58:59], 1.0 op_sel_hi:[1,0]
	v_pk_mul_f32 v[26:27], v[10:11], v[26:27]
	v_pk_fma_f32 v[26:27], v[58:59], v[26:27], v[42:43]
	v_pk_mul_f32 v[28:29], v[28:29], v[248:249] op_sel_hi:[1,0]
	v_pk_add_f32 v[60:61], v[60:61], 1.0 op_sel_hi:[1,0]
	v_pk_mul_f32 v[28:29], v[12:13], v[28:29]
	v_pk_fma_f32 v[28:29], v[60:61], v[28:29], v[44:45]
	v_cvt_pk_bf16_f32 v42, v26, v27
	v_cvt_pk_bf16_f32 v43, v28, v29
	global_store_dwordx2 v245, v[42:43], s[10:11] offset:1024
	v_pk_mul_f32 v[30:31], v[30:31], v[248:249] op_sel_hi:[1,0]
	v_pk_add_f32 v[62:63], v[62:63], 1.0 op_sel_hi:[1,0]
	v_pk_mul_f32 v[30:31], v[14:15], v[30:31]
	v_pk_fma_f32 v[30:31], v[62:63], v[30:31], v[46:47]
	v_pk_mul_f32 v[32:33], v[32:33], v[248:249] op_sel_hi:[1,0]
	v_pk_add_f32 v[64:65], v[64:65], 1.0 op_sel_hi:[1,0]
	v_pk_mul_f32 v[32:33], v[16:17], v[32:33]
	v_pk_fma_f32 v[32:33], v[64:65], v[32:33], v[48:49]
	v_cvt_pk_bf16_f32 v46, v30, v31
	v_cvt_pk_bf16_f32 v47, v32, v33
	global_store_dwordx2 v245, v[46:47], s[10:11] offset:1536
	s_add_i32 s21, s37, 1536
	s_mul_hi_u32 s7, s21, 0x38e38e39
	s_lshr_b32 s7, s7, 9
	s_mul_i32 s8, s7, 0x900
	s_sub_i32 s8, s21, s8
	s_lshl_b32 s9, s7, 11
	s_add_i32 s9, s9, s8
	s_add_i32 s9, s9, 0xffffff00
	s_lshl_b32 s10, s7, 8
	s_add_i32 s10, s10, s8
	s_cmpk_gt_i32 s8, 0xff
	s_cselect_b32 s9, s9, s10
	s_cselect_b32 s26, s12, s14
	s_cselect_b32 s27, s13, s15
	s_cselect_b32 s10, s7, 8
	s_lshl_b32 s9, s9, 12
	s_add_u32 s26, s26, s9
	s_addc_u32 s27, s27, 0
	s_add_i32 s10, s10, s82
	s_mul_i32 s10, s10, s24
	s_add_u32 s28, s58, s10
	s_addc_u32 s29, s59, 0
	s_add_u32 s28, s28, 0x3000
	s_addc_u32 s29, s29, 0
	s_add_u32 s0, s28, 0x1000
	s_addc_u32 s1, s29, 0
	global_load_dwordx4 v[18:21], v244, s[26:27]
	global_load_dwordx4 v[22:25], v244, s[26:27] offset:1024
	global_load_dwordx4 v[26:29], v244, s[26:27] offset:2048
	global_load_dwordx4 v[30:33], v244, s[26:27] offset:3072
	global_load_dwordx4 v[34:37], v244, s[28:29]
	global_load_dwordx4 v[38:41], v244, s[28:29] offset:1024
	global_load_dwordx4 v[42:45], v244, s[28:29] offset:2048
	global_load_dwordx4 v[46:49], v244, s[28:29] offset:3072
	global_load_dwordx4 v[50:53], v244, s[0:1]
	global_load_dwordx4 v[54:57], v244, s[0:1] offset:1024
	global_load_dwordx4 v[58:61], v244, s[0:1] offset:2048
	global_load_dwordx4 v[62:65], v244, s[0:1] offset:3072
	s_waitcnt vmcnt(32)
; DI unsigned pk_bf16(float lo, float hi) { f32x2 v = {lo, hi}; bf16v2 b = __builtin_convertvector(v, bf16v2); return __builtin_bit_cast(unsigned, b); }
; DI float red64(float x) { for (int o = 32; o > 0; o >>= 1) x += __shfl_xor(x, o); return x; }
; DI void modnorm_rows(const Params& p, int l, int which  , bool from_inputs, bool skip_ctx, int w0, int wstride, int lane) {
;     ...
;     const int row = rowof(i); const int b = row / TB, s = row % TB;
;     f32x4 v[4];
; #pragma unroll
;     for (int q = 0; q < 4; ++q) v[q] = vn[q];
;     if (i + wstride < nrows) {
;       const int rn = rowof(i + wstride); const float* src = xsrc_row(p, from_inputs, rn / TB, rn % TB);
; #pragma unroll
;       for (int q = 0; q < 4; ++q) vn[q] = *(const f32x4*)(src + q * 256 + lane * 4);
;     }
;     const float* mod = p.MOD + (size_t)(l * 9 + (s < NCTX ? 8 : b)) * 6144 + (which ? 3 * 1024 : 0);
;     f32x4 sh[4], sc[4];
; #pragma unroll
;     for (int q = 0; q < 4; ++q) { sh[q] = *(const f32x4*)(mod + q * 256 + lane * 4); sc[q] = *(const f32x4*)(mod + 1024 + q * 256 + lane * 4); }
;     float ss = 0.f;
; #pragma unroll
;     for (int q = 0; q < 4; ++q) ss += v[q][0] * v[q][0] + v[q][1] * v[q][1] + v[q][2] * v[q][2] + v[q][3] * v[q][3];
;     ss = red64(ss);
;     const float rs = rsqrtf(ss * (1.f / 1024.f) + EPSF);
;     bf16_t* dst = p.HY + (size_t)row * DM;
; #pragma unroll
;     for (int q = 0; q < 4; ++q) {
;       float o[4];
; #pragma unroll
;       for (int j = 0; j < 4; ++j) o[j] = (v[q][j] * rs * gg[q][j]) * (1.f + sc[q][j]) + sh[q][j];
;       u32x2 w = {pk_bf16(o[0], o[1]), pk_bf16(o[2], o[3])};
;       *(u32x2*)(dst + q * 256 + lane * 4) = w;
;     }
	v_pk_mul_f32 v[246:247], v[66:67], v[66:67]
	v_pk_fma_f32 v[246:247], v[68:69], v[68:69], v[246:247]
	v_pk_fma_f32 v[246:247], v[70:71], v[70:71], v[246:247]
	v_pk_fma_f32 v[246:247], v[72:73], v[72:73], v[246:247]
	v_pk_fma_f32 v[246:247], v[74:75], v[74:75], v[246:247]
	v_pk_fma_f32 v[246:247], v[76:77], v[76:77], v[246:247]
	v_pk_fma_f32 v[246:247], v[78:79], v[78:79], v[246:247]
	v_pk_fma_f32 v[246:247], v[80:81], v[80:81], v[246:247]
	s_nop 0
	v_add_f32_e32 v246, v246, v247
	s_nop 1
	v_add_f32_dpp v246, v246, v246 quad_perm:[1,0,3,2] row_mask:0xf bank_mask:0xf
	s_nop 1
	v_add_f32_dpp v246, v246, v246 quad_perm:[2,3,0,1] row_mask:0xf bank_mask:0xf
	s_nop 1
	v_add_f32_dpp v246, v246, v246 row_half_mirror row_mask:0xf bank_mask:0xf
	s_nop 1
	v_add_f32_dpp v246, v246, v246 row_mirror row_mask:0xf bank_mask:0xf
	s_nop 1
	v_add_f32_dpp v246, v246, v246 row_bcast:15 row_mask:0xa bank_mask:0xf
	s_nop 1
	v_add_f32_dpp v246, v246, v246 row_bcast:31 row_mask:0xc bank_mask:0xf
	s_nop 1
	v_readlane_b32 s0, v246, 63
	s_add_i32 s21, s37, 1024
	s_lshl_b32 s21, s21, 11
	s_add_u32 s10, s16, s21
	s_addc_u32 s11, s17, 0
	v_mov_b32_e32 v248, s0
	v_fmamk_f32 v248, v248, 0x3a800000, v143
	v_rsq_f32_e32 v248, v248
	s_nop 0
	v_pk_mul_f32 v[66:67], v[66:67], v[248:249] op_sel_hi:[1,0]
	v_pk_add_f32 v[98:99], v[98:99], 1.0 op_sel_hi:[1,0]
	v_pk_mul_f32 v[66:67], v[2:3], v[66:67]
	v_pk_fma_f32 v[66:67], v[98:99], v[66:67], v[82:83]
	v_pk_mul_f32 v[68:69], v[68:69], v[248:249] op_sel_hi:[1,0]
	v_pk_add_f32 v[100:101], v[100:101], 1.0 op_sel_hi:[1,0]
	v_pk_mul_f32 v[68:69], v[4:5], v[68:69]
	v_pk_fma_f32 v[68:69], v[100:101], v[68:69], v[84:85]
	v_cvt_pk_bf16_f32 v82, v66, v67
	v_cvt_pk_bf16_f32 v83, v68, v69
	global_store_dwordx2 v245, v[82:83], s[10:11]
	v_pk_mul_f32 v[70:71], v[70:71], v[248:249] op_sel_hi:[1,0]
	v_pk_add_f32 v[102:103], v[102:103], 1.0 op_sel_hi:[1,0]
	v_pk_mul_f32 v[70:71], v[6:7], v[70:71]
	v_pk_fma_f32 v[70:71], v[102:103], v[70:71], v[86:87]
	v_pk_mul_f32 v[72:73], v[72:73], v[248:249] op_sel_hi:[1,0]
	v_pk_add_f32 v[104:105], v[104:105], 1.0 op_sel_hi:[1,0]
	v_pk_mul_f32 v[72:73], v[8:9], v[72:73]
	v_pk_fma_f32 v[72:73], v[104:105], v[72:73], v[88:89]
	v_cvt_pk_bf16_f32 v86, v70, v71
	v_cvt_pk_bf16_f32 v87, v72, v73
	global_store_dwordx2 v245, v[86:87], s[10:11] offset:512
	v_pk_mul_f32 v[74:75], v[74:75], v[248:249] op_sel_hi:[1,0]
	v_pk_add_f32 v[106:107], v[106:107], 1.0 op_sel_hi:[1,0]
	v_pk_mul_f32 v[74:75], v[10:11], v[74:75]
	v_pk_fma_f32 v[74:75], v[106:107], v[74:75], v[90:91]
	v_pk_mul_f32 v[76:77], v[76:77], v[248:249] op_sel_hi:[1,0]
	v_pk_add_f32 v[108:109], v[108:109], 1.0 op_sel_hi:[1,0]
	v_pk_mul_f32 v[76:77], v[12:13], v[76:77]
	v_pk_fma_f32 v[76:77], v[108:109], v[76:77], v[92:93]
	v_cvt_pk_bf16_f32 v90, v74, v75
	v_cvt_pk_bf16_f32 v91, v76, v77
	global_store_dwordx2 v245, v[90:91], s[10:11] offset:1024
	v_pk_mul_f32 v[78:79], v[78:79], v[248:249] op_sel_hi:[1,0]
	v_pk_add_f32 v[118:119], v[118:119], 1.0 op_sel_hi:[1,0]
	v_pk_mul_f32 v[78:79], v[14:15], v[78:79]
	v_pk_fma_f32 v[78:79], v[118:119], v[78:79], v[94:95]
	v_pk_mul_f32 v[80:81], v[80:81], v[248:249] op_sel_hi:[1,0]
	v_pk_add_f32 v[120:121], v[120:121], 1.0 op_sel_hi:[1,0]
	v_pk_mul_f32 v[80:81], v[16:17], v[80:81]
	v_pk_fma_f32 v[80:81], v[120:121], v[80:81], v[96:97]
	v_cvt_pk_bf16_f32 v94, v78, v79
	v_cvt_pk_bf16_f32 v95, v80, v81
	global_store_dwordx2 v245, v[94:95], s[10:11] offset:1536
	s_add_i32 s21, s37, 1792
	s_mul_hi_u32 s7, s21, 0x38e38e39
	s_lshr_b32 s7, s7, 9
	s_mul_i32 s8, s7, 0x900
	s_sub_i32 s8, s21, s8
	s_lshl_b32 s9, s7, 11
	s_add_i32 s9, s9, s8
	s_add_i32 s9, s9, 0xffffff00
	s_lshl_b32 s10, s7, 8
	s_add_i32 s10, s10, s8
	s_cmpk_gt_i32 s8, 0xff
	s_cselect_b32 s9, s9, s10
	s_cselect_b32 s26, s12, s14
	s_cselect_b32 s27, s13, s15
	s_cselect_b32 s10, s7, 8
	s_lshl_b32 s9, s9, 12
	s_add_u32 s26, s26, s9
	s_addc_u32 s27, s27, 0
	s_add_i32 s10, s10, s82
	s_mul_i32 s10, s10, s24
	s_add_u32 s28, s58, s10
	s_addc_u32 s29, s59, 0
	s_add_u32 s28, s28, 0x3000
	s_addc_u32 s29, s29, 0
	s_add_u32 s0, s28, 0x1000
	s_addc_u32 s1, s29, 0
	global_load_dwordx4 v[66:69], v244, s[26:27]
	global_load_dwordx4 v[70:73], v244, s[26:27] offset:1024
	global_load_dwordx4 v[74:77], v244, s[26:27] offset:2048
	global_load_dwordx4 v[78:81], v244, s[26:27] offset:3072
	global_load_dwordx4 v[82:85], v244, s[28:29]
	global_load_dwordx4 v[86:89], v244, s[28:29] offset:1024
	global_load_dwordx4 v[90:93], v244, s[28:29] offset:2048
	global_load_dwordx4 v[94:97], v244, s[28:29] offset:3072
	global_load_dwordx4 v[98:101], v244, s[0:1]
	global_load_dwordx4 v[102:105], v244, s[0:1] offset:1024
	global_load_dwordx4 v[106:109], v244, s[0:1] offset:2048
	global_load_dwordx4 v[118:121], v244, s[0:1] offset:3072
	s_waitcnt vmcnt(32)
; DI unsigned pk_bf16(float lo, float hi) { f32x2 v = {lo, hi}; bf16v2 b = __builtin_convertvector(v, bf16v2); return __builtin_bit_cast(unsigned, b); }
; DI float red64(float x) { for (int o = 32; o > 0; o >>= 1) x += __shfl_xor(x, o); return x; }
; DI void modnorm_rows(const Params& p, int l, int which  , bool from_inputs, bool skip_ctx, int w0, int wstride, int lane) {
;     ...
;     const int row = rowof(i); const int b = row / TB, s = row % TB;
;     f32x4 v[4];
; #pragma unroll
;     for (int q = 0; q < 4; ++q) v[q] = vn[q];
;     if (i + wstride < nrows) {
;       const int rn = rowof(i + wstride); const float* src = xsrc_row(p, from_inputs, rn / TB, rn % TB);
; #pragma unroll
;       for (int q = 0; q < 4; ++q) vn[q] = *(const f32x4*)(src + q * 256 + lane * 4);
;     }
;     const float* mod = p.MOD + (size_t)(l * 9 + (s < NCTX ? 8 : b)) * 6144 + (which ? 3 * 1024 : 0);
;     f32x4 sh[4], sc[4];
; #pragma unroll
;     for (int q = 0; q < 4; ++q) { sh[q] = *(const f32x4*)(mod + q * 256 + lane * 4); sc[q] = *(const f32x4*)(mod + 1024 + q * 256 + lane * 4); }
;     float ss = 0.f;
; #pragma unroll
;     for (int q = 0; q < 4; ++q) ss += v[q][0] * v[q][0] + v[q][1] * v[q][1] + v[q][2] * v[q][2] + v[q][3] * v[q][3];
;     ss = red64(ss);
;     const float rs = rsqrtf(ss * (1.f / 1024.f) + EPSF);
;     bf16_t* dst = p.HY + (size_t)row * DM;
; #pragma unroll
;     for (int q = 0; q < 4; ++q) {
;       float o[4];
; #pragma unroll
;       for (int j = 0; j < 4; ++j) o[j] = (v[q][j] * rs * gg[q][j]) * (1.f + sc[q][j]) + sh[q][j];
;       u32x2 w = {pk_bf16(o[0], o[1]), pk_bf16(o[2], o[3])};
;       *(u32x2*)(dst + q * 256 + lane * 4) = w;
;     }
	v_pk_mul_f32 v[246:247], v[122:123], v[122:123]
	v_pk_fma_f32 v[246:247], v[124:125], v[124:125], v[246:247]
	v_pk_fma_f32 v[246:247], v[126:127], v[126:127], v[246:247]
	v_pk_fma_f32 v[246:247], v[128:129], v[128:129], v[246:247]
	v_pk_fma_f32 v[246:247], v[130:131], v[130:131], v[246:247]
	v_pk_fma_f32 v[246:247], v[132:133], v[132:133], v[246:247]
	v_pk_fma_f32 v[246:247], v[134:135], v[134:135], v[246:247]
	v_pk_fma_f32 v[246:247], v[136:137], v[136:137], v[246:247]
	s_nop 0
	v_add_f32_e32 v246, v246, v247
	s_nop 1
	v_add_f32_dpp v246, v246, v246 quad_perm:[1,0,3,2] row_mask:0xf bank_mask:0xf
	s_nop 1
	v_add_f32_dpp v246, v246, v246 quad_perm:[2,3,0,1] row_mask:0xf bank_mask:0xf
	s_nop 1
	v_add_f32_dpp v246, v246, v246 row_half_mirror row_mask:0xf bank_mask:0xf
	s_nop 1
	v_add_f32_dpp v246, v246, v246 row_mirror row_mask:0xf bank_mask:0xf
	s_nop 1
	v_add_f32_dpp v246, v246, v246 row_bcast:15 row_mask:0xa bank_mask:0xf
	s_nop 1
	v_add_f32_dpp v246, v246, v246 row_bcast:31 row_mask:0xc bank_mask:0xf
	s_nop 1
	v_readlane_b32 s0, v246, 63
	s_add_i32 s21, s37, 1280
	s_lshl_b32 s21, s21, 11
	s_add_u32 s10, s16, s21
	s_addc_u32 s11, s17, 0
	v_mov_b32_e32 v248, s0
	v_fmamk_f32 v248, v248, 0x3a800000, v143
	v_rsq_f32_e32 v248, v248
	s_nop 0
	v_pk_mul_f32 v[122:123], v[122:123], v[248:249] op_sel_hi:[1,0]
	v_pk_add_f32 v[176:177], v[176:177], 1.0 op_sel_hi:[1,0]
	v_pk_mul_f32 v[122:123], v[2:3], v[122:123]
	v_pk_fma_f32 v[122:123], v[176:177], v[122:123], v[160:161]
	v_pk_mul_f32 v[124:125], v[124:125], v[248:249] op_sel_hi:[1,0]
	v_pk_add_f32 v[178:179], v[178:179], 1.0 op_sel_hi:[1,0]
	v_pk_mul_f32 v[124:125], v[4:5], v[124:125]
	v_pk_fma_f32 v[124:125], v[178:179], v[124:125], v[162:163]
	v_cvt_pk_bf16_f32 v160, v122, v123
	v_cvt_pk_bf16_f32 v161, v124, v125
	global_store_dwordx2 v245, v[160:161], s[10:11]
	v_pk_mul_f32 v[126:127], v[126:127], v[248:249] op_sel_hi:[1,0]
	v_pk_add_f32 v[180:181], v[180:181], 1.0 op_sel_hi:[1,0]
	v_pk_mul_f32 v[126:127], v[6:7], v[126:127]
	v_pk_fma_f32 v[126:127], v[180:181], v[126:127], v[164:165]
	v_pk_mul_f32 v[128:129], v[128:129], v[248:249] op_sel_hi:[1,0]
	v_pk_add_f32 v[182:183], v[182:183], 1.0 op_sel_hi:[1,0]
	v_pk_mul_f32 v[128:129], v[8:9], v[128:129]
	v_pk_fma_f32 v[128:129], v[182:183], v[128:129], v[166:167]
	v_cvt_pk_bf16_f32 v164, v126, v127
	v_cvt_pk_bf16_f32 v165, v128, v129
	global_store_dwordx2 v245, v[164:165], s[10:11] offset:512
	v_pk_mul_f32 v[130:131], v[130:131], v[248:249] op_sel_hi:[1,0]
	v_pk_add_f32 v[184:185], v[184:185], 1.0 op_sel_hi:[1,0]
	v_pk_mul_f32 v[130:131], v[10:11], v[130:131]
	v_pk_fma_f32 v[130:131], v[184:185], v[130:131], v[168:169]
	v_pk_mul_f32 v[132:133], v[132:133], v[248:249] op_sel_hi:[1,0]
	v_pk_add_f32 v[186:187], v[186:187], 1.0 op_sel_hi:[1,0]
	v_pk_mul_f32 v[132:133], v[12:13], v[132:133]
	v_pk_fma_f32 v[132:133], v[186:187], v[132:133], v[170:171]
	v_cvt_pk_bf16_f32 v168, v130, v131
	v_cvt_pk_bf16_f32 v169, v132, v133
	global_store_dwordx2 v245, v[168:169], s[10:11] offset:1024
	v_pk_mul_f32 v[134:135], v[134:135], v[248:249] op_sel_hi:[1,0]
	v_pk_add_f32 v[188:189], v[188:189], 1.0 op_sel_hi:[1,0]
	v_pk_mul_f32 v[134:135], v[14:15], v[134:135]
	v_pk_fma_f32 v[134:135], v[188:189], v[134:135], v[172:173]
	v_pk_mul_f32 v[136:137], v[136:137], v[248:249] op_sel_hi:[1,0]
	v_pk_add_f32 v[190:191], v[190:191], 1.0 op_sel_hi:[1,0]
	v_pk_mul_f32 v[136:137], v[16:17], v[136:137]
	v_pk_fma_f32 v[136:137], v[190:191], v[136:137], v[174:175]
	v_cvt_pk_bf16_f32 v172, v134, v135
	v_cvt_pk_bf16_f32 v173, v136, v137
	global_store_dwordx2 v245, v[172:173], s[10:11] offset:1536
	s_add_i32 s21, s37, 2048
	s_mul_hi_u32 s7, s21, 0x38e38e39
	s_lshr_b32 s7, s7, 9
	s_mul_i32 s8, s7, 0x900
	s_sub_i32 s8, s21, s8
	s_lshl_b32 s9, s7, 11
	s_add_i32 s9, s9, s8
	s_add_i32 s9, s9, 0xffffff00
	s_lshl_b32 s10, s7, 8
	s_add_i32 s10, s10, s8
	s_cmpk_gt_i32 s8, 0xff
	s_cselect_b32 s9, s9, s10
	s_cselect_b32 s26, s12, s14
	s_cselect_b32 s27, s13, s15
	s_cselect_b32 s10, s7, 8
	s_lshl_b32 s9, s9, 12
	s_add_u32 s26, s26, s9
	s_addc_u32 s27, s27, 0
	s_add_i32 s10, s10, s82
	s_mul_i32 s10, s10, s24
	s_add_u32 s28, s58, s10
	s_addc_u32 s29, s59, 0
	s_add_u32 s28, s28, 0x3000
	s_addc_u32 s29, s29, 0
	s_add_u32 s0, s28, 0x1000
	s_addc_u32 s1, s29, 0
	global_load_dwordx4 v[122:125], v244, s[26:27]
	global_load_dwordx4 v[126:129], v244, s[26:27] offset:1024
	global_load_dwordx4 v[130:133], v244, s[26:27] offset:2048
	global_load_dwordx4 v[134:137], v244, s[26:27] offset:3072
	global_load_dwordx4 v[160:163], v244, s[28:29]
	global_load_dwordx4 v[164:167], v244, s[28:29] offset:1024
	global_load_dwordx4 v[168:171], v244, s[28:29] offset:2048
	global_load_dwordx4 v[172:175], v244, s[28:29] offset:3072
	global_load_dwordx4 v[176:179], v244, s[0:1]
	global_load_dwordx4 v[180:183], v244, s[0:1] offset:1024
	global_load_dwordx4 v[184:187], v244, s[0:1] offset:2048
	global_load_dwordx4 v[188:191], v244, s[0:1] offset:3072
	s_waitcnt vmcnt(32)
; DI unsigned pk_bf16(float lo, float hi) { f32x2 v = {lo, hi}; bf16v2 b = __builtin_convertvector(v, bf16v2); return __builtin_bit_cast(unsigned, b); }
; DI float red64(float x) { for (int o = 32; o > 0; o >>= 1) x += __shfl_xor(x, o); return x; }
; DI void modnorm_rows(const Params& p, int l, int which  , bool from_inputs, bool skip_ctx, int w0, int wstride, int lane) {
;     ...
;     const int row = rowof(i); const int b = row / TB, s = row % TB;
;     f32x4 v[4];
; #pragma unroll
;     for (int q = 0; q < 4; ++q) v[q] = vn[q];
;     if (i + wstride < nrows) {
;       const int rn = rowof(i + wstride); const float* src = xsrc_row(p, from_inputs, rn / TB, rn % TB);
; #pragma unroll
;       for (int q = 0; q < 4; ++q) vn[q] = *(const f32x4*)(src + q * 256 + lane * 4);
;     }
;     const float* mod = p.MOD + (size_t)(l * 9 + (s < NCTX ? 8 : b)) * 6144 + (which ? 3 * 1024 : 0);
;     f32x4 sh[4], sc[4];
; #pragma unroll
;     for (int q = 0; q < 4; ++q) { sh[q] = *(const f32x4*)(mod + q * 256 + lane * 4); sc[q] = *(const f32x4*)(mod + 1024 + q * 256 + lane * 4); }
;     float ss = 0.f;
; #pragma unroll
;     for (int q = 0; q < 4; ++q) ss += v[q][0] * v[q][0] + v[q][1] * v[q][1] + v[q][2] * v[q][2] + v[q][3] * v[q][3];
;     ss = red64(ss);
;     const float rs = rsqrtf(ss * (1.f / 1024.f) + EPSF);
;     bf16_t* dst = p.HY + (size_t)row * DM;
; #pragma unroll
;     for (int q = 0; q < 4; ++q) {
;       float o[4];
; #pragma unroll
;       for (int j = 0; j < 4; ++j) o[j] = (v[q][j] * rs * gg[q][j]) * (1.f + sc[q][j]) + sh[q][j];
;       u32x2 w = {pk_bf16(o[0], o[1]), pk_bf16(o[2], o[3])};
;       *(u32x2*)(dst + q * 256 + lane * 4) = w;
;     }
	v_pk_mul_f32 v[246:247], v[18:19], v[18:19]
	v_pk_fma_f32 v[246:247], v[20:21], v[20:21], v[246:247]
	v_pk_fma_f32 v[246:247], v[22:23], v[22:23], v[246:247]
	v_pk_fma_f32 v[246:247], v[24:25], v[24:25], v[246:247]
	v_pk_fma_f32 v[246:247], v[26:27], v[26:27], v[246:247]
	v_pk_fma_f32 v[246:247], v[28:29], v[28:29], v[246:247]
	v_pk_fma_f32 v[246:247], v[30:31], v[30:31], v[246:247]
	v_pk_fma_f32 v[246:247], v[32:33], v[32:33], v[246:247]
	s_nop 0
	v_add_f32_e32 v246, v246, v247
	s_nop 1
	v_add_f32_dpp v246, v246, v246 quad_perm:[1,0,3,2] row_mask:0xf bank_mask:0xf
	s_nop 1
	v_add_f32_dpp v246, v246, v246 quad_perm:[2,3,0,1] row_mask:0xf bank_mask:0xf
	s_nop 1
	v_add_f32_dpp v246, v246, v246 row_half_mirror row_mask:0xf bank_mask:0xf
	s_nop 1
	v_add_f32_dpp v246, v246, v246 row_mirror row_mask:0xf bank_mask:0xf
	s_nop 1
	v_add_f32_dpp v246, v246, v246 row_bcast:15 row_mask:0xa bank_mask:0xf
	s_nop 1
	v_add_f32_dpp v246, v246, v246 row_bcast:31 row_mask:0xc bank_mask:0xf
	s_nop 1
	v_readlane_b32 s0, v246, 63
	s_add_i32 s21, s37, 1536
	s_lshl_b32 s21, s21, 11
	s_add_u32 s10, s16, s21
	s_addc_u32 s11, s17, 0
	v_mov_b32_e32 v248, s0
	v_fmamk_f32 v248, v248, 0x3a800000, v143
	v_rsq_f32_e32 v248, v248
	s_nop 0
	v_pk_mul_f32 v[18:19], v[18:19], v[248:249] op_sel_hi:[1,0]
	v_pk_add_f32 v[50:51], v[50:51], 1.0 op_sel_hi:[1,0]
	v_pk_mul_f32 v[18:19], v[2:3], v[18:19]
	v_pk_fma_f32 v[18:19], v[50:51], v[18:19], v[34:35]
	v_pk_mul_f32 v[20:21], v[20:21], v[248:249] op_sel_hi:[1,0]
	v_pk_add_f32 v[52:53], v[52:53], 1.0 op_sel_hi:[1,0]
	v_pk_mul_f32 v[20:21], v[4:5], v[20:21]
	v_pk_fma_f32 v[20:21], v[52:53], v[20:21], v[36:37]
	v_cvt_pk_bf16_f32 v34, v18, v19
	v_cvt_pk_bf16_f32 v35, v20, v21
	global_store_dwordx2 v245, v[34:35], s[10:11]
	v_pk_mul_f32 v[22:23], v[22:23], v[248:249] op_sel_hi:[1,0]
	v_pk_add_f32 v[54:55], v[54:55], 1.0 op_sel_hi:[1,0]
	v_pk_mul_f32 v[22:23], v[6:7], v[22:23]
	v_pk_fma_f32 v[22:23], v[54:55], v[22:23], v[38:39]
	v_pk_mul_f32 v[24:25], v[24:25], v[248:249] op_sel_hi:[1,0]
	v_pk_add_f32 v[56:57], v[56:57], 1.0 op_sel_hi:[1,0]
	v_pk_mul_f32 v[24:25], v[8:9], v[24:25]
	v_pk_fma_f32 v[24:25], v[56:57], v[24:25], v[40:41]
	v_cvt_pk_bf16_f32 v38, v22, v23
	v_cvt_pk_bf16_f32 v39, v24, v25
	global_store_dwordx2 v245, v[38:39], s[10:11] offset:512
	v_pk_mul_f32 v[26:27], v[26:27], v[248:249] op_sel_hi:[1,0]
	v_pk_add_f32 v[58:59], v[58:59], 1.0 op_sel_hi:[1,0]
	v_pk_mul_f32 v[26:27], v[10:11], v[26:27]
	v_pk_fma_f32 v[26:27], v[58:59], v[26:27], v[42:43]
	v_pk_mul_f32 v[28:29], v[28:29], v[248:249] op_sel_hi:[1,0]
	v_pk_add_f32 v[60:61], v[60:61], 1.0 op_sel_hi:[1,0]
	v_pk_mul_f32 v[28:29], v[12:13], v[28:29]
	v_pk_fma_f32 v[28:29], v[60:61], v[28:29], v[44:45]
	v_cvt_pk_bf16_f32 v42, v26, v27
	v_cvt_pk_bf16_f32 v43, v28, v29
	global_store_dwordx2 v245, v[42:43], s[10:11] offset:1024
	v_pk_mul_f32 v[30:31], v[30:31], v[248:249] op_sel_hi:[1,0]
	v_pk_add_f32 v[62:63], v[62:63], 1.0 op_sel_hi:[1,0]
	v_pk_mul_f32 v[30:31], v[14:15], v[30:31]
	v_pk_fma_f32 v[30:31], v[62:63], v[30:31], v[46:47]
	v_pk_mul_f32 v[32:33], v[32:33], v[248:249] op_sel_hi:[1,0]
	v_pk_add_f32 v[64:65], v[64:65], 1.0 op_sel_hi:[1,0]
	v_pk_mul_f32 v[32:33], v[16:17], v[32:33]
	v_pk_fma_f32 v[32:33], v[64:65], v[32:33], v[48:49]
	v_cvt_pk_bf16_f32 v46, v30, v31
	v_cvt_pk_bf16_f32 v47, v32, v33
	global_store_dwordx2 v245, v[46:47], s[10:11] offset:1536
	s_waitcnt vmcnt(20)
	v_pk_mul_f32 v[246:247], v[66:67], v[66:67]
	v_pk_fma_f32 v[246:247], v[68:69], v[68:69], v[246:247]
	v_pk_fma_f32 v[246:247], v[70:71], v[70:71], v[246:247]
	v_pk_fma_f32 v[246:247], v[72:73], v[72:73], v[246:247]
	v_pk_fma_f32 v[246:247], v[74:75], v[74:75], v[246:247]
	v_pk_fma_f32 v[246:247], v[76:77], v[76:77], v[246:247]
	v_pk_fma_f32 v[246:247], v[78:79], v[78:79], v[246:247]
	v_pk_fma_f32 v[246:247], v[80:81], v[80:81], v[246:247]
	s_nop 0
	v_add_f32_e32 v246, v246, v247
	s_nop 1
	v_add_f32_dpp v246, v246, v246 quad_perm:[1,0,3,2] row_mask:0xf bank_mask:0xf
	s_nop 1
	v_add_f32_dpp v246, v246, v246 quad_perm:[2,3,0,1] row_mask:0xf bank_mask:0xf
	s_nop 1
	v_add_f32_dpp v246, v246, v246 row_half_mirror row_mask:0xf bank_mask:0xf
	s_nop 1
	v_add_f32_dpp v246, v246, v246 row_mirror row_mask:0xf bank_mask:0xf
	s_nop 1
	v_add_f32_dpp v246, v246, v246 row_bcast:15 row_mask:0xa bank_mask:0xf
	s_nop 1
	v_add_f32_dpp v246, v246, v246 row_bcast:31 row_mask:0xc bank_mask:0xf
	s_nop 1
	v_readlane_b32 s0, v246, 63
	s_add_i32 s21, s37, 1792
	s_lshl_b32 s21, s21, 11
	s_add_u32 s10, s16, s21
	s_addc_u32 s11, s17, 0
	v_mov_b32_e32 v248, s0
	v_fmamk_f32 v248, v248, 0x3a800000, v143
	v_rsq_f32_e32 v248, v248
	s_nop 0
	v_pk_mul_f32 v[66:67], v[66:67], v[248:249] op_sel_hi:[1,0]
	v_pk_add_f32 v[98:99], v[98:99], 1.0 op_sel_hi:[1,0]
	v_pk_mul_f32 v[66:67], v[2:3], v[66:67]
	v_pk_fma_f32 v[66:67], v[98:99], v[66:67], v[82:83]
	v_pk_mul_f32 v[68:69], v[68:69], v[248:249] op_sel_hi:[1,0]
	v_pk_add_f32 v[100:101], v[100:101], 1.0 op_sel_hi:[1,0]
	v_pk_mul_f32 v[68:69], v[4:5], v[68:69]
	v_pk_fma_f32 v[68:69], v[100:101], v[68:69], v[84:85]
	v_cvt_pk_bf16_f32 v82, v66, v67
	v_cvt_pk_bf16_f32 v83, v68, v69
	global_store_dwordx2 v245, v[82:83], s[10:11]
	v_pk_mul_f32 v[70:71], v[70:71], v[248:249] op_sel_hi:[1,0]
	v_pk_add_f32 v[102:103], v[102:103], 1.0 op_sel_hi:[1,0]
	v_pk_mul_f32 v[70:71], v[6:7], v[70:71]
	v_pk_fma_f32 v[70:71], v[102:103], v[70:71], v[86:87]
	v_pk_mul_f32 v[72:73], v[72:73], v[248:249] op_sel_hi:[1,0]
	v_pk_add_f32 v[104:105], v[104:105], 1.0 op_sel_hi:[1,0]
	v_pk_mul_f32 v[72:73], v[8:9], v[72:73]
	v_pk_fma_f32 v[72:73], v[104:105], v[72:73], v[88:89]
	v_cvt_pk_bf16_f32 v86, v70, v71
	v_cvt_pk_bf16_f32 v87, v72, v73
	global_store_dwordx2 v245, v[86:87], s[10:11] offset:512
	v_pk_mul_f32 v[74:75], v[74:75], v[248:249] op_sel_hi:[1,0]
	v_pk_add_f32 v[106:107], v[106:107], 1.0 op_sel_hi:[1,0]
	v_pk_mul_f32 v[74:75], v[10:11], v[74:75]
	v_pk_fma_f32 v[74:75], v[106:107], v[74:75], v[90:91]
	v_pk_mul_f32 v[76:77], v[76:77], v[248:249] op_sel_hi:[1,0]
	v_pk_add_f32 v[108:109], v[108:109], 1.0 op_sel_hi:[1,0]
	v_pk_mul_f32 v[76:77], v[12:13], v[76:77]
	v_pk_fma_f32 v[76:77], v[108:109], v[76:77], v[92:93]
	v_cvt_pk_bf16_f32 v90, v74, v75
	v_cvt_pk_bf16_f32 v91, v76, v77
	global_store_dwordx2 v245, v[90:91], s[10:11] offset:1024
	v_pk_mul_f32 v[78:79], v[78:79], v[248:249] op_sel_hi:[1,0]
	v_pk_add_f32 v[118:119], v[118:119], 1.0 op_sel_hi:[1,0]
	v_pk_mul_f32 v[78:79], v[14:15], v[78:79]
	v_pk_fma_f32 v[78:79], v[118:119], v[78:79], v[94:95]
	v_pk_mul_f32 v[80:81], v[80:81], v[248:249] op_sel_hi:[1,0]
	v_pk_add_f32 v[120:121], v[120:121], 1.0 op_sel_hi:[1,0]
	v_pk_mul_f32 v[80:81], v[16:17], v[80:81]
	v_pk_fma_f32 v[80:81], v[120:121], v[80:81], v[96:97]
	v_cvt_pk_bf16_f32 v94, v78, v79
	v_cvt_pk_bf16_f32 v95, v80, v81
	global_store_dwordx2 v245, v[94:95], s[10:11] offset:1536
	s_waitcnt vmcnt(8)
; DI unsigned pk_bf16(float lo, float hi) { f32x2 v = {lo, hi}; bf16v2 b = __builtin_convertvector(v, bf16v2); return __builtin_bit_cast(unsigned, b); }
; DI float red64(float x) { for (int o = 32; o > 0; o >>= 1) x += __shfl_xor(x, o); return x; }
; DI void modnorm_rows(const Params& p, int l, int which  , bool from_inputs, bool skip_ctx, int w0, int wstride, int lane) {
;   const float* g = (which ? p.norm2_g : p.norm1_g) + l * DM;
;   f32x4 gg[4];
; #pragma unroll
;   for (int i = 0; i < 4; ++i) gg[i] = *(const f32x4*)(g + i * 256 + lane * 4);
;   const int nrows = skip_ctx ? 8 * NLAT : T_TOK;
;   auto rowof = [&](int i) -> int { return skip_ctx ? (i / NLAT) * TB + NCTX + (i % NLAT) : i; };
;   int i = w0;
;   if (i >= nrows) return;
;   f32x4 vn[4];
;   {
;     const int row = rowof(i); const float* src = xsrc_row(p, from_inputs, row / TB, row % TB);
; #pragma unroll
;     for (int q = 0; q < 4; ++q) vn[q] = *(const f32x4*)(src + q * 256 + lane * 4);
;   }
;   for (; i < nrows; i += wstride) {
;     const int row = rowof(i); const int b = row / TB, s = row % TB;
;     f32x4 v[4];
; #pragma unroll
;     for (int q = 0; q < 4; ++q) v[q] = vn[q];
;     if (i + wstride < nrows) {
;       const int rn = rowof(i + wstride); const float* src = xsrc_row(p, from_inputs, rn / TB, rn % TB);
; #pragma unroll
;       for (int q = 0; q < 4; ++q) vn[q] = *(const f32x4*)(src + q * 256 + lane * 4);
;     }
;     const float* mod = p.MOD + (size_t)(l * 9 + (s < NCTX ? 8 : b)) * 6144 + (which ? 3 * 1024 : 0);
;     f32x4 sh[4], sc[4];
; #pragma unroll
;     for (int q = 0; q < 4; ++q) { sh[q] = *(const f32x4*)(mod + q * 256 + lane * 4); sc[q] = *(const f32x4*)(mod + 1024 + q * 256 + lane * 4); }
;     float ss = 0.f;
; #pragma unroll
;     for (int q = 0; q < 4; ++q) ss += v[q][0] * v[q][0] + v[q][1] * v[q][1] + v[q][2] * v[q][2] + v[q][3] * v[q][3];
;     ss = red64(ss);
;     const float rs = rsqrtf(ss * (1.f / 1024.f) + EPSF);
;     bf16_t* dst = p.HY + (size_t)row * DM;
; #pragma unroll
;     for (int q = 0; q < 4; ++q) {
;       float o[4];
; #pragma unroll
;       for (int j = 0; j < 4; ++j) o[j] = (v[q][j] * rs * gg[q][j]) * (1.f + sc[q][j]) + sh[q][j];
;       u32x2 w = {pk_bf16(o[0], o[1]), pk_bf16(o[2], o[3])};
;       *(u32x2*)(dst + q * 256 + lane * 4) = w;
;     }
	v_pk_mul_f32 v[246:247], v[122:123], v[122:123]
	v_pk_fma_f32 v[246:247], v[124:125], v[124:125], v[246:247]
	v_pk_fma_f32 v[246:247], v[126:127], v[126:127], v[246:247]
	v_pk_fma_f32 v[246:247], v[128:129], v[128:129], v[246:247]
	v_pk_fma_f32 v[246:247], v[130:131], v[130:131], v[246:247]
	v_pk_fma_f32 v[246:247], v[132:133], v[132:133], v[246:247]
	v_pk_fma_f32 v[246:247], v[134:135], v[134:135], v[246:247]
	v_pk_fma_f32 v[246:247], v[136:137], v[136:137], v[246:247]
	s_nop 0
	v_add_f32_e32 v246, v246, v247
	s_nop 1
	v_add_f32_dpp v246, v246, v246 quad_perm:[1,0,3,2] row_mask:0xf bank_mask:0xf
	s_nop 1
	v_add_f32_dpp v246, v246, v246 quad_perm:[2,3,0,1] row_mask:0xf bank_mask:0xf
	s_nop 1
	v_add_f32_dpp v246, v246, v246 row_half_mirror row_mask:0xf bank_mask:0xf
	s_nop 1
	v_add_f32_dpp v246, v246, v246 row_mirror row_mask:0xf bank_mask:0xf
	s_nop 1
	v_add_f32_dpp v246, v246, v246 row_bcast:15 row_mask:0xa bank_mask:0xf
	s_nop 1
	v_add_f32_dpp v246, v246, v246 row_bcast:31 row_mask:0xc bank_mask:0xf
	s_nop 1
	v_readlane_b32 s0, v246, 63
	s_add_i32 s21, s37, 2048
	s_lshl_b32 s21, s21, 11
	s_add_u32 s10, s16, s21
	s_addc_u32 s11, s17, 0
	v_mov_b32_e32 v248, s0
	v_fmamk_f32 v248, v248, 0x3a800000, v143
	v_rsq_f32_e32 v248, v248
	s_nop 0
	v_pk_mul_f32 v[122:123], v[122:123], v[248:249] op_sel_hi:[1,0]
	v_pk_add_f32 v[176:177], v[176:177], 1.0 op_sel_hi:[1,0]
	v_pk_mul_f32 v[122:123], v[2:3], v[122:123]
	v_pk_fma_f32 v[122:123], v[176:177], v[122:123], v[160:161]
	v_pk_mul_f32 v[124:125], v[124:125], v[248:249] op_sel_hi:[1,0]
	v_pk_add_f32 v[178:179], v[178:179], 1.0 op_sel_hi:[1,0]
	v_pk_mul_f32 v[124:125], v[4:5], v[124:125]
	v_pk_fma_f32 v[124:125], v[178:179], v[124:125], v[162:163]
	v_cvt_pk_bf16_f32 v160, v122, v123
	v_cvt_pk_bf16_f32 v161, v124, v125
	global_store_dwordx2 v245, v[160:161], s[10:11]
	v_pk_mul_f32 v[126:127], v[126:127], v[248:249] op_sel_hi:[1,0]
	v_pk_add_f32 v[180:181], v[180:181], 1.0 op_sel_hi:[1,0]
	v_pk_mul_f32 v[126:127], v[6:7], v[126:127]
	v_pk_fma_f32 v[126:127], v[180:181], v[126:127], v[164:165]
	v_pk_mul_f32 v[128:129], v[128:129], v[248:249] op_sel_hi:[1,0]
	v_pk_add_f32 v[182:183], v[182:183], 1.0 op_sel_hi:[1,0]
	v_pk_mul_f32 v[128:129], v[8:9], v[128:129]
	v_pk_fma_f32 v[128:129], v[182:183], v[128:129], v[166:167]
	v_cvt_pk_bf16_f32 v164, v126, v127
	v_cvt_pk_bf16_f32 v165, v128, v129
	global_store_dwordx2 v245, v[164:165], s[10:11] offset:512
	v_pk_mul_f32 v[130:131], v[130:131], v[248:249] op_sel_hi:[1,0]
	v_pk_add_f32 v[184:185], v[184:185], 1.0 op_sel_hi:[1,0]
	v_pk_mul_f32 v[130:131], v[10:11], v[130:131]
	v_pk_fma_f32 v[130:131], v[184:185], v[130:131], v[168:169]
	v_pk_mul_f32 v[132:133], v[132:133], v[248:249] op_sel_hi:[1,0]
	v_pk_add_f32 v[186:187], v[186:187], 1.0 op_sel_hi:[1,0]
	v_pk_mul_f32 v[132:133], v[12:13], v[132:133]
	v_pk_fma_f32 v[132:133], v[186:187], v[132:133], v[170:171]
	v_cvt_pk_bf16_f32 v168, v130, v131
	v_cvt_pk_bf16_f32 v169, v132, v133
	global_store_dwordx2 v245, v[168:169], s[10:11] offset:1024
	v_pk_mul_f32 v[134:135], v[134:135], v[248:249] op_sel_hi:[1,0]
	v_pk_add_f32 v[188:189], v[188:189], 1.0 op_sel_hi:[1,0]
	v_pk_mul_f32 v[134:135], v[14:15], v[134:135]
	v_pk_fma_f32 v[134:135], v[188:189], v[134:135], v[172:173]
	v_pk_mul_f32 v[136:137], v[136:137], v[248:249] op_sel_hi:[1,0]
	v_pk_add_f32 v[190:191], v[190:191], 1.0 op_sel_hi:[1,0]
	v_pk_mul_f32 v[136:137], v[16:17], v[136:137]
	v_pk_fma_f32 v[136:137], v[190:191], v[136:137], v[174:175]
	v_cvt_pk_bf16_f32 v172, v134, v135
	v_cvt_pk_bf16_f32 v173, v136, v137
	global_store_dwordx2 v245, v[172:173], s[10:11] offset:1536
	s_branch .Lnorm2_done
.Lnorm2_last:
	s_lshr_b32 s39, s20, 5
	s_lshl_b32 s39, s39, 2
	s_and_b32 s38, s20, 3
	s_or_b32 s39, s39, s38
	s_lshr_b32 s38, s20, 2
	s_and_b32 s38, s38, 7
	s_mul_i32 s37, s38, 0x900
	s_add_i32 s37, s37, s39
	s_add_i32 s21, s37, 256
	s_mov_b32 s7, s38
	s_add_i32 s8, s39, 256
	s_lshl_b32 s9, s7, 11
	s_add_i32 s9, s9, s8
	s_add_i32 s9, s9, 0xffffff00
	s_lshl_b32 s10, s7, 8
	s_add_i32 s10, s10, s8
	s_cmpk_gt_i32 s8, 0xff
	s_cselect_b32 s9, s9, s10
	s_cselect_b32 s26, s12, s14
	s_cselect_b32 s27, s13, s15
	s_cselect_b32 s10, s7, 8
	s_lshl_b32 s9, s9, 12
	s_add_u32 s26, s26, s9
	s_addc_u32 s27, s27, 0
	s_add_i32 s10, s10, s82
	s_mul_i32 s10, s10, s24
	s_add_u32 s28, s58, s10
	s_addc_u32 s29, s59, 0
	s_add_u32 s28, s28, 0x3000
	s_addc_u32 s29, s29, 0
	s_add_u32 s0, s28, 0x1000
	s_addc_u32 s1, s29, 0
	global_load_dwordx4 v[18:21], v244, s[26:27]
	global_load_dwordx4 v[22:25], v244, s[26:27] offset:1024
	global_load_dwordx4 v[26:29], v244, s[26:27] offset:2048
	global_load_dwordx4 v[30:33], v244, s[26:27] offset:3072
	global_load_dwordx4 v[34:37], v244, s[28:29]
	global_load_dwordx4 v[38:41], v244, s[28:29] offset:1024
	global_load_dwordx4 v[42:45], v244, s[28:29] offset:2048
	global_load_dwordx4 v[46:49], v244, s[28:29] offset:3072
	global_load_dwordx4 v[50:53], v244, s[0:1]
	global_load_dwordx4 v[54:57], v244, s[0:1] offset:1024
	global_load_dwordx4 v[58:61], v244, s[0:1] offset:2048
	global_load_dwordx4 v[62:65], v244, s[0:1] offset:3072
	s_add_i32 s21, s37, 512
	s_mov_b32 s7, s38
	s_add_i32 s8, s39, 512
	s_lshl_b32 s9, s7, 11
	s_add_i32 s9, s9, s8
	s_add_i32 s9, s9, 0xffffff00
	s_lshl_b32 s10, s7, 8
	s_add_i32 s10, s10, s8
	s_cmpk_gt_i32 s8, 0xff
	s_cselect_b32 s9, s9, s10
	s_cselect_b32 s26, s12, s14
	s_cselect_b32 s27, s13, s15
	s_cselect_b32 s10, s7, 8
	s_lshl_b32 s9, s9, 12
	s_add_u32 s26, s26, s9
	s_addc_u32 s27, s27, 0
	s_add_i32 s10, s10, s82
	s_mul_i32 s10, s10, s24
	s_add_u32 s28, s58, s10
	s_addc_u32 s29, s59, 0
	s_add_u32 s28, s28, 0x3000
	s_addc_u32 s29, s29, 0
; DI unsigned pk_bf16(float lo, float hi) { f32x2 v = {lo, hi}; bf16v2 b = __builtin_convertvector(v, bf16v2); return __builtin_bit_cast(unsigned, b); }
; DI float red64(float x) { for (int o = 32; o > 0; o >>= 1) x += __shfl_xor(x, o); return x; }
; DI void modnorm_rows(const Params& p, int l, int which  , bool from_inputs, bool skip_ctx, int w0, int wstride, int lane) {
;     ...
;     const int row = rowof(i); const int b = row / TB, s = row % TB;
;     f32x4 v[4];
; #pragma unroll
;     for (int q = 0; q < 4; ++q) v[q] = vn[q];
;     if (i + wstride < nrows) {
;       const int rn = rowof(i + wstride); const float* src = xsrc_row(p, from_inputs, rn / TB, rn % TB);
; #pragma unroll
;       for (int q = 0; q < 4; ++q) vn[q] = *(const f32x4*)(src + q * 256 + lane * 4);
;     }
;     const float* mod = p.MOD + (size_t)(l * 9 + (s < NCTX ? 8 : b)) * 6144 + (which ? 3 * 1024 : 0);
;     f32x4 sh[4], sc[4];
; #pragma unroll
;     for (int q = 0; q < 4; ++q) { sh[q] = *(const f32x4*)(mod + q * 256 + lane * 4); sc[q] = *(const f32x4*)(mod + 1024 + q * 256 + lane * 4); }
;     float ss = 0.f;
; #pragma unroll
;     for (int q = 0; q < 4; ++q) ss += v[q][0] * v[q][0] + v[q][1] * v[q][1] + v[q][2] * v[q][2] + v[q][3] * v[q][3];
;     ss = red64(ss);
;     const float rs = rsqrtf(ss * (1.f / 1024.f) + EPSF);
;     bf16_t* dst = p.HY + (size_t)row * DM;
; #pragma unroll
;     for (int q = 0; q < 4; ++q) {
;       float o[4];
; #pragma unroll
;       for (int j = 0; j < 4; ++j) o[j] = (v[q][j] * rs * gg[q][j]) * (1.f + sc[q][j]) + sh[q][j];
;       u32x2 w = {pk_bf16(o[0], o[1]), pk_bf16(o[2], o[3])};
;       *(u32x2*)(dst + q * 256 + lane * 4) = w;
;     }
	s_add_u32 s0, s28, 0x1000
	s_addc_u32 s1, s29, 0
	global_load_dwordx4 v[66:69], v244, s[26:27]
	global_load_dwordx4 v[70:73], v244, s[26:27] offset:1024
	global_load_dwordx4 v[74:77], v244, s[26:27] offset:2048
	global_load_dwordx4 v[78:81], v244, s[26:27] offset:3072
	global_load_dwordx4 v[82:85], v244, s[28:29]
	global_load_dwordx4 v[86:89], v244, s[28:29] offset:1024
	global_load_dwordx4 v[90:93], v244, s[28:29] offset:2048
	global_load_dwordx4 v[94:97], v244, s[28:29] offset:3072
	global_load_dwordx4 v[98:101], v244, s[0:1]
	global_load_dwordx4 v[102:105], v244, s[0:1] offset:1024
	global_load_dwordx4 v[106:109], v244, s[0:1] offset:2048
	global_load_dwordx4 v[118:121], v244, s[0:1] offset:3072
	s_add_i32 s21, s37, 768
	s_mov_b32 s7, s38
	s_add_i32 s8, s39, 768
	s_lshl_b32 s9, s7, 11
	s_add_i32 s9, s9, s8
	s_add_i32 s9, s9, 0xffffff00
	s_lshl_b32 s10, s7, 8
	s_add_i32 s10, s10, s8
	s_cmpk_gt_i32 s8, 0xff
	s_cselect_b32 s9, s9, s10
	s_cselect_b32 s26, s12, s14
	s_cselect_b32 s27, s13, s15
	s_cselect_b32 s10, s7, 8
	s_lshl_b32 s9, s9, 12
	s_add_u32 s26, s26, s9
	s_addc_u32 s27, s27, 0
	s_add_i32 s10, s10, s82
	s_mul_i32 s10, s10, s24
	s_add_u32 s28, s58, s10
	s_addc_u32 s29, s59, 0
	s_add_u32 s28, s28, 0x3000
	s_addc_u32 s29, s29, 0
	s_add_u32 s0, s28, 0x1000
	s_addc_u32 s1, s29, 0
	global_load_dwordx4 v[122:125], v244, s[26:27]
	global_load_dwordx4 v[126:129], v244, s[26:27] offset:1024
	global_load_dwordx4 v[130:133], v244, s[26:27] offset:2048
	global_load_dwordx4 v[134:137], v244, s[26:27] offset:3072
	global_load_dwordx4 v[160:163], v244, s[28:29]
	global_load_dwordx4 v[164:167], v244, s[28:29] offset:1024
	global_load_dwordx4 v[168:171], v244, s[28:29] offset:2048
	global_load_dwordx4 v[172:175], v244, s[28:29] offset:3072
	global_load_dwordx4 v[176:179], v244, s[0:1]
	global_load_dwordx4 v[180:183], v244, s[0:1] offset:1024
	global_load_dwordx4 v[184:187], v244, s[0:1] offset:2048
	global_load_dwordx4 v[188:191], v244, s[0:1] offset:3072
	s_waitcnt vmcnt(24)
	v_pk_mul_f32 v[246:247], v[18:19], v[18:19]
	v_pk_fma_f32 v[246:247], v[20:21], v[20:21], v[246:247]
	v_pk_fma_f32 v[246:247], v[22:23], v[22:23], v[246:247]
	v_pk_fma_f32 v[246:247], v[24:25], v[24:25], v[246:247]
	v_pk_fma_f32 v[246:247], v[26:27], v[26:27], v[246:247]
	v_pk_fma_f32 v[246:247], v[28:29], v[28:29], v[246:247]
	v_pk_fma_f32 v[246:247], v[30:31], v[30:31], v[246:247]
	v_pk_fma_f32 v[246:247], v[32:33], v[32:33], v[246:247]
	s_nop 0
	v_add_f32_e32 v246, v246, v247
	s_nop 1
	v_add_f32_dpp v246, v246, v246 quad_perm:[1,0,3,2] row_mask:0xf bank_mask:0xf
	s_nop 1
	v_add_f32_dpp v246, v246, v246 quad_perm:[2,3,0,1] row_mask:0xf bank_mask:0xf
	s_nop 1
	v_add_f32_dpp v246, v246, v246 row_half_mirror row_mask:0xf bank_mask:0xf
	s_nop 1
	v_add_f32_dpp v246, v246, v246 row_mirror row_mask:0xf bank_mask:0xf
	s_nop 1
	v_add_f32_dpp v246, v246, v246 row_bcast:15 row_mask:0xa bank_mask:0xf
	s_nop 1
	v_add_f32_dpp v246, v246, v246 row_bcast:31 row_mask:0xc bank_mask:0xf
	s_nop 1
	v_readlane_b32 s0, v246, 63
	s_add_i32 s21, s37, 256
	s_lshl_b32 s21, s21, 11
	s_add_u32 s10, s16, s21
	s_addc_u32 s11, s17, 0
	v_mov_b32_e32 v248, s0
	v_fmamk_f32 v248, v248, 0x3a800000, v143
	v_rsq_f32_e32 v248, v248
	s_nop 0
	v_pk_mul_f32 v[18:19], v[18:19], v[248:249] op_sel_hi:[1,0]
	v_pk_add_f32 v[50:51], v[50:51], 1.0 op_sel_hi:[1,0]
	v_pk_mul_f32 v[18:19], v[2:3], v[18:19]
	v_pk_fma_f32 v[18:19], v[50:51], v[18:19], v[34:35]
	v_pk_mul_f32 v[20:21], v[20:21], v[248:249] op_sel_hi:[1,0]
	v_pk_add_f32 v[52:53], v[52:53], 1.0 op_sel_hi:[1,0]
	v_pk_mul_f32 v[20:21], v[4:5], v[20:21]
	v_pk_fma_f32 v[20:21], v[52:53], v[20:21], v[36:37]
	v_cvt_pk_bf16_f32 v34, v18, v19
	v_cvt_pk_bf16_f32 v35, v20, v21
	global_store_dwordx2 v245, v[34:35], s[10:11]
	v_pk_mul_f32 v[22:23], v[22:23], v[248:249] op_sel_hi:[1,0]
	v_pk_add_f32 v[54:55], v[54:55], 1.0 op_sel_hi:[1,0]
	v_pk_mul_f32 v[22:23], v[6:7], v[22:23]
	v_pk_fma_f32 v[22:23], v[54:55], v[22:23], v[38:39]
	v_pk_mul_f32 v[24:25], v[24:25], v[248:249] op_sel_hi:[1,0]
	v_pk_add_f32 v[56:57], v[56:57], 1.0 op_sel_hi:[1,0]
	v_pk_mul_f32 v[24:25], v[8:9], v[24:25]
	v_pk_fma_f32 v[24:25], v[56:57], v[24:25], v[40:41]
	v_cvt_pk_bf16_f32 v38, v22, v23
	v_cvt_pk_bf16_f32 v39, v24, v25
	global_store_dwordx2 v245, v[38:39], s[10:11] offset:512
	v_pk_mul_f32 v[26:27], v[26:27], v[248:249] op_sel_hi:[1,0]
	v_pk_add_f32 v[58:59], v[58:59], 1.0 op_sel_hi:[1,0]
	v_pk_mul_f32 v[26:27], v[10:11], v[26:27]
	v_pk_fma_f32 v[26:27], v[58:59], v[26:27], v[42:43]
	v_pk_mul_f32 v[28:29], v[28:29], v[248:249] op_sel_hi:[1,0]
	v_pk_add_f32 v[60:61], v[60:61], 1.0 op_sel_hi:[1,0]
	v_pk_mul_f32 v[28:29], v[12:13], v[28:29]
	v_pk_fma_f32 v[28:29], v[60:61], v[28:29], v[44:45]
	v_cvt_pk_bf16_f32 v42, v26, v27
	v_cvt_pk_bf16_f32 v43, v28, v29
	global_store_dwordx2 v245, v[42:43], s[10:11] offset:1024
	v_pk_mul_f32 v[30:31], v[30:31], v[248:249] op_sel_hi:[1,0]
	v_pk_add_f32 v[62:63], v[62:63], 1.0 op_sel_hi:[1,0]
	v_pk_mul_f32 v[30:31], v[14:15], v[30:31]
	v_pk_fma_f32 v[30:31], v[62:63], v[30:31], v[46:47]
	v_pk_mul_f32 v[32:33], v[32:33], v[248:249] op_sel_hi:[1,0]
	v_pk_add_f32 v[64:65], v[64:65], 1.0 op_sel_hi:[1,0]
	v_pk_mul_f32 v[32:33], v[16:17], v[32:33]
	v_pk_fma_f32 v[32:33], v[64:65], v[32:33], v[48:49]
	v_cvt_pk_bf16_f32 v46, v30, v31
	v_cvt_pk_bf16_f32 v47, v32, v33
	global_store_dwordx2 v245, v[46:47], s[10:11] offset:1536
	s_add_i32 s21, s37, 1024
	s_mov_b32 s7, s38
	s_add_i32 s8, s39, 1024
	s_lshl_b32 s9, s7, 11
	s_add_i32 s9, s9, s8
	s_add_i32 s9, s9, 0xffffff00
	s_lshl_b32 s10, s7, 8
	s_add_i32 s10, s10, s8
	s_cmpk_gt_i32 s8, 0xff
	s_cselect_b32 s9, s9, s10
	s_cselect_b32 s26, s12, s14
	s_cselect_b32 s27, s13, s15
	s_cselect_b32 s10, s7, 8
	s_lshl_b32 s9, s9, 12
	s_add_u32 s26, s26, s9
	s_addc_u32 s27, s27, 0
	s_add_i32 s10, s10, s82
	s_mul_i32 s10, s10, s24
	s_add_u32 s28, s58, s10
	s_addc_u32 s29, s59, 0
	s_add_u32 s28, s28, 0x3000
	s_addc_u32 s29, s29, 0
	s_add_u32 s0, s28, 0x1000
	s_addc_u32 s1, s29, 0
	global_load_dwordx4 v[18:21], v244, s[26:27]
	global_load_dwordx4 v[22:25], v244, s[26:27] offset:1024
	global_load_dwordx4 v[26:29], v244, s[26:27] offset:2048
	global_load_dwordx4 v[30:33], v244, s[26:27] offset:3072
	global_load_dwordx4 v[34:37], v244, s[28:29]
	global_load_dwordx4 v[38:41], v244, s[28:29] offset:1024
	global_load_dwordx4 v[42:45], v244, s[28:29] offset:2048
	global_load_dwordx4 v[46:49], v244, s[28:29] offset:3072
	global_load_dwordx4 v[50:53], v244, s[0:1]
	global_load_dwordx4 v[54:57], v244, s[0:1] offset:1024
	global_load_dwordx4 v[58:61], v244, s[0:1] offset:2048
	global_load_dwordx4 v[62:65], v244, s[0:1] offset:3072
	s_waitcnt vmcnt(28)
; DI unsigned pk_bf16(float lo, float hi) { f32x2 v = {lo, hi}; bf16v2 b = __builtin_convertvector(v, bf16v2); return __builtin_bit_cast(unsigned, b); }
; DI float red64(float x) { for (int o = 32; o > 0; o >>= 1) x += __shfl_xor(x, o); return x; }
; DI void modnorm_rows(const Params& p, int l, int which  , bool from_inputs, bool skip_ctx, int w0, int wstride, int lane) {
;     ...
;     const int row = rowof(i); const int b = row / TB, s = row % TB;
;     f32x4 v[4];
; #pragma unroll
;     for (int q = 0; q < 4; ++q) v[q] = vn[q];
;     if (i + wstride < nrows) {
;       const int rn = rowof(i + wstride); const float* src = xsrc_row(p, from_inputs, rn / TB, rn % TB);
; #pragma unroll
;       for (int q = 0; q < 4; ++q) vn[q] = *(const f32x4*)(src + q * 256 + lane * 4);
;     }
;     const float* mod = p.MOD + (size_t)(l * 9 + (s < NCTX ? 8 : b)) * 6144 + (which ? 3 * 1024 : 0);
;     f32x4 sh[4], sc[4];
; #pragma unroll
;     for (int q = 0; q < 4; ++q) { sh[q] = *(const f32x4*)(mod + q * 256 + lane * 4); sc[q] = *(const f32x4*)(mod + 1024 + q * 256 + lane * 4); }
;     float ss = 0.f;
; #pragma unroll
;     for (int q = 0; q < 4; ++q) ss += v[q][0] * v[q][0] + v[q][1] * v[q][1] + v[q][2] * v[q][2] + v[q][3] * v[q][3];
;     ss = red64(ss);
;     const float rs = rsqrtf(ss * (1.f / 1024.f) + EPSF);
;     bf16_t* dst = p.HY + (size_t)row * DM;
; #pragma unroll
;     for (int q = 0; q < 4; ++q) {
;       float o[4];
; #pragma unroll
;       for (int j = 0; j < 4; ++j) o[j] = (v[q][j] * rs * gg[q][j]) * (1.f + sc[q][j]) + sh[q][j];
;       u32x2 w = {pk_bf16(o[0], o[1]), pk_bf16(o[2], o[3])};
;       *(u32x2*)(dst + q * 256 + lane * 4) = w;
;     }
	v_pk_mul_f32 v[246:247], v[66:67], v[66:67]
	v_pk_fma_f32 v[246:247], v[68:69], v[68:69], v[246:247]
	v_pk_fma_f32 v[246:247], v[70:71], v[70:71], v[246:247]
	v_pk_fma_f32 v[246:247], v[72:73], v[72:73], v[246:247]
	v_pk_fma_f32 v[246:247], v[74:75], v[74:75], v[246:247]
	v_pk_fma_f32 v[246:247], v[76:77], v[76:77], v[246:247]
	v_pk_fma_f32 v[246:247], v[78:79], v[78:79], v[246:247]
	v_pk_fma_f32 v[246:247], v[80:81], v[80:81], v[246:247]
	s_nop 0
	v_add_f32_e32 v246, v246, v247
	s_nop 1
	v_add_f32_dpp v246, v246, v246 quad_perm:[1,0,3,2] row_mask:0xf bank_mask:0xf
	s_nop 1
	v_add_f32_dpp v246, v246, v246 quad_perm:[2,3,0,1] row_mask:0xf bank_mask:0xf
	s_nop 1
	v_add_f32_dpp v246, v246, v246 row_half_mirror row_mask:0xf bank_mask:0xf
	s_nop 1
	v_add_f32_dpp v246, v246, v246 row_mirror row_mask:0xf bank_mask:0xf
	s_nop 1
	v_add_f32_dpp v246, v246, v246 row_bcast:15 row_mask:0xa bank_mask:0xf
	s_nop 1
	v_add_f32_dpp v246, v246, v246 row_bcast:31 row_mask:0xc bank_mask:0xf
	s_nop 1
	v_readlane_b32 s0, v246, 63
	s_add_i32 s21, s37, 512
	s_lshl_b32 s21, s21, 11
	s_add_u32 s10, s16, s21
	s_addc_u32 s11, s17, 0
	v_mov_b32_e32 v248, s0
	v_fmamk_f32 v248, v248, 0x3a800000, v143
	v_rsq_f32_e32 v248, v248
	s_nop 0
	v_pk_mul_f32 v[66:67], v[66:67], v[248:249] op_sel_hi:[1,0]
	v_pk_add_f32 v[98:99], v[98:99], 1.0 op_sel_hi:[1,0]
	v_pk_mul_f32 v[66:67], v[2:3], v[66:67]
	v_pk_fma_f32 v[66:67], v[98:99], v[66:67], v[82:83]
	v_pk_mul_f32 v[68:69], v[68:69], v[248:249] op_sel_hi:[1,0]
	v_pk_add_f32 v[100:101], v[100:101], 1.0 op_sel_hi:[1,0]
	v_pk_mul_f32 v[68:69], v[4:5], v[68:69]
	v_pk_fma_f32 v[68:69], v[100:101], v[68:69], v[84:85]
	v_cvt_pk_bf16_f32 v82, v66, v67
	v_cvt_pk_bf16_f32 v83, v68, v69
	global_store_dwordx2 v245, v[82:83], s[10:11]
	v_pk_mul_f32 v[70:71], v[70:71], v[248:249] op_sel_hi:[1,0]
	v_pk_add_f32 v[102:103], v[102:103], 1.0 op_sel_hi:[1,0]
	v_pk_mul_f32 v[70:71], v[6:7], v[70:71]
	v_pk_fma_f32 v[70:71], v[102:103], v[70:71], v[86:87]
	v_pk_mul_f32 v[72:73], v[72:73], v[248:249] op_sel_hi:[1,0]
	v_pk_add_f32 v[104:105], v[104:105], 1.0 op_sel_hi:[1,0]
	v_pk_mul_f32 v[72:73], v[8:9], v[72:73]
	v_pk_fma_f32 v[72:73], v[104:105], v[72:73], v[88:89]
	v_cvt_pk_bf16_f32 v86, v70, v71
	v_cvt_pk_bf16_f32 v87, v72, v73
	global_store_dwordx2 v245, v[86:87], s[10:11] offset:512
	v_pk_mul_f32 v[74:75], v[74:75], v[248:249] op_sel_hi:[1,0]
	v_pk_add_f32 v[106:107], v[106:107], 1.0 op_sel_hi:[1,0]
	v_pk_mul_f32 v[74:75], v[10:11], v[74:75]
	v_pk_fma_f32 v[74:75], v[106:107], v[74:75], v[90:91]
	v_pk_mul_f32 v[76:77], v[76:77], v[248:249] op_sel_hi:[1,0]
	v_pk_add_f32 v[108:109], v[108:109], 1.0 op_sel_hi:[1,0]
	v_pk_mul_f32 v[76:77], v[12:13], v[76:77]
	v_pk_fma_f32 v[76:77], v[108:109], v[76:77], v[92:93]
	v_cvt_pk_bf16_f32 v90, v74, v75
	v_cvt_pk_bf16_f32 v91, v76, v77
	global_store_dwordx2 v245, v[90:91], s[10:11] offset:1024
	v_pk_mul_f32 v[78:79], v[78:79], v[248:249] op_sel_hi:[1,0]
	v_pk_add_f32 v[118:119], v[118:119], 1.0 op_sel_hi:[1,0]
	v_pk_mul_f32 v[78:79], v[14:15], v[78:79]
	v_pk_fma_f32 v[78:79], v[118:119], v[78:79], v[94:95]
	v_pk_mul_f32 v[80:81], v[80:81], v[248:249] op_sel_hi:[1,0]
	v_pk_add_f32 v[120:121], v[120:121], 1.0 op_sel_hi:[1,0]
	v_pk_mul_f32 v[80:81], v[16:17], v[80:81]
	v_pk_fma_f32 v[80:81], v[120:121], v[80:81], v[96:97]
	v_cvt_pk_bf16_f32 v94, v78, v79
	v_cvt_pk_bf16_f32 v95, v80, v81
	global_store_dwordx2 v245, v[94:95], s[10:11] offset:1536
	s_add_i32 s21, s37, 1280
	s_mov_b32 s7, s38
	s_add_i32 s8, s39, 1280
	s_lshl_b32 s9, s7, 11
	s_add_i32 s9, s9, s8
	s_add_i32 s9, s9, 0xffffff00
	s_lshl_b32 s10, s7, 8
	s_add_i32 s10, s10, s8
	s_cmpk_gt_i32 s8, 0xff
	s_cselect_b32 s9, s9, s10
	s_cselect_b32 s26, s12, s14
	s_cselect_b32 s27, s13, s15
	s_cselect_b32 s10, s7, 8
	s_lshl_b32 s9, s9, 12
	s_add_u32 s26, s26, s9
	s_addc_u32 s27, s27, 0
	s_add_i32 s10, s10, s82
	s_mul_i32 s10, s10, s24
	s_add_u32 s28, s58, s10
	s_addc_u32 s29, s59, 0
	s_add_u32 s28, s28, 0x3000
	s_addc_u32 s29, s29, 0
	s_add_u32 s0, s28, 0x1000
	s_addc_u32 s1, s29, 0
	global_load_dwordx4 v[66:69], v244, s[26:27]
	global_load_dwordx4 v[70:73], v244, s[26:27] offset:1024
	global_load_dwordx4 v[74:77], v244, s[26:27] offset:2048
	global_load_dwordx4 v[78:81], v244, s[26:27] offset:3072
	global_load_dwordx4 v[82:85], v244, s[28:29]
	global_load_dwordx4 v[86:89], v244, s[28:29] offset:1024
	global_load_dwordx4 v[90:93], v244, s[28:29] offset:2048
	global_load_dwordx4 v[94:97], v244, s[28:29] offset:3072
	global_load_dwordx4 v[98:101], v244, s[0:1]
	global_load_dwordx4 v[102:105], v244, s[0:1] offset:1024
	global_load_dwordx4 v[106:109], v244, s[0:1] offset:2048
	global_load_dwordx4 v[118:121], v244, s[0:1] offset:3072
	s_waitcnt vmcnt(32)
; DI unsigned pk_bf16(float lo, float hi) { f32x2 v = {lo, hi}; bf16v2 b = __builtin_convertvector(v, bf16v2); return __builtin_bit_cast(unsigned, b); }
; DI float red64(float x) { for (int o = 32; o > 0; o >>= 1) x += __shfl_xor(x, o); return x; }
; DI void modnorm_rows(const Params& p, int l, int which  , bool from_inputs, bool skip_ctx, int w0, int wstride, int lane) {
;     ...
;     const int row = rowof(i); const int b = row / TB, s = row % TB;
;     f32x4 v[4];
; #pragma unroll
;     for (int q = 0; q < 4; ++q) v[q] = vn[q];
;     if (i + wstride < nrows) {
;       const int rn = rowof(i + wstride); const float* src = xsrc_row(p, from_inputs, rn / TB, rn % TB);
; #pragma unroll
;       for (int q = 0; q < 4; ++q) vn[q] = *(const f32x4*)(src + q * 256 + lane * 4);
;     }
;     const float* mod = p.MOD + (size_t)(l * 9 + (s < NCTX ? 8 : b)) * 6144 + (which ? 3 * 1024 : 0);
;     f32x4 sh[4], sc[4];
; #pragma unroll
;     for (int q = 0; q < 4; ++q) { sh[q] = *(const f32x4*)(mod + q * 256 + lane * 4); sc[q] = *(const f32x4*)(mod + 1024 + q * 256 + lane * 4); }
;     float ss = 0.f;
; #pragma unroll
;     for (int q = 0; q < 4; ++q) ss += v[q][0] * v[q][0] + v[q][1] * v[q][1] + v[q][2] * v[q][2] + v[q][3] * v[q][3];
;     ss = red64(ss);
;     const float rs = rsqrtf(ss * (1.f / 1024.f) + EPSF);
;     bf16_t* dst = p.HY + (size_t)row * DM;
; #pragma unroll
;     for (int q = 0; q < 4; ++q) {
;       float o[4];
; #pragma unroll
;       for (int j = 0; j < 4; ++j) o[j] = (v[q][j] * rs * gg[q][j]) * (1.f + sc[q][j]) + sh[q][j];
;       u32x2 w = {pk_bf16(o[0], o[1]), pk_bf16(o[2], o[3])};
;       *(u32x2*)(dst + q * 256 + lane * 4) = w;
;     }
	v_pk_mul_f32 v[246:247], v[122:123], v[122:123]
	v_pk_fma_f32 v[246:247], v[124:125], v[124:125], v[246:247]
	v_pk_fma_f32 v[246:247], v[126:127], v[126:127], v[246:247]
	v_pk_fma_f32 v[246:247], v[128:129], v[128:129], v[246:247]
	v_pk_fma_f32 v[246:247], v[130:131], v[130:131], v[246:247]
	v_pk_fma_f32 v[246:247], v[132:133], v[132:133], v[246:247]
	v_pk_fma_f32 v[246:247], v[134:135], v[134:135], v[246:247]
	v_pk_fma_f32 v[246:247], v[136:137], v[136:137], v[246:247]
	s_nop 0
	v_add_f32_e32 v246, v246, v247
	s_nop 1
	v_add_f32_dpp v246, v246, v246 quad_perm:[1,0,3,2] row_mask:0xf bank_mask:0xf
	s_nop 1
	v_add_f32_dpp v246, v246, v246 quad_perm:[2,3,0,1] row_mask:0xf bank_mask:0xf
	s_nop 1
	v_add_f32_dpp v246, v246, v246 row_half_mirror row_mask:0xf bank_mask:0xf
	s_nop 1
	v_add_f32_dpp v246, v246, v246 row_mirror row_mask:0xf bank_mask:0xf
	s_nop 1
	v_add_f32_dpp v246, v246, v246 row_bcast:15 row_mask:0xa bank_mask:0xf
	s_nop 1
	v_add_f32_dpp v246, v246, v246 row_bcast:31 row_mask:0xc bank_mask:0xf
	s_nop 1
	v_readlane_b32 s0, v246, 63
	s_add_i32 s21, s37, 768
	s_lshl_b32 s21, s21, 11
	s_add_u32 s10, s16, s21
	s_addc_u32 s11, s17, 0
	v_mov_b32_e32 v248, s0
	v_fmamk_f32 v248, v248, 0x3a800000, v143
	v_rsq_f32_e32 v248, v248
	s_nop 0
	v_pk_mul_f32 v[122:123], v[122:123], v[248:249] op_sel_hi:[1,0]
	v_pk_add_f32 v[176:177], v[176:177], 1.0 op_sel_hi:[1,0]
	v_pk_mul_f32 v[122:123], v[2:3], v[122:123]
	v_pk_fma_f32 v[122:123], v[176:177], v[122:123], v[160:161]
	v_pk_mul_f32 v[124:125], v[124:125], v[248:249] op_sel_hi:[1,0]
	v_pk_add_f32 v[178:179], v[178:179], 1.0 op_sel_hi:[1,0]
	v_pk_mul_f32 v[124:125], v[4:5], v[124:125]
	v_pk_fma_f32 v[124:125], v[178:179], v[124:125], v[162:163]
	v_cvt_pk_bf16_f32 v160, v122, v123
	v_cvt_pk_bf16_f32 v161, v124, v125
	global_store_dwordx2 v245, v[160:161], s[10:11]
	v_pk_mul_f32 v[126:127], v[126:127], v[248:249] op_sel_hi:[1,0]
	v_pk_add_f32 v[180:181], v[180:181], 1.0 op_sel_hi:[1,0]
	v_pk_mul_f32 v[126:127], v[6:7], v[126:127]
	v_pk_fma_f32 v[126:127], v[180:181], v[126:127], v[164:165]
	v_pk_mul_f32 v[128:129], v[128:129], v[248:249] op_sel_hi:[1,0]
	v_pk_add_f32 v[182:183], v[182:183], 1.0 op_sel_hi:[1,0]
	v_pk_mul_f32 v[128:129], v[8:9], v[128:129]
	v_pk_fma_f32 v[128:129], v[182:183], v[128:129], v[166:167]
	v_cvt_pk_bf16_f32 v164, v126, v127
	v_cvt_pk_bf16_f32 v165, v128, v129
	global_store_dwordx2 v245, v[164:165], s[10:11] offset:512
	v_pk_mul_f32 v[130:131], v[130:131], v[248:249] op_sel_hi:[1,0]
	v_pk_add_f32 v[184:185], v[184:185], 1.0 op_sel_hi:[1,0]
	v_pk_mul_f32 v[130:131], v[10:11], v[130:131]
	v_pk_fma_f32 v[130:131], v[184:185], v[130:131], v[168:169]
	v_pk_mul_f32 v[132:133], v[132:133], v[248:249] op_sel_hi:[1,0]
	v_pk_add_f32 v[186:187], v[186:187], 1.0 op_sel_hi:[1,0]
	v_pk_mul_f32 v[132:133], v[12:13], v[132:133]
	v_pk_fma_f32 v[132:133], v[186:187], v[132:133], v[170:171]
	v_cvt_pk_bf16_f32 v168, v130, v131
	v_cvt_pk_bf16_f32 v169, v132, v133
	global_store_dwordx2 v245, v[168:169], s[10:11] offset:1024
	v_pk_mul_f32 v[134:135], v[134:135], v[248:249] op_sel_hi:[1,0]
	v_pk_add_f32 v[188:189], v[188:189], 1.0 op_sel_hi:[1,0]
	v_pk_mul_f32 v[134:135], v[14:15], v[134:135]
	v_pk_fma_f32 v[134:135], v[188:189], v[134:135], v[172:173]
	v_pk_mul_f32 v[136:137], v[136:137], v[248:249] op_sel_hi:[1,0]
	v_pk_add_f32 v[190:191], v[190:191], 1.0 op_sel_hi:[1,0]
	v_pk_mul_f32 v[136:137], v[16:17], v[136:137]
	v_pk_fma_f32 v[136:137], v[190:191], v[136:137], v[174:175]
	v_cvt_pk_bf16_f32 v172, v134, v135
	v_cvt_pk_bf16_f32 v173, v136, v137
	global_store_dwordx2 v245, v[172:173], s[10:11] offset:1536
	s_add_i32 s21, s37, 1536
	s_mov_b32 s7, s38
	s_add_i32 s8, s39, 1536
	s_lshl_b32 s9, s7, 11
	s_add_i32 s9, s9, s8
	s_add_i32 s9, s9, 0xffffff00
	s_lshl_b32 s10, s7, 8
	s_add_i32 s10, s10, s8
	s_cmpk_gt_i32 s8, 0xff
	s_cselect_b32 s9, s9, s10
	s_cselect_b32 s26, s12, s14
	s_cselect_b32 s27, s13, s15
	s_cselect_b32 s10, s7, 8
	s_lshl_b32 s9, s9, 12
	s_add_u32 s26, s26, s9
	s_addc_u32 s27, s27, 0
	s_add_i32 s10, s10, s82
	s_mul_i32 s10, s10, s24
	s_add_u32 s28, s58, s10
	s_addc_u32 s29, s59, 0
	s_add_u32 s28, s28, 0x3000
	s_addc_u32 s29, s29, 0
	s_add_u32 s0, s28, 0x1000
	s_addc_u32 s1, s29, 0
	global_load_dwordx4 v[122:125], v244, s[26:27]
	global_load_dwordx4 v[126:129], v244, s[26:27] offset:1024
	global_load_dwordx4 v[130:133], v244, s[26:27] offset:2048
	global_load_dwordx4 v[134:137], v244, s[26:27] offset:3072
	global_load_dwordx4 v[160:163], v244, s[28:29]
	global_load_dwordx4 v[164:167], v244, s[28:29] offset:1024
	global_load_dwordx4 v[168:171], v244, s[28:29] offset:2048
	global_load_dwordx4 v[172:175], v244, s[28:29] offset:3072
	global_load_dwordx4 v[176:179], v244, s[0:1]
	global_load_dwordx4 v[180:183], v244, s[0:1] offset:1024
	global_load_dwordx4 v[184:187], v244, s[0:1] offset:2048
	global_load_dwordx4 v[188:191], v244, s[0:1] offset:3072
	s_waitcnt vmcnt(32)
; DI unsigned pk_bf16(float lo, float hi) { f32x2 v = {lo, hi}; bf16v2 b = __builtin_convertvector(v, bf16v2); return __builtin_bit_cast(unsigned, b); }
; DI float red64(float x) { for (int o = 32; o > 0; o >>= 1) x += __shfl_xor(x, o); return x; }
; DI void modnorm_rows(const Params& p, int l, int which  , bool from_inputs, bool skip_ctx, int w0, int wstride, int lane) {
;     ...
;     const int row = rowof(i); const int b = row / TB, s = row % TB;
;     f32x4 v[4];
; #pragma unroll
;     for (int q = 0; q < 4; ++q) v[q] = vn[q];
;     if (i + wstride < nrows) {
;       const int rn = rowof(i + wstride); const float* src = xsrc_row(p, from_inputs, rn / TB, rn % TB);
; #pragma unroll
;       for (int q = 0; q < 4; ++q) vn[q] = *(const f32x4*)(src + q * 256 + lane * 4);
;     }
;     const float* mod = p.MOD + (size_t)(l * 9 + (s < NCTX ? 8 : b)) * 6144 + (which ? 3 * 1024 : 0);
;     f32x4 sh[4], sc[4];
; #pragma unroll
;     for (int q = 0; q < 4; ++q) { sh[q] = *(const f32x4*)(mod + q * 256 + lane * 4); sc[q] = *(const f32x4*)(mod + 1024 + q * 256 + lane * 4); }
;     float ss = 0.f;
; #pragma unroll
;     for (int q = 0; q < 4; ++q) ss += v[q][0] * v[q][0] + v[q][1] * v[q][1] + v[q][2] * v[q][2] + v[q][3] * v[q][3];
;     ss = red64(ss);
;     const float rs = rsqrtf(ss * (1.f / 1024.f) + EPSF);
;     bf16_t* dst = p.HY + (size_t)row * DM;
; #pragma unroll
;     for (int q = 0; q < 4; ++q) {
;       float o[4];
; #pragma unroll
;       for (int j = 0; j < 4; ++j) o[j] = (v[q][j] * rs * gg[q][j]) * (1.f + sc[q][j]) + sh[q][j];
;       u32x2 w = {pk_bf16(o[0], o[1]), pk_bf16(o[2], o[3])};
;       *(u32x2*)(dst + q * 256 + lane * 4) = w;
;     }
	v_pk_mul_f32 v[246:247], v[18:19], v[18:19]
	v_pk_fma_f32 v[246:247], v[20:21], v[20:21], v[246:247]
	v_pk_fma_f32 v[246:247], v[22:23], v[22:23], v[246:247]
	v_pk_fma_f32 v[246:247], v[24:25], v[24:25], v[246:247]
	v_pk_fma_f32 v[246:247], v[26:27], v[26:27], v[246:247]
	v_pk_fma_f32 v[246:247], v[28:29], v[28:29], v[246:247]
	v_pk_fma_f32 v[246:247], v[30:31], v[30:31], v[246:247]
	v_pk_fma_f32 v[246:247], v[32:33], v[32:33], v[246:247]
	s_nop 0
	v_add_f32_e32 v246, v246, v247
	s_nop 1
	v_add_f32_dpp v246, v246, v246 quad_perm:[1,0,3,2] row_mask:0xf bank_mask:0xf
	s_nop 1
	v_add_f32_dpp v246, v246, v246 quad_perm:[2,3,0,1] row_mask:0xf bank_mask:0xf
	s_nop 1
	v_add_f32_dpp v246, v246, v246 row_half_mirror row_mask:0xf bank_mask:0xf
	s_nop 1
	v_add_f32_dpp v246, v246, v246 row_mirror row_mask:0xf bank_mask:0xf
	s_nop 1
	v_add_f32_dpp v246, v246, v246 row_bcast:15 row_mask:0xa bank_mask:0xf
	s_nop 1
	v_add_f32_dpp v246, v246, v246 row_bcast:31 row_mask:0xc bank_mask:0xf
	s_nop 1
	v_readlane_b32 s0, v246, 63
	s_add_i32 s21, s37, 1024
	s_lshl_b32 s21, s21, 11
	s_add_u32 s10, s16, s21
	s_addc_u32 s11, s17, 0
	v_mov_b32_e32 v248, s0
	v_fmamk_f32 v248, v248, 0x3a800000, v143
	v_rsq_f32_e32 v248, v248
	s_nop 0
	v_pk_mul_f32 v[18:19], v[18:19], v[248:249] op_sel_hi:[1,0]
	v_pk_add_f32 v[50:51], v[50:51], 1.0 op_sel_hi:[1,0]
	v_pk_mul_f32 v[18:19], v[2:3], v[18:19]
	v_pk_fma_f32 v[18:19], v[50:51], v[18:19], v[34:35]
	v_pk_mul_f32 v[20:21], v[20:21], v[248:249] op_sel_hi:[1,0]
	v_pk_add_f32 v[52:53], v[52:53], 1.0 op_sel_hi:[1,0]
	v_pk_mul_f32 v[20:21], v[4:5], v[20:21]
	v_pk_fma_f32 v[20:21], v[52:53], v[20:21], v[36:37]
	v_cvt_pk_bf16_f32 v34, v18, v19
	v_cvt_pk_bf16_f32 v35, v20, v21
	global_store_dwordx2 v245, v[34:35], s[10:11]
	v_pk_mul_f32 v[22:23], v[22:23], v[248:249] op_sel_hi:[1,0]
	v_pk_add_f32 v[54:55], v[54:55], 1.0 op_sel_hi:[1,0]
	v_pk_mul_f32 v[22:23], v[6:7], v[22:23]
	v_pk_fma_f32 v[22:23], v[54:55], v[22:23], v[38:39]
	v_pk_mul_f32 v[24:25], v[24:25], v[248:249] op_sel_hi:[1,0]
	v_pk_add_f32 v[56:57], v[56:57], 1.0 op_sel_hi:[1,0]
	v_pk_mul_f32 v[24:25], v[8:9], v[24:25]
	v_pk_fma_f32 v[24:25], v[56:57], v[24:25], v[40:41]
	v_cvt_pk_bf16_f32 v38, v22, v23
	v_cvt_pk_bf16_f32 v39, v24, v25
	global_store_dwordx2 v245, v[38:39], s[10:11] offset:512
	v_pk_mul_f32 v[26:27], v[26:27], v[248:249] op_sel_hi:[1,0]
	v_pk_add_f32 v[58:59], v[58:59], 1.0 op_sel_hi:[1,0]
	v_pk_mul_f32 v[26:27], v[10:11], v[26:27]
	v_pk_fma_f32 v[26:27], v[58:59], v[26:27], v[42:43]
	v_pk_mul_f32 v[28:29], v[28:29], v[248:249] op_sel_hi:[1,0]
	v_pk_add_f32 v[60:61], v[60:61], 1.0 op_sel_hi:[1,0]
	v_pk_mul_f32 v[28:29], v[12:13], v[28:29]
	v_pk_fma_f32 v[28:29], v[60:61], v[28:29], v[44:45]
	v_cvt_pk_bf16_f32 v42, v26, v27
	v_cvt_pk_bf16_f32 v43, v28, v29
	global_store_dwordx2 v245, v[42:43], s[10:11] offset:1024
	v_pk_mul_f32 v[30:31], v[30:31], v[248:249] op_sel_hi:[1,0]
	v_pk_add_f32 v[62:63], v[62:63], 1.0 op_sel_hi:[1,0]
	v_pk_mul_f32 v[30:31], v[14:15], v[30:31]
	v_pk_fma_f32 v[30:31], v[62:63], v[30:31], v[46:47]
	v_pk_mul_f32 v[32:33], v[32:33], v[248:249] op_sel_hi:[1,0]
	v_pk_add_f32 v[64:65], v[64:65], 1.0 op_sel_hi:[1,0]
	v_pk_mul_f32 v[32:33], v[16:17], v[32:33]
	v_pk_fma_f32 v[32:33], v[64:65], v[32:33], v[48:49]
	v_cvt_pk_bf16_f32 v46, v30, v31
	v_cvt_pk_bf16_f32 v47, v32, v33
	global_store_dwordx2 v245, v[46:47], s[10:11] offset:1536
	s_add_i32 s21, s37, 1792
	s_mov_b32 s7, s38
	s_add_i32 s8, s39, 1792
	s_lshl_b32 s9, s7, 11
	s_add_i32 s9, s9, s8
	s_add_i32 s9, s9, 0xffffff00
	s_lshl_b32 s10, s7, 8
	s_add_i32 s10, s10, s8
	s_cmpk_gt_i32 s8, 0xff
	s_cselect_b32 s9, s9, s10
	s_cselect_b32 s26, s12, s14
	s_cselect_b32 s27, s13, s15
	s_cselect_b32 s10, s7, 8
	s_lshl_b32 s9, s9, 12
	s_add_u32 s26, s26, s9
	s_addc_u32 s27, s27, 0
	s_add_i32 s10, s10, s82
	s_mul_i32 s10, s10, s24
	s_add_u32 s28, s58, s10
	s_addc_u32 s29, s59, 0
	s_add_u32 s28, s28, 0x3000
	s_addc_u32 s29, s29, 0
	s_add_u32 s0, s28, 0x1000
	s_addc_u32 s1, s29, 0
	global_load_dwordx4 v[18:21], v244, s[26:27]
	global_load_dwordx4 v[22:25], v244, s[26:27] offset:1024
	global_load_dwordx4 v[26:29], v244, s[26:27] offset:2048
	global_load_dwordx4 v[30:33], v244, s[26:27] offset:3072
	global_load_dwordx4 v[34:37], v244, s[28:29]
	global_load_dwordx4 v[38:41], v244, s[28:29] offset:1024
	global_load_dwordx4 v[42:45], v244, s[28:29] offset:2048
	global_load_dwordx4 v[46:49], v244, s[28:29] offset:3072
	global_load_dwordx4 v[50:53], v244, s[0:1]
	global_load_dwordx4 v[54:57], v244, s[0:1] offset:1024
	global_load_dwordx4 v[58:61], v244, s[0:1] offset:2048
	global_load_dwordx4 v[62:65], v244, s[0:1] offset:3072
	s_waitcnt vmcnt(32)
; DI unsigned pk_bf16(float lo, float hi) { f32x2 v = {lo, hi}; bf16v2 b = __builtin_convertvector(v, bf16v2); return __builtin_bit_cast(unsigned, b); }
; DI float red64(float x) { for (int o = 32; o > 0; o >>= 1) x += __shfl_xor(x, o); return x; }
; DI void modnorm_rows(const Params& p, int l, int which  , bool from_inputs, bool skip_ctx, int w0, int wstride, int lane) {
;     ...
;     const int row = rowof(i); const int b = row / TB, s = row % TB;
;     f32x4 v[4];
; #pragma unroll
;     for (int q = 0; q < 4; ++q) v[q] = vn[q];
;     if (i + wstride < nrows) {
;       const int rn = rowof(i + wstride); const float* src = xsrc_row(p, from_inputs, rn / TB, rn % TB);
; #pragma unroll
;       for (int q = 0; q < 4; ++q) vn[q] = *(const f32x4*)(src + q * 256 + lane * 4);
;     }
;     const float* mod = p.MOD + (size_t)(l * 9 + (s < NCTX ? 8 : b)) * 6144 + (which ? 3 * 1024 : 0);
;     f32x4 sh[4], sc[4];
; #pragma unroll
;     for (int q = 0; q < 4; ++q) { sh[q] = *(const f32x4*)(mod + q * 256 + lane * 4); sc[q] = *(const f32x4*)(mod + 1024 + q * 256 + lane * 4); }
;     float ss = 0.f;
; #pragma unroll
;     for (int q = 0; q < 4; ++q) ss += v[q][0] * v[q][0] + v[q][1] * v[q][1] + v[q][2] * v[q][2] + v[q][3] * v[q][3];
;     ss = red64(ss);
;     const float rs = rsqrtf(ss * (1.f / 1024.f) + EPSF);
;     bf16_t* dst = p.HY + (size_t)row * DM;
; #pragma unroll
;     for (int q = 0; q < 4; ++q) {
;       float o[4];
; #pragma unroll
;       for (int j = 0; j < 4; ++j) o[j] = (v[q][j] * rs * gg[q][j]) * (1.f + sc[q][j]) + sh[q][j];
;       u32x2 w = {pk_bf16(o[0], o[1]), pk_bf16(o[2], o[3])};
;       *(u32x2*)(dst + q * 256 + lane * 4) = w;
;     }
	v_pk_mul_f32 v[246:247], v[66:67], v[66:67]
	v_pk_fma_f32 v[246:247], v[68:69], v[68:69], v[246:247]
	v_pk_fma_f32 v[246:247], v[70:71], v[70:71], v[246:247]
	v_pk_fma_f32 v[246:247], v[72:73], v[72:73], v[246:247]
	v_pk_fma_f32 v[246:247], v[74:75], v[74:75], v[246:247]
	v_pk_fma_f32 v[246:247], v[76:77], v[76:77], v[246:247]
	v_pk_fma_f32 v[246:247], v[78:79], v[78:79], v[246:247]
	v_pk_fma_f32 v[246:247], v[80:81], v[80:81], v[246:247]
	s_nop 0
	v_add_f32_e32 v246, v246, v247
	s_nop 1
	v_add_f32_dpp v246, v246, v246 quad_perm:[1,0,3,2] row_mask:0xf bank_mask:0xf
	s_nop 1
	v_add_f32_dpp v246, v246, v246 quad_perm:[2,3,0,1] row_mask:0xf bank_mask:0xf
	s_nop 1
	v_add_f32_dpp v246, v246, v246 row_half_mirror row_mask:0xf bank_mask:0xf
	s_nop 1
	v_add_f32_dpp v246, v246, v246 row_mirror row_mask:0xf bank_mask:0xf
	s_nop 1
	v_add_f32_dpp v246, v246, v246 row_bcast:15 row_mask:0xa bank_mask:0xf
	s_nop 1
	v_add_f32_dpp v246, v246, v246 row_bcast:31 row_mask:0xc bank_mask:0xf
	s_nop 1
	v_readlane_b32 s0, v246, 63
	s_add_i32 s21, s37, 1280
	s_lshl_b32 s21, s21, 11
	s_add_u32 s10, s16, s21
	s_addc_u32 s11, s17, 0
	v_mov_b32_e32 v248, s0
	v_fmamk_f32 v248, v248, 0x3a800000, v143
	v_rsq_f32_e32 v248, v248
	s_nop 0
	v_pk_mul_f32 v[66:67], v[66:67], v[248:249] op_sel_hi:[1,0]
	v_pk_add_f32 v[98:99], v[98:99], 1.0 op_sel_hi:[1,0]
	v_pk_mul_f32 v[66:67], v[2:3], v[66:67]
	v_pk_fma_f32 v[66:67], v[98:99], v[66:67], v[82:83]
	v_pk_mul_f32 v[68:69], v[68:69], v[248:249] op_sel_hi:[1,0]
	v_pk_add_f32 v[100:101], v[100:101], 1.0 op_sel_hi:[1,0]
	v_pk_mul_f32 v[68:69], v[4:5], v[68:69]
	v_pk_fma_f32 v[68:69], v[100:101], v[68:69], v[84:85]
	v_cvt_pk_bf16_f32 v82, v66, v67
	v_cvt_pk_bf16_f32 v83, v68, v69
	global_store_dwordx2 v245, v[82:83], s[10:11]
	v_pk_mul_f32 v[70:71], v[70:71], v[248:249] op_sel_hi:[1,0]
	v_pk_add_f32 v[102:103], v[102:103], 1.0 op_sel_hi:[1,0]
	v_pk_mul_f32 v[70:71], v[6:7], v[70:71]
	v_pk_fma_f32 v[70:71], v[102:103], v[70:71], v[86:87]
	v_pk_mul_f32 v[72:73], v[72:73], v[248:249] op_sel_hi:[1,0]
	v_pk_add_f32 v[104:105], v[104:105], 1.0 op_sel_hi:[1,0]
	v_pk_mul_f32 v[72:73], v[8:9], v[72:73]
	v_pk_fma_f32 v[72:73], v[104:105], v[72:73], v[88:89]
	v_cvt_pk_bf16_f32 v86, v70, v71
	v_cvt_pk_bf16_f32 v87, v72, v73
	global_store_dwordx2 v245, v[86:87], s[10:11] offset:512
	v_pk_mul_f32 v[74:75], v[74:75], v[248:249] op_sel_hi:[1,0]
	v_pk_add_f32 v[106:107], v[106:107], 1.0 op_sel_hi:[1,0]
	v_pk_mul_f32 v[74:75], v[10:11], v[74:75]
	v_pk_fma_f32 v[74:75], v[106:107], v[74:75], v[90:91]
	v_pk_mul_f32 v[76:77], v[76:77], v[248:249] op_sel_hi:[1,0]
	v_pk_add_f32 v[108:109], v[108:109], 1.0 op_sel_hi:[1,0]
	v_pk_mul_f32 v[76:77], v[12:13], v[76:77]
	v_pk_fma_f32 v[76:77], v[108:109], v[76:77], v[92:93]
	v_cvt_pk_bf16_f32 v90, v74, v75
	v_cvt_pk_bf16_f32 v91, v76, v77
	global_store_dwordx2 v245, v[90:91], s[10:11] offset:1024
	v_pk_mul_f32 v[78:79], v[78:79], v[248:249] op_sel_hi:[1,0]
	v_pk_add_f32 v[118:119], v[118:119], 1.0 op_sel_hi:[1,0]
	v_pk_mul_f32 v[78:79], v[14:15], v[78:79]
	v_pk_fma_f32 v[78:79], v[118:119], v[78:79], v[94:95]
	v_pk_mul_f32 v[80:81], v[80:81], v[248:249] op_sel_hi:[1,0]
	v_pk_add_f32 v[120:121], v[120:121], 1.0 op_sel_hi:[1,0]
	v_pk_mul_f32 v[80:81], v[16:17], v[80:81]
	v_pk_fma_f32 v[80:81], v[120:121], v[80:81], v[96:97]
	v_cvt_pk_bf16_f32 v94, v78, v79
	v_cvt_pk_bf16_f32 v95, v80, v81
	global_store_dwordx2 v245, v[94:95], s[10:11] offset:1536
	s_add_i32 s21, s37, 2048
	s_mov_b32 s7, s38
	s_add_i32 s8, s39, 2048
	s_lshl_b32 s9, s7, 11
	s_add_i32 s9, s9, s8
	s_add_i32 s9, s9, 0xffffff00
	s_lshl_b32 s10, s7, 8
	s_add_i32 s10, s10, s8
	s_cmpk_gt_i32 s8, 0xff
	s_cselect_b32 s9, s9, s10
	s_cselect_b32 s26, s12, s14
	s_cselect_b32 s27, s13, s15
	s_cselect_b32 s10, s7, 8
	s_lshl_b32 s9, s9, 12
	s_add_u32 s26, s26, s9
	s_addc_u32 s27, s27, 0
	s_add_i32 s10, s10, s82
	s_mul_i32 s10, s10, s24
	s_add_u32 s28, s58, s10
	s_addc_u32 s29, s59, 0
	s_add_u32 s28, s28, 0x3000
	s_addc_u32 s29, s29, 0
	s_add_u32 s0, s28, 0x1000
	s_addc_u32 s1, s29, 0
	global_load_dwordx4 v[66:69], v244, s[26:27]
	global_load_dwordx4 v[70:73], v244, s[26:27] offset:1024
	global_load_dwordx4 v[74:77], v244, s[26:27] offset:2048
	global_load_dwordx4 v[78:81], v244, s[26:27] offset:3072
	global_load_dwordx4 v[82:85], v244, s[28:29]
	global_load_dwordx4 v[86:89], v244, s[28:29] offset:1024
	global_load_dwordx4 v[90:93], v244, s[28:29] offset:2048
	global_load_dwordx4 v[94:97], v244, s[28:29] offset:3072
	global_load_dwordx4 v[98:101], v244, s[0:1]
	global_load_dwordx4 v[102:105], v244, s[0:1] offset:1024
	global_load_dwordx4 v[106:109], v244, s[0:1] offset:2048
	global_load_dwordx4 v[118:121], v244, s[0:1] offset:3072
	s_waitcnt vmcnt(32)
; DI unsigned pk_bf16(float lo, float hi) { f32x2 v = {lo, hi}; bf16v2 b = __builtin_convertvector(v, bf16v2); return __builtin_bit_cast(unsigned, b); }
; DI float red64(float x) { for (int o = 32; o > 0; o >>= 1) x += __shfl_xor(x, o); return x; }
; DI void modnorm_rows(const Params& p, int l, int which  , bool from_inputs, bool skip_ctx, int w0, int wstride, int lane) {
;     ...
;     const int row = rowof(i); const int b = row / TB, s = row % TB;
;     f32x4 v[4];
; #pragma unroll
;     for (int q = 0; q < 4; ++q) v[q] = vn[q];
;     if (i + wstride < nrows) {
;       const int rn = rowof(i + wstride); const float* src = xsrc_row(p, from_inputs, rn / TB, rn % TB);
; #pragma unroll
;       for (int q = 0; q < 4; ++q) vn[q] = *(const f32x4*)(src + q * 256 + lane * 4);
;     }
;     const float* mod = p.MOD + (size_t)(l * 9 + (s < NCTX ? 8 : b)) * 6144 + (which ? 3 * 1024 : 0);
;     f32x4 sh[4], sc[4];
; #pragma unroll
;     for (int q = 0; q < 4; ++q) { sh[q] = *(const f32x4*)(mod + q * 256 + lane * 4); sc[q] = *(const f32x4*)(mod + 1024 + q * 256 + lane * 4); }
;     float ss = 0.f;
; #pragma unroll
;     for (int q = 0; q < 4; ++q) ss += v[q][0] * v[q][0] + v[q][1] * v[q][1] + v[q][2] * v[q][2] + v[q][3] * v[q][3];
;     ss = red64(ss);
;     const float rs = rsqrtf(ss * (1.f / 1024.f) + EPSF);
;     bf16_t* dst = p.HY + (size_t)row * DM;
; #pragma unroll
;     for (int q = 0; q < 4; ++q) {
;       float o[4];
; #pragma unroll
;       for (int j = 0; j < 4; ++j) o[j] = (v[q][j] * rs * gg[q][j]) * (1.f + sc[q][j]) + sh[q][j];
;       u32x2 w = {pk_bf16(o[0], o[1]), pk_bf16(o[2], o[3])};
;       *(u32x2*)(dst + q * 256 + lane * 4) = w;
;     }
	v_pk_mul_f32 v[246:247], v[122:123], v[122:123]
	v_pk_fma_f32 v[246:247], v[124:125], v[124:125], v[246:247]
	v_pk_fma_f32 v[246:247], v[126:127], v[126:127], v[246:247]
	v_pk_fma_f32 v[246:247], v[128:129], v[128:129], v[246:247]
	v_pk_fma_f32 v[246:247], v[130:131], v[130:131], v[246:247]
	v_pk_fma_f32 v[246:247], v[132:133], v[132:133], v[246:247]
	v_pk_fma_f32 v[246:247], v[134:135], v[134:135], v[246:247]
	v_pk_fma_f32 v[246:247], v[136:137], v[136:137], v[246:247]
	s_nop 0
	v_add_f32_e32 v246, v246, v247
	s_nop 1
	v_add_f32_dpp v246, v246, v246 quad_perm:[1,0,3,2] row_mask:0xf bank_mask:0xf
	s_nop 1
	v_add_f32_dpp v246, v246, v246 quad_perm:[2,3,0,1] row_mask:0xf bank_mask:0xf
	s_nop 1
	v_add_f32_dpp v246, v246, v246 row_half_mirror row_mask:0xf bank_mask:0xf
	s_nop 1
	v_add_f32_dpp v246, v246, v246 row_mirror row_mask:0xf bank_mask:0xf
	s_nop 1
	v_add_f32_dpp v246, v246, v246 row_bcast:15 row_mask:0xa bank_mask:0xf
	s_nop 1
	v_add_f32_dpp v246, v246, v246 row_bcast:31 row_mask:0xc bank_mask:0xf
	s_nop 1
	v_readlane_b32 s0, v246, 63
	s_add_i32 s21, s37, 1536
	s_lshl_b32 s21, s21, 11
	s_add_u32 s10, s16, s21
	s_addc_u32 s11, s17, 0
	v_mov_b32_e32 v248, s0
	v_fmamk_f32 v248, v248, 0x3a800000, v143
	v_rsq_f32_e32 v248, v248
	s_nop 0
	v_pk_mul_f32 v[122:123], v[122:123], v[248:249] op_sel_hi:[1,0]
	v_pk_add_f32 v[176:177], v[176:177], 1.0 op_sel_hi:[1,0]
	v_pk_mul_f32 v[122:123], v[2:3], v[122:123]
	v_pk_fma_f32 v[122:123], v[176:177], v[122:123], v[160:161]
	v_pk_mul_f32 v[124:125], v[124:125], v[248:249] op_sel_hi:[1,0]
	v_pk_add_f32 v[178:179], v[178:179], 1.0 op_sel_hi:[1,0]
	v_pk_mul_f32 v[124:125], v[4:5], v[124:125]
	v_pk_fma_f32 v[124:125], v[178:179], v[124:125], v[162:163]
	v_cvt_pk_bf16_f32 v160, v122, v123
	v_cvt_pk_bf16_f32 v161, v124, v125
	global_store_dwordx2 v245, v[160:161], s[10:11]
	v_pk_mul_f32 v[126:127], v[126:127], v[248:249] op_sel_hi:[1,0]
	v_pk_add_f32 v[180:181], v[180:181], 1.0 op_sel_hi:[1,0]
	v_pk_mul_f32 v[126:127], v[6:7], v[126:127]
	v_pk_fma_f32 v[126:127], v[180:181], v[126:127], v[164:165]
	v_pk_mul_f32 v[128:129], v[128:129], v[248:249] op_sel_hi:[1,0]
	v_pk_add_f32 v[182:183], v[182:183], 1.0 op_sel_hi:[1,0]
	v_pk_mul_f32 v[128:129], v[8:9], v[128:129]
	v_pk_fma_f32 v[128:129], v[182:183], v[128:129], v[166:167]
	v_cvt_pk_bf16_f32 v164, v126, v127
	v_cvt_pk_bf16_f32 v165, v128, v129
	global_store_dwordx2 v245, v[164:165], s[10:11] offset:512
	v_pk_mul_f32 v[130:131], v[130:131], v[248:249] op_sel_hi:[1,0]
	v_pk_add_f32 v[184:185], v[184:185], 1.0 op_sel_hi:[1,0]
	v_pk_mul_f32 v[130:131], v[10:11], v[130:131]
	v_pk_fma_f32 v[130:131], v[184:185], v[130:131], v[168:169]
	v_pk_mul_f32 v[132:133], v[132:133], v[248:249] op_sel_hi:[1,0]
	v_pk_add_f32 v[186:187], v[186:187], 1.0 op_sel_hi:[1,0]
	v_pk_mul_f32 v[132:133], v[12:13], v[132:133]
	v_pk_fma_f32 v[132:133], v[186:187], v[132:133], v[170:171]
	v_cvt_pk_bf16_f32 v168, v130, v131
	v_cvt_pk_bf16_f32 v169, v132, v133
	global_store_dwordx2 v245, v[168:169], s[10:11] offset:1024
	v_pk_mul_f32 v[134:135], v[134:135], v[248:249] op_sel_hi:[1,0]
	v_pk_add_f32 v[188:189], v[188:189], 1.0 op_sel_hi:[1,0]
	v_pk_mul_f32 v[134:135], v[14:15], v[134:135]
	v_pk_fma_f32 v[134:135], v[188:189], v[134:135], v[172:173]
	v_pk_mul_f32 v[136:137], v[136:137], v[248:249] op_sel_hi:[1,0]
	v_pk_add_f32 v[190:191], v[190:191], 1.0 op_sel_hi:[1,0]
	v_pk_mul_f32 v[136:137], v[16:17], v[136:137]
	v_pk_fma_f32 v[136:137], v[190:191], v[136:137], v[174:175]
	v_cvt_pk_bf16_f32 v172, v134, v135
	v_cvt_pk_bf16_f32 v173, v136, v137
	global_store_dwordx2 v245, v[172:173], s[10:11] offset:1536
	s_waitcnt vmcnt(20)
; DI unsigned pk_bf16(float lo, float hi) { f32x2 v = {lo, hi}; bf16v2 b = __builtin_convertvector(v, bf16v2); return __builtin_bit_cast(unsigned, b); }
; DI float red64(float x) { for (int o = 32; o > 0; o >>= 1) x += __shfl_xor(x, o); return x; }
; DI void modnorm_rows(const Params& p, int l, int which  , bool from_inputs, bool skip_ctx, int w0, int wstride, int lane) {
;     ...
;     const int row = rowof(i); const int b = row / TB, s = row % TB;
;     f32x4 v[4];
; #pragma unroll
;     for (int q = 0; q < 4; ++q) v[q] = vn[q];
;     if (i + wstride < nrows) {
;       const int rn = rowof(i + wstride); const float* src = xsrc_row(p, from_inputs, rn / TB, rn % TB);
; #pragma unroll
;       for (int q = 0; q < 4; ++q) vn[q] = *(const f32x4*)(src + q * 256 + lane * 4);
;     }
;     const float* mod = p.MOD + (size_t)(l * 9 + (s < NCTX ? 8 : b)) * 6144 + (which ? 3 * 1024 : 0);
;     f32x4 sh[4], sc[4];
; #pragma unroll
;     for (int q = 0; q < 4; ++q) { sh[q] = *(const f32x4*)(mod + q * 256 + lane * 4); sc[q] = *(const f32x4*)(mod + 1024 + q * 256 + lane * 4); }
;     float ss = 0.f;
; #pragma unroll
;     for (int q = 0; q < 4; ++q) ss += v[q][0] * v[q][0] + v[q][1] * v[q][1] + v[q][2] * v[q][2] + v[q][3] * v[q][3];
;     ss = red64(ss);
;     const float rs = rsqrtf(ss * (1.f / 1024.f) + EPSF);
;     bf16_t* dst = p.HY + (size_t)row * DM;
; #pragma unroll
;     for (int q = 0; q < 4; ++q) {
;       float o[4];
; #pragma unroll
;       for (int j = 0; j < 4; ++j) o[j] = (v[q][j] * rs * gg[q][j]) * (1.f + sc[q][j]) + sh[q][j];
;       u32x2 w = {pk_bf16(o[0], o[1]), pk_bf16(o[2], o[3])};
;       *(u32x2*)(dst + q * 256 + lane * 4) = w;
;     }
	v_pk_mul_f32 v[246:247], v[18:19], v[18:19]
	v_pk_fma_f32 v[246:247], v[20:21], v[20:21], v[246:247]
	v_pk_fma_f32 v[246:247], v[22:23], v[22:23], v[246:247]
	v_pk_fma_f32 v[246:247], v[24:25], v[24:25], v[246:247]
	v_pk_fma_f32 v[246:247], v[26:27], v[26:27], v[246:247]
	v_pk_fma_f32 v[246:247], v[28:29], v[28:29], v[246:247]
	v_pk_fma_f32 v[246:247], v[30:31], v[30:31], v[246:247]
	v_pk_fma_f32 v[246:247], v[32:33], v[32:33], v[246:247]
	s_nop 0
	v_add_f32_e32 v246, v246, v247
	s_nop 1
	v_add_f32_dpp v246, v246, v246 quad_perm:[1,0,3,2] row_mask:0xf bank_mask:0xf
	s_nop 1
	v_add_f32_dpp v246, v246, v246 quad_perm:[2,3,0,1] row_mask:0xf bank_mask:0xf
	s_nop 1
	v_add_f32_dpp v246, v246, v246 row_half_mirror row_mask:0xf bank_mask:0xf
	s_nop 1
	v_add_f32_dpp v246, v246, v246 row_mirror row_mask:0xf bank_mask:0xf
	s_nop 1
	v_add_f32_dpp v246, v246, v246 row_bcast:15 row_mask:0xa bank_mask:0xf
	s_nop 1
	v_add_f32_dpp v246, v246, v246 row_bcast:31 row_mask:0xc bank_mask:0xf
	s_nop 1
	v_readlane_b32 s0, v246, 63
	s_add_i32 s21, s37, 1792
	s_lshl_b32 s21, s21, 11
	s_add_u32 s10, s16, s21
	s_addc_u32 s11, s17, 0
	v_mov_b32_e32 v248, s0
	v_fmamk_f32 v248, v248, 0x3a800000, v143
	v_rsq_f32_e32 v248, v248
	s_nop 0
	v_pk_mul_f32 v[18:19], v[18:19], v[248:249] op_sel_hi:[1,0]
	v_pk_add_f32 v[50:51], v[50:51], 1.0 op_sel_hi:[1,0]
	v_pk_mul_f32 v[18:19], v[2:3], v[18:19]
	v_pk_fma_f32 v[18:19], v[50:51], v[18:19], v[34:35]
	v_pk_mul_f32 v[20:21], v[20:21], v[248:249] op_sel_hi:[1,0]
	v_pk_add_f32 v[52:53], v[52:53], 1.0 op_sel_hi:[1,0]
	v_pk_mul_f32 v[20:21], v[4:5], v[20:21]
	v_pk_fma_f32 v[20:21], v[52:53], v[20:21], v[36:37]
	v_cvt_pk_bf16_f32 v34, v18, v19
	v_cvt_pk_bf16_f32 v35, v20, v21
	global_store_dwordx2 v245, v[34:35], s[10:11]
	v_pk_mul_f32 v[22:23], v[22:23], v[248:249] op_sel_hi:[1,0]
	v_pk_add_f32 v[54:55], v[54:55], 1.0 op_sel_hi:[1,0]
	v_pk_mul_f32 v[22:23], v[6:7], v[22:23]
	v_pk_fma_f32 v[22:23], v[54:55], v[22:23], v[38:39]
	v_pk_mul_f32 v[24:25], v[24:25], v[248:249] op_sel_hi:[1,0]
	v_pk_add_f32 v[56:57], v[56:57], 1.0 op_sel_hi:[1,0]
	v_pk_mul_f32 v[24:25], v[8:9], v[24:25]
	v_pk_fma_f32 v[24:25], v[56:57], v[24:25], v[40:41]
	v_cvt_pk_bf16_f32 v38, v22, v23
	v_cvt_pk_bf16_f32 v39, v24, v25
	global_store_dwordx2 v245, v[38:39], s[10:11] offset:512
	v_pk_mul_f32 v[26:27], v[26:27], v[248:249] op_sel_hi:[1,0]
	v_pk_add_f32 v[58:59], v[58:59], 1.0 op_sel_hi:[1,0]
	v_pk_mul_f32 v[26:27], v[10:11], v[26:27]
	v_pk_fma_f32 v[26:27], v[58:59], v[26:27], v[42:43]
	v_pk_mul_f32 v[28:29], v[28:29], v[248:249] op_sel_hi:[1,0]
	v_pk_add_f32 v[60:61], v[60:61], 1.0 op_sel_hi:[1,0]
	v_pk_mul_f32 v[28:29], v[12:13], v[28:29]
	v_pk_fma_f32 v[28:29], v[60:61], v[28:29], v[44:45]
	v_cvt_pk_bf16_f32 v42, v26, v27
	v_cvt_pk_bf16_f32 v43, v28, v29
	global_store_dwordx2 v245, v[42:43], s[10:11] offset:1024
	v_pk_mul_f32 v[30:31], v[30:31], v[248:249] op_sel_hi:[1,0]
	v_pk_add_f32 v[62:63], v[62:63], 1.0 op_sel_hi:[1,0]
	v_pk_mul_f32 v[30:31], v[14:15], v[30:31]
	v_pk_fma_f32 v[30:31], v[62:63], v[30:31], v[46:47]
	v_pk_mul_f32 v[32:33], v[32:33], v[248:249] op_sel_hi:[1,0]
	v_pk_add_f32 v[64:65], v[64:65], 1.0 op_sel_hi:[1,0]
	v_pk_mul_f32 v[32:33], v[16:17], v[32:33]
	v_pk_fma_f32 v[32:33], v[64:65], v[32:33], v[48:49]
	v_cvt_pk_bf16_f32 v46, v30, v31
	v_cvt_pk_bf16_f32 v47, v32, v33
	global_store_dwordx2 v245, v[46:47], s[10:11] offset:1536
	s_waitcnt vmcnt(8)
	v_pk_mul_f32 v[246:247], v[66:67], v[66:67]
	v_pk_fma_f32 v[246:247], v[68:69], v[68:69], v[246:247]
	v_pk_fma_f32 v[246:247], v[70:71], v[70:71], v[246:247]
	v_pk_fma_f32 v[246:247], v[72:73], v[72:73], v[246:247]
	v_pk_fma_f32 v[246:247], v[74:75], v[74:75], v[246:247]
	v_pk_fma_f32 v[246:247], v[76:77], v[76:77], v[246:247]
	v_pk_fma_f32 v[246:247], v[78:79], v[78:79], v[246:247]
	v_pk_fma_f32 v[246:247], v[80:81], v[80:81], v[246:247]
	s_nop 0
	v_add_f32_e32 v246, v246, v247
	s_nop 1
	v_add_f32_dpp v246, v246, v246 quad_perm:[1,0,3,2] row_mask:0xf bank_mask:0xf
	s_nop 1
	v_add_f32_dpp v246, v246, v246 quad_perm:[2,3,0,1] row_mask:0xf bank_mask:0xf
	s_nop 1
	v_add_f32_dpp v246, v246, v246 row_half_mirror row_mask:0xf bank_mask:0xf
	s_nop 1
	v_add_f32_dpp v246, v246, v246 row_mirror row_mask:0xf bank_mask:0xf
	s_nop 1
	v_add_f32_dpp v246, v246, v246 row_bcast:15 row_mask:0xa bank_mask:0xf
	s_nop 1
	v_add_f32_dpp v246, v246, v246 row_bcast:31 row_mask:0xc bank_mask:0xf
	s_nop 1
	v_readlane_b32 s0, v246, 63
	s_add_i32 s21, s37, 2048
	s_lshl_b32 s21, s21, 11
	s_add_u32 s10, s16, s21
	s_addc_u32 s11, s17, 0
	v_mov_b32_e32 v248, s0
	v_fmamk_f32 v248, v248, 0x3a800000, v143
	v_rsq_f32_e32 v248, v248
	s_nop 0
	v_pk_mul_f32 v[66:67], v[66:67], v[248:249] op_sel_hi:[1,0]
	v_pk_add_f32 v[98:99], v[98:99], 1.0 op_sel_hi:[1,0]
	v_pk_mul_f32 v[66:67], v[2:3], v[66:67]
	v_pk_fma_f32 v[66:67], v[98:99], v[66:67], v[82:83]
	v_pk_mul_f32 v[68:69], v[68:69], v[248:249] op_sel_hi:[1,0]
	v_pk_add_f32 v[100:101], v[100:101], 1.0 op_sel_hi:[1,0]
	v_pk_mul_f32 v[68:69], v[4:5], v[68:69]
	v_pk_fma_f32 v[68:69], v[100:101], v[68:69], v[84:85]
	v_cvt_pk_bf16_f32 v82, v66, v67
	v_cvt_pk_bf16_f32 v83, v68, v69
	global_store_dwordx2 v245, v[82:83], s[10:11]
	v_pk_mul_f32 v[70:71], v[70:71], v[248:249] op_sel_hi:[1,0]
	v_pk_add_f32 v[102:103], v[102:103], 1.0 op_sel_hi:[1,0]
	v_pk_mul_f32 v[70:71], v[6:7], v[70:71]
	v_pk_fma_f32 v[70:71], v[102:103], v[70:71], v[86:87]
	v_pk_mul_f32 v[72:73], v[72:73], v[248:249] op_sel_hi:[1,0]
	v_pk_add_f32 v[104:105], v[104:105], 1.0 op_sel_hi:[1,0]
	v_pk_mul_f32 v[72:73], v[8:9], v[72:73]
	v_pk_fma_f32 v[72:73], v[104:105], v[72:73], v[88:89]
	v_cvt_pk_bf16_f32 v86, v70, v71
	v_cvt_pk_bf16_f32 v87, v72, v73
	global_store_dwordx2 v245, v[86:87], s[10:11] offset:512
	v_pk_mul_f32 v[74:75], v[74:75], v[248:249] op_sel_hi:[1,0]
	v_pk_add_f32 v[106:107], v[106:107], 1.0 op_sel_hi:[1,0]
	v_pk_mul_f32 v[74:75], v[10:11], v[74:75]
	v_pk_fma_f32 v[74:75], v[106:107], v[74:75], v[90:91]
	v_pk_mul_f32 v[76:77], v[76:77], v[248:249] op_sel_hi:[1,0]
	v_pk_add_f32 v[108:109], v[108:109], 1.0 op_sel_hi:[1,0]
	v_pk_mul_f32 v[76:77], v[12:13], v[76:77]
	v_pk_fma_f32 v[76:77], v[108:109], v[76:77], v[92:93]
	v_cvt_pk_bf16_f32 v90, v74, v75
	v_cvt_pk_bf16_f32 v91, v76, v77
	global_store_dwordx2 v245, v[90:91], s[10:11] offset:1024
	v_pk_mul_f32 v[78:79], v[78:79], v[248:249] op_sel_hi:[1,0]
	v_pk_add_f32 v[118:119], v[118:119], 1.0 op_sel_hi:[1,0]
	v_pk_mul_f32 v[78:79], v[14:15], v[78:79]
	v_pk_fma_f32 v[78:79], v[118:119], v[78:79], v[94:95]
	v_pk_mul_f32 v[80:81], v[80:81], v[248:249] op_sel_hi:[1,0]
	v_pk_add_f32 v[120:121], v[120:121], 1.0 op_sel_hi:[1,0]
	v_pk_mul_f32 v[80:81], v[16:17], v[80:81]
	v_pk_fma_f32 v[80:81], v[120:121], v[80:81], v[96:97]
	v_cvt_pk_bf16_f32 v94, v78, v79
	v_cvt_pk_bf16_f32 v95, v80, v81
	global_store_dwordx2 v245, v[94:95], s[10:11] offset:1536
	s_branch .Lnorm2_done

; DI void modnorm_rows(const Params& p, int l, int which  , bool from_inputs, bool skip_ctx, int w0, int wstride, int lane) {
;   const float* g = (which ? p.norm2_g : p.norm1_g) + l * DM;
;   f32x4 gg[4];
; #pragma unroll
;   for (int i = 0; i < 4; ++i) gg[i] = *(const f32x4*)(g + i * 256 + lane * 4);
;   const int nrows = skip_ctx ? 8 * NLAT : T_TOK;
;   auto rowof = [&](int i) -> int { return skip_ctx ? (i / NLAT) * TB + NCTX + (i % NLAT) : i; };
;   int i = w0;
;   if (i >= nrows) return;
;   f32x4 vn[4];
;   {
;     const int row = rowof(i); const float* src = xsrc_row(p, from_inputs, row / TB, row % TB);
; #pragma unroll
;     for (int q = 0; q < 4; ++q) vn[q] = *(const f32x4*)(src + q * 256 + lane * 4);
;   }
;   for (; i < nrows; i += wstride) {
;     const int row = rowof(i); const int b = row / TB, s = row % TB;
;     f32x4 v[4];
; #pragma unroll
;     for (int q = 0; q < 4; ++q) v[q] = vn[q];
;     if (i + wstride < nrows) {
;       const int rn = rowof(i + wstride); const float* src = xsrc_row(p, from_inputs, rn / TB, rn % TB);
; #pragma unroll
;       for (int q = 0; q < 4; ++q) vn[q] = *(const f32x4*)(src + q * 256 + lane * 4);
;     }
;     const float* mod = p.MOD + (size_t)(l * 9 + (s < NCTX ? 8 : b)) * 6144 + (which ? 3 * 1024 : 0);
;     f32x4 sh[4], sc[4];
; #pragma unroll
;     for (int q = 0; q < 4; ++q) { sh[q] = *(const f32x4*)(mod + q * 256 + lane * 4); sc[q] = *(const f32x4*)(mod + 1024 + q * 256 + lane * 4); }
.LBB0_823:
	s_or_b64 exec, exec, s[0:1]
	v_readlane_b32 s0, v252, 9
	s_nop 1
	v_add_u32_e32 v50, s0, v158
	s_movk_i32 s0, 0x4800
	v_cmp_gt_i32_e32 vcc, s0, v50
	s_and_saveexec_b64 s[2:3], vcc
	s_cbranch_execz .LBB0_852
	v_readlane_b32 s0, v252, 9
	v_lshlrev_b32_e32 v244, 4, v115
	v_lshlrev_b32_e32 v245, 3, v115
	v_add_u32_e32 v1, s0, v158
	s_nop 1
	v_readfirstlane_b32 s20, v1
	v_readlane_b32 s4, v254, 40
	v_readlane_b32 s5, v254, 41
	v_readlane_b32 s12, v254, 28
	v_readlane_b32 s13, v254, 29
	v_readlane_b32 s14, v254, 32
	v_readlane_b32 s15, v254, 33
	v_readlane_b32 s16, v253, 40
	v_readlane_b32 s17, v253, 41
	v_readlane_b32 s18, v250, 4
	v_readlane_b32 s19, v250, 5
	s_nop 3
	s_lshl_b32 s0, s49, 12
	s_add_u32 s4, s4, s0
	s_addc_u32 s5, s5, 0
	global_load_dwordx4 v[2:5], v244, s[4:5]
	global_load_dwordx4 v[6:9], v244, s[4:5] offset:1024
	global_load_dwordx4 v[10:13], v244, s[4:5] offset:2048
	global_load_dwordx4 v[14:17], v244, s[4:5] offset:3072
	s_add_i32 s0, s77, 7
	s_cmp_gt_u32 s0, 16
	s_cselect_b32 s12, s56, s12
	s_cselect_b32 s13, s57, s13
	s_cselect_b32 s14, s64, s14
	s_cselect_b32 s15, s65, s15
	s_lshr_b32 s39, s20, 5
	s_lshl_b32 s39, s39, 2
	s_and_b32 s38, s20, 3
	s_or_b32 s39, s39, s38
	s_lshr_b32 s38, s20, 2
	s_and_b32 s38, s38, 7
	s_mul_i32 s37, s38, 0x900
	s_add_i32 s37, s37, s39
	s_add_i32 s21, s37, 0
	s_mul_hi_u32 s7, s21, 0x38e38e39
	s_lshr_b32 s7, s7, 9
	s_mul_i32 s8, s7, 0x900
	s_sub_i32 s8, s21, s8
	s_lshl_b32 s9, s7, 11
	s_add_i32 s9, s9, s8
	s_add_i32 s9, s9, 0xffffff00
	s_lshl_b32 s10, s7, 8
	s_add_i32 s10, s10, s8
	s_cmpk_gt_i32 s8, 0xff
	s_cselect_b32 s9, s9, s10
	s_cselect_b32 s26, s12, s14
	s_cselect_b32 s27, s13, s15
	s_cselect_b32 s10, s7, 8
	s_lshl_b32 s9, s9, 12
	s_add_u32 s26, s26, s9
	s_addc_u32 s27, s27, 0
	s_add_i32 s10, s10, s82
	s_mul_i32 s10, s10, s24
	s_add_u32 s28, s58, s10
	s_addc_u32 s29, s59, 0
	s_add_u32 s28, s28, 0x0
	s_addc_u32 s29, s29, 0
	s_add_u32 s0, s28, 0x1000
	s_addc_u32 s1, s29, 0
	global_load_dwordx4 v[18:21], v244, s[26:27]
	global_load_dwordx4 v[22:25], v244, s[26:27] offset:1024
	global_load_dwordx4 v[26:29], v244, s[26:27] offset:2048
	global_load_dwordx4 v[30:33], v244, s[26:27] offset:3072
	global_load_dwordx4 v[34:37], v244, s[28:29]
	global_load_dwordx4 v[38:41], v244, s[28:29] offset:1024
	global_load_dwordx4 v[42:45], v244, s[28:29] offset:2048
	global_load_dwordx4 v[46:49], v244, s[28:29] offset:3072
	global_load_dwordx4 v[50:53], v244, s[0:1]
	global_load_dwordx4 v[54:57], v244, s[0:1] offset:1024
	global_load_dwordx4 v[58:61], v244, s[0:1] offset:2048
	global_load_dwordx4 v[62:65], v244, s[0:1] offset:3072
	s_add_i32 s21, s37, 256
	s_mul_hi_u32 s7, s21, 0x38e38e39
	s_lshr_b32 s7, s7, 9
	s_mul_i32 s8, s7, 0x900
	s_sub_i32 s8, s21, s8
	s_lshl_b32 s9, s7, 11
	s_add_i32 s9, s9, s8
	s_add_i32 s9, s9, 0xffffff00
	s_lshl_b32 s10, s7, 8
	s_add_i32 s10, s10, s8
	s_cmpk_gt_i32 s8, 0xff
	s_cselect_b32 s9, s9, s10
	s_cselect_b32 s26, s12, s14
	s_cselect_b32 s27, s13, s15
	s_cselect_b32 s10, s7, 8
	s_lshl_b32 s9, s9, 12
	s_add_u32 s26, s26, s9
	s_addc_u32 s27, s27, 0
	s_add_i32 s10, s10, s82
	s_mul_i32 s10, s10, s24
	s_add_u32 s28, s58, s10
	s_addc_u32 s29, s59, 0
	s_add_u32 s28, s28, 0x0
	s_addc_u32 s29, s29, 0
	s_add_u32 s0, s28, 0x1000
	s_addc_u32 s1, s29, 0
	global_load_dwordx4 v[66:69], v244, s[26:27]
	global_load_dwordx4 v[70:73], v244, s[26:27] offset:1024
	global_load_dwordx4 v[74:77], v244, s[26:27] offset:2048
	global_load_dwordx4 v[78:81], v244, s[26:27] offset:3072
	global_load_dwordx4 v[82:85], v244, s[28:29]
	global_load_dwordx4 v[86:89], v244, s[28:29] offset:1024
	global_load_dwordx4 v[90:93], v244, s[28:29] offset:2048
	global_load_dwordx4 v[94:97], v244, s[28:29] offset:3072
	global_load_dwordx4 v[98:101], v244, s[0:1]
	global_load_dwordx4 v[102:105], v244, s[0:1] offset:1024
	global_load_dwordx4 v[106:109], v244, s[0:1] offset:2048
	global_load_dwordx4 v[118:121], v244, s[0:1] offset:3072
	s_add_i32 s21, s37, 512
	s_mul_hi_u32 s7, s21, 0x38e38e39
	s_lshr_b32 s7, s7, 9
	s_mul_i32 s8, s7, 0x900
	s_sub_i32 s8, s21, s8
	s_lshl_b32 s9, s7, 11
	s_add_i32 s9, s9, s8
	s_add_i32 s9, s9, 0xffffff00
	s_lshl_b32 s10, s7, 8
	s_add_i32 s10, s10, s8
	s_cmpk_gt_i32 s8, 0xff
	s_cselect_b32 s9, s9, s10
	s_cselect_b32 s26, s12, s14
	s_cselect_b32 s27, s13, s15
	s_cselect_b32 s10, s7, 8
	s_lshl_b32 s9, s9, 12
	s_add_u32 s26, s26, s9
	s_addc_u32 s27, s27, 0
	s_add_i32 s10, s10, s82
	s_mul_i32 s10, s10, s24
	s_add_u32 s28, s58, s10
	s_addc_u32 s29, s59, 0
	s_add_u32 s28, s28, 0x0
	s_addc_u32 s29, s29, 0
	s_add_u32 s0, s28, 0x1000
	s_addc_u32 s1, s29, 0
	global_load_dwordx4 v[122:125], v244, s[26:27]
	global_load_dwordx4 v[126:129], v244, s[26:27] offset:1024
	global_load_dwordx4 v[130:133], v244, s[26:27] offset:2048
	global_load_dwordx4 v[134:137], v244, s[26:27] offset:3072
	global_load_dwordx4 v[160:163], v244, s[28:29]
	global_load_dwordx4 v[164:167], v244, s[28:29] offset:1024
	global_load_dwordx4 v[168:171], v244, s[28:29] offset:2048
	global_load_dwordx4 v[172:175], v244, s[28:29] offset:3072
	global_load_dwordx4 v[176:179], v244, s[0:1]
	global_load_dwordx4 v[180:183], v244, s[0:1] offset:1024
	global_load_dwordx4 v[184:187], v244, s[0:1] offset:2048
	global_load_dwordx4 v[188:191], v244, s[0:1] offset:3072
	s_waitcnt vmcnt(24)
; DI unsigned pk_bf16(float lo, float hi) { f32x2 v = {lo, hi}; bf16v2 b = __builtin_convertvector(v, bf16v2); return __builtin_bit_cast(unsigned, b); }
; DI float red64(float x) { for (int o = 32; o > 0; o >>= 1) x += __shfl_xor(x, o); return x; }
; DI void modnorm_rows(const Params& p, int l, int which  , bool from_inputs, bool skip_ctx, int w0, int wstride, int lane) {
;     ...
;     const int row = rowof(i); const int b = row / TB, s = row % TB;
;     f32x4 v[4];
; #pragma unroll
;     for (int q = 0; q < 4; ++q) v[q] = vn[q];
;     if (i + wstride < nrows) {
;       const int rn = rowof(i + wstride); const float* src = xsrc_row(p, from_inputs, rn / TB, rn % TB);
; #pragma unroll
;       for (int q = 0; q < 4; ++q) vn[q] = *(const f32x4*)(src + q * 256 + lane * 4);
;     }
;     const float* mod = p.MOD + (size_t)(l * 9 + (s < NCTX ? 8 : b)) * 6144 + (which ? 3 * 1024 : 0);
;     f32x4 sh[4], sc[4];
; #pragma unroll
;     for (int q = 0; q < 4; ++q) { sh[q] = *(const f32x4*)(mod + q * 256 + lane * 4); sc[q] = *(const f32x4*)(mod + 1024 + q * 256 + lane * 4); }
;     float ss = 0.f;
; #pragma unroll
;     for (int q = 0; q < 4; ++q) ss += v[q][0] * v[q][0] + v[q][1] * v[q][1] + v[q][2] * v[q][2] + v[q][3] * v[q][3];
;     ss = red64(ss);
;     const float rs = rsqrtf(ss * (1.f / 1024.f) + EPSF);
;     bf16_t* dst = p.HY + (size_t)row * DM;
; #pragma unroll
;     for (int q = 0; q < 4; ++q) {
;       float o[4];
; #pragma unroll
;       for (int j = 0; j < 4; ++j) o[j] = (v[q][j] * rs * gg[q][j]) * (1.f + sc[q][j]) + sh[q][j];
;       u32x2 w = {pk_bf16(o[0], o[1]), pk_bf16(o[2], o[3])};
;       *(u32x2*)(dst + q * 256 + lane * 4) = w;
;     }
	v_pk_mul_f32 v[246:247], v[18:19], v[18:19]
	v_pk_fma_f32 v[246:247], v[20:21], v[20:21], v[246:247]
	v_pk_fma_f32 v[246:247], v[22:23], v[22:23], v[246:247]
	v_pk_fma_f32 v[246:247], v[24:25], v[24:25], v[246:247]
	v_pk_fma_f32 v[246:247], v[26:27], v[26:27], v[246:247]
	v_pk_fma_f32 v[246:247], v[28:29], v[28:29], v[246:247]
	v_pk_fma_f32 v[246:247], v[30:31], v[30:31], v[246:247]
	v_pk_fma_f32 v[246:247], v[32:33], v[32:33], v[246:247]
	s_nop 0
	v_add_f32_e32 v246, v246, v247
	s_nop 1
	v_add_f32_dpp v246, v246, v246 quad_perm:[1,0,3,2] row_mask:0xf bank_mask:0xf
	s_nop 1
	v_add_f32_dpp v246, v246, v246 quad_perm:[2,3,0,1] row_mask:0xf bank_mask:0xf
	s_nop 1
	v_add_f32_dpp v246, v246, v246 row_half_mirror row_mask:0xf bank_mask:0xf
	s_nop 1
	v_add_f32_dpp v246, v246, v246 row_mirror row_mask:0xf bank_mask:0xf
	s_nop 1
	v_add_f32_dpp v246, v246, v246 row_bcast:15 row_mask:0xa bank_mask:0xf
	s_nop 1
	v_add_f32_dpp v246, v246, v246 row_bcast:31 row_mask:0xc bank_mask:0xf
	s_nop 1
	v_readlane_b32 s0, v246, 63
	s_add_i32 s21, s37, 0
	s_lshl_b32 s21, s21, 11
	s_add_u32 s10, s16, s21
	s_addc_u32 s11, s17, 0
	v_mov_b32_e32 v248, s0
	v_fmamk_f32 v248, v248, 0x3a800000, v143
	v_rsq_f32_e32 v248, v248
	s_nop 0
	v_pk_mul_f32 v[18:19], v[18:19], v[248:249] op_sel_hi:[1,0]
	v_pk_add_f32 v[50:51], v[50:51], 1.0 op_sel_hi:[1,0]
	v_pk_mul_f32 v[18:19], v[2:3], v[18:19]
	v_pk_fma_f32 v[18:19], v[50:51], v[18:19], v[34:35]
	v_pk_mul_f32 v[20:21], v[20:21], v[248:249] op_sel_hi:[1,0]
	v_pk_add_f32 v[52:53], v[52:53], 1.0 op_sel_hi:[1,0]
	v_pk_mul_f32 v[20:21], v[4:5], v[20:21]
	v_pk_fma_f32 v[20:21], v[52:53], v[20:21], v[36:37]
	v_cvt_pk_bf16_f32 v34, v18, v19
	v_cvt_pk_bf16_f32 v35, v20, v21
	global_store_dwordx2 v245, v[34:35], s[10:11]
	v_pk_mul_f32 v[22:23], v[22:23], v[248:249] op_sel_hi:[1,0]
	v_pk_add_f32 v[54:55], v[54:55], 1.0 op_sel_hi:[1,0]
	v_pk_mul_f32 v[22:23], v[6:7], v[22:23]
	v_pk_fma_f32 v[22:23], v[54:55], v[22:23], v[38:39]
	v_pk_mul_f32 v[24:25], v[24:25], v[248:249] op_sel_hi:[1,0]
	v_pk_add_f32 v[56:57], v[56:57], 1.0 op_sel_hi:[1,0]
	v_pk_mul_f32 v[24:25], v[8:9], v[24:25]
	v_pk_fma_f32 v[24:25], v[56:57], v[24:25], v[40:41]
	v_cvt_pk_bf16_f32 v38, v22, v23
	v_cvt_pk_bf16_f32 v39, v24, v25
	global_store_dwordx2 v245, v[38:39], s[10:11] offset:512
	v_pk_mul_f32 v[26:27], v[26:27], v[248:249] op_sel_hi:[1,0]
	v_pk_add_f32 v[58:59], v[58:59], 1.0 op_sel_hi:[1,0]
	v_pk_mul_f32 v[26:27], v[10:11], v[26:27]
	v_pk_fma_f32 v[26:27], v[58:59], v[26:27], v[42:43]
	v_pk_mul_f32 v[28:29], v[28:29], v[248:249] op_sel_hi:[1,0]
	v_pk_add_f32 v[60:61], v[60:61], 1.0 op_sel_hi:[1,0]
	v_pk_mul_f32 v[28:29], v[12:13], v[28:29]
	v_pk_fma_f32 v[28:29], v[60:61], v[28:29], v[44:45]
	v_cvt_pk_bf16_f32 v42, v26, v27
	v_cvt_pk_bf16_f32 v43, v28, v29
	global_store_dwordx2 v245, v[42:43], s[10:11] offset:1024
	v_pk_mul_f32 v[30:31], v[30:31], v[248:249] op_sel_hi:[1,0]
	v_pk_add_f32 v[62:63], v[62:63], 1.0 op_sel_hi:[1,0]
	v_pk_mul_f32 v[30:31], v[14:15], v[30:31]
	v_pk_fma_f32 v[30:31], v[62:63], v[30:31], v[46:47]
	v_pk_mul_f32 v[32:33], v[32:33], v[248:249] op_sel_hi:[1,0]
	v_pk_add_f32 v[64:65], v[64:65], 1.0 op_sel_hi:[1,0]
	v_pk_mul_f32 v[32:33], v[16:17], v[32:33]
	v_pk_fma_f32 v[32:33], v[64:65], v[32:33], v[48:49]
	v_cvt_pk_bf16_f32 v46, v30, v31
	v_cvt_pk_bf16_f32 v47, v32, v33
	global_store_dwordx2 v245, v[46:47], s[10:11] offset:1536
	s_add_i32 s21, s37, 768
	s_mul_hi_u32 s7, s21, 0x38e38e39
	s_lshr_b32 s7, s7, 9
	s_mul_i32 s8, s7, 0x900
	s_sub_i32 s8, s21, s8
	s_lshl_b32 s9, s7, 11
	s_add_i32 s9, s9, s8
	s_add_i32 s9, s9, 0xffffff00
	s_lshl_b32 s10, s7, 8
	s_add_i32 s10, s10, s8
	s_cmpk_gt_i32 s8, 0xff
	s_cselect_b32 s9, s9, s10
	s_cselect_b32 s26, s12, s14
	s_cselect_b32 s27, s13, s15
	s_cselect_b32 s10, s7, 8
	s_lshl_b32 s9, s9, 12
	s_add_u32 s26, s26, s9
	s_addc_u32 s27, s27, 0
	s_add_i32 s10, s10, s82
	s_mul_i32 s10, s10, s24
	s_add_u32 s28, s58, s10
	s_addc_u32 s29, s59, 0
	s_add_u32 s28, s28, 0x0
	s_addc_u32 s29, s29, 0
	s_add_u32 s0, s28, 0x1000
	s_addc_u32 s1, s29, 0
	global_load_dwordx4 v[18:21], v244, s[26:27]
	global_load_dwordx4 v[22:25], v244, s[26:27] offset:1024
	global_load_dwordx4 v[26:29], v244, s[26:27] offset:2048
	global_load_dwordx4 v[30:33], v244, s[26:27] offset:3072
	global_load_dwordx4 v[34:37], v244, s[28:29]
	global_load_dwordx4 v[38:41], v244, s[28:29] offset:1024
	global_load_dwordx4 v[42:45], v244, s[28:29] offset:2048
	global_load_dwordx4 v[46:49], v244, s[28:29] offset:3072
	global_load_dwordx4 v[50:53], v244, s[0:1]
	global_load_dwordx4 v[54:57], v244, s[0:1] offset:1024
	global_load_dwordx4 v[58:61], v244, s[0:1] offset:2048
	global_load_dwordx4 v[62:65], v244, s[0:1] offset:3072
	s_waitcnt vmcnt(28)
; DI unsigned pk_bf16(float lo, float hi) { f32x2 v = {lo, hi}; bf16v2 b = __builtin_convertvector(v, bf16v2); return __builtin_bit_cast(unsigned, b); }
; DI float red64(float x) { for (int o = 32; o > 0; o >>= 1) x += __shfl_xor(x, o); return x; }
; DI void modnorm_rows(const Params& p, int l, int which  , bool from_inputs, bool skip_ctx, int w0, int wstride, int lane) {
;     ...
;     const int row = rowof(i); const int b = row / TB, s = row % TB;
;     f32x4 v[4];
; #pragma unroll
;     for (int q = 0; q < 4; ++q) v[q] = vn[q];
;     if (i + wstride < nrows) {
;       const int rn = rowof(i + wstride); const float* src = xsrc_row(p, from_inputs, rn / TB, rn % TB);
; #pragma unroll
;       for (int q = 0; q < 4; ++q) vn[q] = *(const f32x4*)(src + q * 256 + lane * 4);
;     }
;     const float* mod = p.MOD + (size_t)(l * 9 + (s < NCTX ? 8 : b)) * 6144 + (which ? 3 * 1024 : 0);
;     f32x4 sh[4], sc[4];
; #pragma unroll
;     for (int q = 0; q < 4; ++q) { sh[q] = *(const f32x4*)(mod + q * 256 + lane * 4); sc[q] = *(const f32x4*)(mod + 1024 + q * 256 + lane * 4); }
;     float ss = 0.f;
; #pragma unroll
;     for (int q = 0; q < 4; ++q) ss += v[q][0] * v[q][0] + v[q][1] * v[q][1] + v[q][2] * v[q][2] + v[q][3] * v[q][3];
;     ss = red64(ss);
;     const float rs = rsqrtf(ss * (1.f / 1024.f) + EPSF);
;     bf16_t* dst = p.HY + (size_t)row * DM;
; #pragma unroll
;     for (int q = 0; q < 4; ++q) {
;       float o[4];
; #pragma unroll
;       for (int j = 0; j < 4; ++j) o[j] = (v[q][j] * rs * gg[q][j]) * (1.f + sc[q][j]) + sh[q][j];
;       u32x2 w = {pk_bf16(o[0], o[1]), pk_bf16(o[2], o[3])};
;       *(u32x2*)(dst + q * 256 + lane * 4) = w;
;     }
	v_pk_mul_f32 v[246:247], v[66:67], v[66:67]
	v_pk_fma_f32 v[246:247], v[68:69], v[68:69], v[246:247]
	v_pk_fma_f32 v[246:247], v[70:71], v[70:71], v[246:247]
	v_pk_fma_f32 v[246:247], v[72:73], v[72:73], v[246:247]
	v_pk_fma_f32 v[246:247], v[74:75], v[74:75], v[246:247]
	v_pk_fma_f32 v[246:247], v[76:77], v[76:77], v[246:247]
	v_pk_fma_f32 v[246:247], v[78:79], v[78:79], v[246:247]
	v_pk_fma_f32 v[246:247], v[80:81], v[80:81], v[246:247]
	s_nop 0
	v_add_f32_e32 v246, v246, v247
	s_nop 1
	v_add_f32_dpp v246, v246, v246 quad_perm:[1,0,3,2] row_mask:0xf bank_mask:0xf
	s_nop 1
	v_add_f32_dpp v246, v246, v246 quad_perm:[2,3,0,1] row_mask:0xf bank_mask:0xf
	s_nop 1
	v_add_f32_dpp v246, v246, v246 row_half_mirror row_mask:0xf bank_mask:0xf
	s_nop 1
	v_add_f32_dpp v246, v246, v246 row_mirror row_mask:0xf bank_mask:0xf
	s_nop 1
	v_add_f32_dpp v246, v246, v246 row_bcast:15 row_mask:0xa bank_mask:0xf
	s_nop 1
	v_add_f32_dpp v246, v246, v246 row_bcast:31 row_mask:0xc bank_mask:0xf
	s_nop 1
	v_readlane_b32 s0, v246, 63
	s_add_i32 s21, s37, 256
	s_lshl_b32 s21, s21, 11
	s_add_u32 s10, s16, s21
	s_addc_u32 s11, s17, 0
	v_mov_b32_e32 v248, s0
	v_fmamk_f32 v248, v248, 0x3a800000, v143
	v_rsq_f32_e32 v248, v248
	s_nop 0
	v_pk_mul_f32 v[66:67], v[66:67], v[248:249] op_sel_hi:[1,0]
	v_pk_add_f32 v[98:99], v[98:99], 1.0 op_sel_hi:[1,0]
	v_pk_mul_f32 v[66:67], v[2:3], v[66:67]
	v_pk_fma_f32 v[66:67], v[98:99], v[66:67], v[82:83]
	v_pk_mul_f32 v[68:69], v[68:69], v[248:249] op_sel_hi:[1,0]
	v_pk_add_f32 v[100:101], v[100:101], 1.0 op_sel_hi:[1,0]
	v_pk_mul_f32 v[68:69], v[4:5], v[68:69]
	v_pk_fma_f32 v[68:69], v[100:101], v[68:69], v[84:85]
	v_cvt_pk_bf16_f32 v82, v66, v67
	v_cvt_pk_bf16_f32 v83, v68, v69
	global_store_dwordx2 v245, v[82:83], s[10:11]
	v_pk_mul_f32 v[70:71], v[70:71], v[248:249] op_sel_hi:[1,0]
	v_pk_add_f32 v[102:103], v[102:103], 1.0 op_sel_hi:[1,0]
	v_pk_mul_f32 v[70:71], v[6:7], v[70:71]
	v_pk_fma_f32 v[70:71], v[102:103], v[70:71], v[86:87]
	v_pk_mul_f32 v[72:73], v[72:73], v[248:249] op_sel_hi:[1,0]
	v_pk_add_f32 v[104:105], v[104:105], 1.0 op_sel_hi:[1,0]
	v_pk_mul_f32 v[72:73], v[8:9], v[72:73]
	v_pk_fma_f32 v[72:73], v[104:105], v[72:73], v[88:89]
	v_cvt_pk_bf16_f32 v86, v70, v71
	v_cvt_pk_bf16_f32 v87, v72, v73
	global_store_dwordx2 v245, v[86:87], s[10:11] offset:512
	v_pk_mul_f32 v[74:75], v[74:75], v[248:249] op_sel_hi:[1,0]
	v_pk_add_f32 v[106:107], v[106:107], 1.0 op_sel_hi:[1,0]
	v_pk_mul_f32 v[74:75], v[10:11], v[74:75]
	v_pk_fma_f32 v[74:75], v[106:107], v[74:75], v[90:91]
	v_pk_mul_f32 v[76:77], v[76:77], v[248:249] op_sel_hi:[1,0]
	v_pk_add_f32 v[108:109], v[108:109], 1.0 op_sel_hi:[1,0]
	v_pk_mul_f32 v[76:77], v[12:13], v[76:77]
	v_pk_fma_f32 v[76:77], v[108:109], v[76:77], v[92:93]
	v_cvt_pk_bf16_f32 v90, v74, v75
	v_cvt_pk_bf16_f32 v91, v76, v77
	global_store_dwordx2 v245, v[90:91], s[10:11] offset:1024
	v_pk_mul_f32 v[78:79], v[78:79], v[248:249] op_sel_hi:[1,0]
	v_pk_add_f32 v[118:119], v[118:119], 1.0 op_sel_hi:[1,0]
	v_pk_mul_f32 v[78:79], v[14:15], v[78:79]
	v_pk_fma_f32 v[78:79], v[118:119], v[78:79], v[94:95]
	v_pk_mul_f32 v[80:81], v[80:81], v[248:249] op_sel_hi:[1,0]
	v_pk_add_f32 v[120:121], v[120:121], 1.0 op_sel_hi:[1,0]
	v_pk_mul_f32 v[80:81], v[16:17], v[80:81]
	v_pk_fma_f32 v[80:81], v[120:121], v[80:81], v[96:97]
	v_cvt_pk_bf16_f32 v94, v78, v79
	v_cvt_pk_bf16_f32 v95, v80, v81
	global_store_dwordx2 v245, v[94:95], s[10:11] offset:1536
	s_add_i32 s21, s37, 1024
	s_mul_hi_u32 s7, s21, 0x38e38e39
	s_lshr_b32 s7, s7, 9
	s_mul_i32 s8, s7, 0x900
	s_sub_i32 s8, s21, s8
	s_lshl_b32 s9, s7, 11
	s_add_i32 s9, s9, s8
	s_add_i32 s9, s9, 0xffffff00
	s_lshl_b32 s10, s7, 8
	s_add_i32 s10, s10, s8
	s_cmpk_gt_i32 s8, 0xff
	s_cselect_b32 s9, s9, s10
	s_cselect_b32 s26, s12, s14
	s_cselect_b32 s27, s13, s15
	s_cselect_b32 s10, s7, 8
	s_lshl_b32 s9, s9, 12
	s_add_u32 s26, s26, s9
	s_addc_u32 s27, s27, 0
	s_add_i32 s10, s10, s82
	s_mul_i32 s10, s10, s24
	s_add_u32 s28, s58, s10
	s_addc_u32 s29, s59, 0
	s_add_u32 s28, s28, 0x0
	s_addc_u32 s29, s29, 0
	s_add_u32 s0, s28, 0x1000
	s_addc_u32 s1, s29, 0
	global_load_dwordx4 v[66:69], v244, s[26:27]
	global_load_dwordx4 v[70:73], v244, s[26:27] offset:1024
	global_load_dwordx4 v[74:77], v244, s[26:27] offset:2048
	global_load_dwordx4 v[78:81], v244, s[26:27] offset:3072
	global_load_dwordx4 v[82:85], v244, s[28:29]
	global_load_dwordx4 v[86:89], v244, s[28:29] offset:1024
	global_load_dwordx4 v[90:93], v244, s[28:29] offset:2048
	global_load_dwordx4 v[94:97], v244, s[28:29] offset:3072
	global_load_dwordx4 v[98:101], v244, s[0:1]
	global_load_dwordx4 v[102:105], v244, s[0:1] offset:1024
	global_load_dwordx4 v[106:109], v244, s[0:1] offset:2048
	global_load_dwordx4 v[118:121], v244, s[0:1] offset:3072
	s_waitcnt vmcnt(32)
; DI unsigned pk_bf16(float lo, float hi) { f32x2 v = {lo, hi}; bf16v2 b = __builtin_convertvector(v, bf16v2); return __builtin_bit_cast(unsigned, b); }
; DI float red64(float x) { for (int o = 32; o > 0; o >>= 1) x += __shfl_xor(x, o); return x; }
; DI void modnorm_rows(const Params& p, int l, int which  , bool from_inputs, bool skip_ctx, int w0, int wstride, int lane) {
;     ...
;     const int row = rowof(i); const int b = row / TB, s = row % TB;
;     f32x4 v[4];
; #pragma unroll
;     for (int q = 0; q < 4; ++q) v[q] = vn[q];
;     if (i + wstride < nrows) {
;       const int rn = rowof(i + wstride); const float* src = xsrc_row(p, from_inputs, rn / TB, rn % TB);
; #pragma unroll
;       for (int q = 0; q < 4; ++q) vn[q] = *(const f32x4*)(src + q * 256 + lane * 4);
;     }
;     const float* mod = p.MOD + (size_t)(l * 9 + (s < NCTX ? 8 : b)) * 6144 + (which ? 3 * 1024 : 0);
;     f32x4 sh[4], sc[4];
; #pragma unroll
;     for (int q = 0; q < 4; ++q) { sh[q] = *(const f32x4*)(mod + q * 256 + lane * 4); sc[q] = *(const f32x4*)(mod + 1024 + q * 256 + lane * 4); }
;     float ss = 0.f;
; #pragma unroll
;     for (int q = 0; q < 4; ++q) ss += v[q][0] * v[q][0] + v[q][1] * v[q][1] + v[q][2] * v[q][2] + v[q][3] * v[q][3];
;     ss = red64(ss);
;     const float rs = rsqrtf(ss * (1.f / 1024.f) + EPSF);
;     bf16_t* dst = p.HY + (size_t)row * DM;
; #pragma unroll
;     for (int q = 0; q < 4; ++q) {
;       float o[4];
; #pragma unroll
;       for (int j = 0; j < 4; ++j) o[j] = (v[q][j] * rs * gg[q][j]) * (1.f + sc[q][j]) + sh[q][j];
;       u32x2 w = {pk_bf16(o[0], o[1]), pk_bf16(o[2], o[3])};
;       *(u32x2*)(dst + q * 256 + lane * 4) = w;
;     }
	v_pk_mul_f32 v[246:247], v[122:123], v[122:123]
	v_pk_fma_f32 v[246:247], v[124:125], v[124:125], v[246:247]
	v_pk_fma_f32 v[246:247], v[126:127], v[126:127], v[246:247]
	v_pk_fma_f32 v[246:247], v[128:129], v[128:129], v[246:247]
	v_pk_fma_f32 v[246:247], v[130:131], v[130:131], v[246:247]
	v_pk_fma_f32 v[246:247], v[132:133], v[132:133], v[246:247]
	v_pk_fma_f32 v[246:247], v[134:135], v[134:135], v[246:247]
	v_pk_fma_f32 v[246:247], v[136:137], v[136:137], v[246:247]
	s_nop 0
	v_add_f32_e32 v246, v246, v247
	s_nop 1
	v_add_f32_dpp v246, v246, v246 quad_perm:[1,0,3,2] row_mask:0xf bank_mask:0xf
	s_nop 1
	v_add_f32_dpp v246, v246, v246 quad_perm:[2,3,0,1] row_mask:0xf bank_mask:0xf
	s_nop 1
	v_add_f32_dpp v246, v246, v246 row_half_mirror row_mask:0xf bank_mask:0xf
	s_nop 1
	v_add_f32_dpp v246, v246, v246 row_mirror row_mask:0xf bank_mask:0xf
	s_nop 1
	v_add_f32_dpp v246, v246, v246 row_bcast:15 row_mask:0xa bank_mask:0xf
	s_nop 1
	v_add_f32_dpp v246, v246, v246 row_bcast:31 row_mask:0xc bank_mask:0xf
	s_nop 1
	v_readlane_b32 s0, v246, 63
	s_add_i32 s21, s37, 512
	s_lshl_b32 s21, s21, 11
	s_add_u32 s10, s16, s21
	s_addc_u32 s11, s17, 0
	v_mov_b32_e32 v248, s0
	v_fmamk_f32 v248, v248, 0x3a800000, v143
	v_rsq_f32_e32 v248, v248
	s_nop 0
	v_pk_mul_f32 v[122:123], v[122:123], v[248:249] op_sel_hi:[1,0]
	v_pk_add_f32 v[176:177], v[176:177], 1.0 op_sel_hi:[1,0]
	v_pk_mul_f32 v[122:123], v[2:3], v[122:123]
	v_pk_fma_f32 v[122:123], v[176:177], v[122:123], v[160:161]
	v_pk_mul_f32 v[124:125], v[124:125], v[248:249] op_sel_hi:[1,0]
	v_pk_add_f32 v[178:179], v[178:179], 1.0 op_sel_hi:[1,0]
	v_pk_mul_f32 v[124:125], v[4:5], v[124:125]
	v_pk_fma_f32 v[124:125], v[178:179], v[124:125], v[162:163]
	v_cvt_pk_bf16_f32 v160, v122, v123
	v_cvt_pk_bf16_f32 v161, v124, v125
	global_store_dwordx2 v245, v[160:161], s[10:11]
	v_pk_mul_f32 v[126:127], v[126:127], v[248:249] op_sel_hi:[1,0]
	v_pk_add_f32 v[180:181], v[180:181], 1.0 op_sel_hi:[1,0]
	v_pk_mul_f32 v[126:127], v[6:7], v[126:127]
	v_pk_fma_f32 v[126:127], v[180:181], v[126:127], v[164:165]
	v_pk_mul_f32 v[128:129], v[128:129], v[248:249] op_sel_hi:[1,0]
	v_pk_add_f32 v[182:183], v[182:183], 1.0 op_sel_hi:[1,0]
	v_pk_mul_f32 v[128:129], v[8:9], v[128:129]
	v_pk_fma_f32 v[128:129], v[182:183], v[128:129], v[166:167]
	v_cvt_pk_bf16_f32 v164, v126, v127
	v_cvt_pk_bf16_f32 v165, v128, v129
	global_store_dwordx2 v245, v[164:165], s[10:11] offset:512
	v_pk_mul_f32 v[130:131], v[130:131], v[248:249] op_sel_hi:[1,0]
	v_pk_add_f32 v[184:185], v[184:185], 1.0 op_sel_hi:[1,0]
	v_pk_mul_f32 v[130:131], v[10:11], v[130:131]
	v_pk_fma_f32 v[130:131], v[184:185], v[130:131], v[168:169]
	v_pk_mul_f32 v[132:133], v[132:133], v[248:249] op_sel_hi:[1,0]
	v_pk_add_f32 v[186:187], v[186:187], 1.0 op_sel_hi:[1,0]
	v_pk_mul_f32 v[132:133], v[12:13], v[132:133]
	v_pk_fma_f32 v[132:133], v[186:187], v[132:133], v[170:171]
	v_cvt_pk_bf16_f32 v168, v130, v131
	v_cvt_pk_bf16_f32 v169, v132, v133
	global_store_dwordx2 v245, v[168:169], s[10:11] offset:1024
	v_pk_mul_f32 v[134:135], v[134:135], v[248:249] op_sel_hi:[1,0]
	v_pk_add_f32 v[188:189], v[188:189], 1.0 op_sel_hi:[1,0]
	v_pk_mul_f32 v[134:135], v[14:15], v[134:135]
	v_pk_fma_f32 v[134:135], v[188:189], v[134:135], v[172:173]
	v_pk_mul_f32 v[136:137], v[136:137], v[248:249] op_sel_hi:[1,0]
	v_pk_add_f32 v[190:191], v[190:191], 1.0 op_sel_hi:[1,0]
	v_pk_mul_f32 v[136:137], v[16:17], v[136:137]
	v_pk_fma_f32 v[136:137], v[190:191], v[136:137], v[174:175]
	v_cvt_pk_bf16_f32 v172, v134, v135
	v_cvt_pk_bf16_f32 v173, v136, v137
	global_store_dwordx2 v245, v[172:173], s[10:11] offset:1536
	s_add_i32 s21, s37, 1280
	s_mul_hi_u32 s7, s21, 0x38e38e39
	s_lshr_b32 s7, s7, 9
	s_mul_i32 s8, s7, 0x900
	s_sub_i32 s8, s21, s8
	s_lshl_b32 s9, s7, 11
	s_add_i32 s9, s9, s8
	s_add_i32 s9, s9, 0xffffff00
	s_lshl_b32 s10, s7, 8
	s_add_i32 s10, s10, s8
	s_cmpk_gt_i32 s8, 0xff
	s_cselect_b32 s9, s9, s10
	s_cselect_b32 s26, s12, s14
	s_cselect_b32 s27, s13, s15
	s_cselect_b32 s10, s7, 8
	s_lshl_b32 s9, s9, 12
	s_add_u32 s26, s26, s9
	s_addc_u32 s27, s27, 0
	s_add_i32 s10, s10, s82
	s_mul_i32 s10, s10, s24
	s_add_u32 s28, s58, s10
	s_addc_u32 s29, s59, 0
	s_add_u32 s28, s28, 0x0
	s_addc_u32 s29, s29, 0
	s_add_u32 s0, s28, 0x1000
	s_addc_u32 s1, s29, 0
	global_load_dwordx4 v[122:125], v244, s[26:27]
	global_load_dwordx4 v[126:129], v244, s[26:27] offset:1024
	global_load_dwordx4 v[130:133], v244, s[26:27] offset:2048
	global_load_dwordx4 v[134:137], v244, s[26:27] offset:3072
	global_load_dwordx4 v[160:163], v244, s[28:29]
	global_load_dwordx4 v[164:167], v244, s[28:29] offset:1024
	global_load_dwordx4 v[168:171], v244, s[28:29] offset:2048
	global_load_dwordx4 v[172:175], v244, s[28:29] offset:3072
	global_load_dwordx4 v[176:179], v244, s[0:1]
	global_load_dwordx4 v[180:183], v244, s[0:1] offset:1024
	global_load_dwordx4 v[184:187], v244, s[0:1] offset:2048
	global_load_dwordx4 v[188:191], v244, s[0:1] offset:3072
	s_waitcnt vmcnt(32)
; DI unsigned pk_bf16(float lo, float hi) { f32x2 v = {lo, hi}; bf16v2 b = __builtin_convertvector(v, bf16v2); return __builtin_bit_cast(unsigned, b); }
; DI float red64(float x) { for (int o = 32; o > 0; o >>= 1) x += __shfl_xor(x, o); return x; }
; DI void modnorm_rows(const Params& p, int l, int which  , bool from_inputs, bool skip_ctx, int w0, int wstride, int lane) {
;     ...
;   for (; i < nrows; i += wstride) {
;     const int row = rowof(i); const int b = row / TB, s = row % TB;
;     f32x4 v[4];
; #pragma unroll
;     for (int q = 0; q < 4; ++q) v[q] = vn[q];
;     if (i + wstride < nrows) {
;       const int rn = rowof(i + wstride); const float* src = xsrc_row(p, from_inputs, rn / TB, rn % TB);
; #pragma unroll
;       for (int q = 0; q < 4; ++q) vn[q] = *(const f32x4*)(src + q * 256 + lane * 4);
;     }
;     const float* mod = p.MOD + (size_t)(l * 9 + (s < NCTX ? 8 : b)) * 6144 + (which ? 3 * 1024 : 0);
;     f32x4 sh[4], sc[4];
; #pragma unroll
;     for (int q = 0; q < 4; ++q) { sh[q] = *(const f32x4*)(mod + q * 256 + lane * 4); sc[q] = *(const f32x4*)(mod + 1024 + q * 256 + lane * 4); }
;     float ss = 0.f;
; #pragma unroll
;     for (int q = 0; q < 4; ++q) ss += v[q][0] * v[q][0] + v[q][1] * v[q][1] + v[q][2] * v[q][2] + v[q][3] * v[q][3];
;     ss = red64(ss);
;     const float rs = rsqrtf(ss * (1.f / 1024.f) + EPSF);
;     bf16_t* dst = p.HY + (size_t)row * DM;
; #pragma unroll
;     for (int q = 0; q < 4; ++q) {
;       float o[4];
; #pragma unroll
;       for (int j = 0; j < 4; ++j) o[j] = (v[q][j] * rs * gg[q][j]) * (1.f + sc[q][j]) + sh[q][j];
;       u32x2 w = {pk_bf16(o[0], o[1]), pk_bf16(o[2], o[3])};
;       *(u32x2*)(dst + q * 256 + lane * 4) = w;
;     }
;   }
	v_pk_mul_f32 v[246:247], v[18:19], v[18:19]
	v_pk_fma_f32 v[246:247], v[20:21], v[20:21], v[246:247]
	v_pk_fma_f32 v[246:247], v[22:23], v[22:23], v[246:247]
	v_pk_fma_f32 v[246:247], v[24:25], v[24:25], v[246:247]
	v_pk_fma_f32 v[246:247], v[26:27], v[26:27], v[246:247]
	v_pk_fma_f32 v[246:247], v[28:29], v[28:29], v[246:247]
	v_pk_fma_f32 v[246:247], v[30:31], v[30:31], v[246:247]
	v_pk_fma_f32 v[246:247], v[32:33], v[32:33], v[246:247]
	s_nop 0
	v_add_f32_e32 v246, v246, v247
	s_nop 1
	v_add_f32_dpp v246, v246, v246 quad_perm:[1,0,3,2] row_mask:0xf bank_mask:0xf
	s_nop 1
	v_add_f32_dpp v246, v246, v246 quad_perm:[2,3,0,1] row_mask:0xf bank_mask:0xf
	s_nop 1
	v_add_f32_dpp v246, v246, v246 row_half_mirror row_mask:0xf bank_mask:0xf
	s_nop 1
	v_add_f32_dpp v246, v246, v246 row_mirror row_mask:0xf bank_mask:0xf
	s_nop 1
	v_add_f32_dpp v246, v246, v246 row_bcast:15 row_mask:0xa bank_mask:0xf
	s_nop 1
	v_add_f32_dpp v246, v246, v246 row_bcast:31 row_mask:0xc bank_mask:0xf
	s_nop 1
	v_readlane_b32 s0, v246, 63
	s_add_i32 s21, s37, 768
	s_lshl_b32 s21, s21, 11
	s_add_u32 s10, s16, s21
	s_addc_u32 s11, s17, 0
	v_mov_b32_e32 v248, s0
	v_fmamk_f32 v248, v248, 0x3a800000, v143
	v_rsq_f32_e32 v248, v248
	s_nop 0
	v_pk_mul_f32 v[18:19], v[18:19], v[248:249] op_sel_hi:[1,0]
	v_pk_add_f32 v[50:51], v[50:51], 1.0 op_sel_hi:[1,0]
	v_pk_mul_f32 v[18:19], v[2:3], v[18:19]
	v_pk_fma_f32 v[18:19], v[50:51], v[18:19], v[34:35]
	v_pk_mul_f32 v[20:21], v[20:21], v[248:249] op_sel_hi:[1,0]
	v_pk_add_f32 v[52:53], v[52:53], 1.0 op_sel_hi:[1,0]
	v_pk_mul_f32 v[20:21], v[4:5], v[20:21]
	v_pk_fma_f32 v[20:21], v[52:53], v[20:21], v[36:37]
	v_cvt_pk_bf16_f32 v34, v18, v19
	v_cvt_pk_bf16_f32 v35, v20, v21
	global_store_dwordx2 v245, v[34:35], s[10:11]
	v_pk_mul_f32 v[22:23], v[22:23], v[248:249] op_sel_hi:[1,0]
	v_pk_add_f32 v[54:55], v[54:55], 1.0 op_sel_hi:[1,0]
	v_pk_mul_f32 v[22:23], v[6:7], v[22:23]
	v_pk_fma_f32 v[22:23], v[54:55], v[22:23], v[38:39]
	v_pk_mul_f32 v[24:25], v[24:25], v[248:249] op_sel_hi:[1,0]
	v_pk_add_f32 v[56:57], v[56:57], 1.0 op_sel_hi:[1,0]
	v_pk_mul_f32 v[24:25], v[8:9], v[24:25]
	v_pk_fma_f32 v[24:25], v[56:57], v[24:25], v[40:41]
	v_cvt_pk_bf16_f32 v38, v22, v23
	v_cvt_pk_bf16_f32 v39, v24, v25
	global_store_dwordx2 v245, v[38:39], s[10:11] offset:512
	v_pk_mul_f32 v[26:27], v[26:27], v[248:249] op_sel_hi:[1,0]
	v_pk_add_f32 v[58:59], v[58:59], 1.0 op_sel_hi:[1,0]
	v_pk_mul_f32 v[26:27], v[10:11], v[26:27]
	v_pk_fma_f32 v[26:27], v[58:59], v[26:27], v[42:43]
	v_pk_mul_f32 v[28:29], v[28:29], v[248:249] op_sel_hi:[1,0]
	v_pk_add_f32 v[60:61], v[60:61], 1.0 op_sel_hi:[1,0]
	v_pk_mul_f32 v[28:29], v[12:13], v[28:29]
	v_pk_fma_f32 v[28:29], v[60:61], v[28:29], v[44:45]
	v_cvt_pk_bf16_f32 v42, v26, v27
	v_cvt_pk_bf16_f32 v43, v28, v29
	global_store_dwordx2 v245, v[42:43], s[10:11] offset:1024
	v_pk_mul_f32 v[30:31], v[30:31], v[248:249] op_sel_hi:[1,0]
	v_pk_add_f32 v[62:63], v[62:63], 1.0 op_sel_hi:[1,0]
	v_pk_mul_f32 v[30:31], v[14:15], v[30:31]
	v_pk_fma_f32 v[30:31], v[62:63], v[30:31], v[46:47]
	v_pk_mul_f32 v[32:33], v[32:33], v[248:249] op_sel_hi:[1,0]
	v_pk_add_f32 v[64:65], v[64:65], 1.0 op_sel_hi:[1,0]
	v_pk_mul_f32 v[32:33], v[16:17], v[32:33]
	v_pk_fma_f32 v[32:33], v[64:65], v[32:33], v[48:49]
	v_cvt_pk_bf16_f32 v46, v30, v31
	v_cvt_pk_bf16_f32 v47, v32, v33
	global_store_dwordx2 v245, v[46:47], s[10:11] offset:1536
	s_add_i32 s21, s37, 1536
	s_mul_hi_u32 s7, s21, 0x38e38e39
	s_lshr_b32 s7, s7, 9
	s_mul_i32 s8, s7, 0x900
	s_sub_i32 s8, s21, s8
	s_lshl_b32 s9, s7, 11
	s_add_i32 s9, s9, s8
	s_add_i32 s9, s9, 0xffffff00
	s_lshl_b32 s10, s7, 8
	s_add_i32 s10, s10, s8
	s_cmpk_gt_i32 s8, 0xff
	s_cselect_b32 s9, s9, s10
	s_cselect_b32 s26, s12, s14
	s_cselect_b32 s27, s13, s15
	s_cselect_b32 s10, s7, 8
	s_lshl_b32 s9, s9, 12
	s_add_u32 s26, s26, s9
	s_addc_u32 s27, s27, 0
	s_add_i32 s10, s10, s82
	s_mul_i32 s10, s10, s24
	s_add_u32 s28, s58, s10
	s_addc_u32 s29, s59, 0
	s_add_u32 s28, s28, 0x0
	s_addc_u32 s29, s29, 0
	s_add_u32 s0, s28, 0x1000
	s_addc_u32 s1, s29, 0
	global_load_dwordx4 v[18:21], v244, s[26:27]
	global_load_dwordx4 v[22:25], v244, s[26:27] offset:1024
	global_load_dwordx4 v[26:29], v244, s[26:27] offset:2048
	global_load_dwordx4 v[30:33], v244, s[26:27] offset:3072
	global_load_dwordx4 v[34:37], v244, s[28:29]
	global_load_dwordx4 v[38:41], v244, s[28:29] offset:1024
	global_load_dwordx4 v[42:45], v244, s[28:29] offset:2048
	global_load_dwordx4 v[46:49], v244, s[28:29] offset:3072
	global_load_dwordx4 v[50:53], v244, s[0:1]
	global_load_dwordx4 v[54:57], v244, s[0:1] offset:1024
	global_load_dwordx4 v[58:61], v244, s[0:1] offset:2048
	global_load_dwordx4 v[62:65], v244, s[0:1] offset:3072
	s_waitcnt vmcnt(32)
; DI unsigned pk_bf16(float lo, float hi) { f32x2 v = {lo, hi}; bf16v2 b = __builtin_convertvector(v, bf16v2); return __builtin_bit_cast(unsigned, b); }
; DI float red64(float x) { for (int o = 32; o > 0; o >>= 1) x += __shfl_xor(x, o); return x; }
; DI void modnorm_rows(const Params& p, int l, int which  , bool from_inputs, bool skip_ctx, int w0, int wstride, int lane) {
;     ...
;   for (; i < nrows; i += wstride) {
;     const int row = rowof(i); const int b = row / TB, s = row % TB;
;     f32x4 v[4];
; #pragma unroll
;     for (int q = 0; q < 4; ++q) v[q] = vn[q];
;     if (i + wstride < nrows) {
;       const int rn = rowof(i + wstride); const float* src = xsrc_row(p, from_inputs, rn / TB, rn % TB);
; #pragma unroll
;       for (int q = 0; q < 4; ++q) vn[q] = *(const f32x4*)(src + q * 256 + lane * 4);
;     }
;     const float* mod = p.MOD + (size_t)(l * 9 + (s < NCTX ? 8 : b)) * 6144 + (which ? 3 * 1024 : 0);
;     f32x4 sh[4], sc[4];
; #pragma unroll
;     for (int q = 0; q < 4; ++q) { sh[q] = *(const f32x4*)(mod + q * 256 + lane * 4); sc[q] = *(const f32x4*)(mod + 1024 + q * 256 + lane * 4); }
;     float ss = 0.f;
; #pragma unroll
;     for (int q = 0; q < 4; ++q) ss += v[q][0] * v[q][0] + v[q][1] * v[q][1] + v[q][2] * v[q][2] + v[q][3] * v[q][3];
;     ss = red64(ss);
;     const float rs = rsqrtf(ss * (1.f / 1024.f) + EPSF);
;     bf16_t* dst = p.HY + (size_t)row * DM;
; #pragma unroll
;     for (int q = 0; q < 4; ++q) {
;       float o[4];
; #pragma unroll
;       for (int j = 0; j < 4; ++j) o[j] = (v[q][j] * rs * gg[q][j]) * (1.f + sc[q][j]) + sh[q][j];
;       u32x2 w = {pk_bf16(o[0], o[1]), pk_bf16(o[2], o[3])};
;       *(u32x2*)(dst + q * 256 + lane * 4) = w;
;     }
;   }
	v_pk_mul_f32 v[246:247], v[66:67], v[66:67]
	v_pk_fma_f32 v[246:247], v[68:69], v[68:69], v[246:247]
	v_pk_fma_f32 v[246:247], v[70:71], v[70:71], v[246:247]
	v_pk_fma_f32 v[246:247], v[72:73], v[72:73], v[246:247]
	v_pk_fma_f32 v[246:247], v[74:75], v[74:75], v[246:247]
	v_pk_fma_f32 v[246:247], v[76:77], v[76:77], v[246:247]
	v_pk_fma_f32 v[246:247], v[78:79], v[78:79], v[246:247]
	v_pk_fma_f32 v[246:247], v[80:81], v[80:81], v[246:247]
	s_nop 0
	v_add_f32_e32 v246, v246, v247
	s_nop 1
	v_add_f32_dpp v246, v246, v246 quad_perm:[1,0,3,2] row_mask:0xf bank_mask:0xf
	s_nop 1
	v_add_f32_dpp v246, v246, v246 quad_perm:[2,3,0,1] row_mask:0xf bank_mask:0xf
	s_nop 1
	v_add_f32_dpp v246, v246, v246 row_half_mirror row_mask:0xf bank_mask:0xf
	s_nop 1
	v_add_f32_dpp v246, v246, v246 row_mirror row_mask:0xf bank_mask:0xf
	s_nop 1
	v_add_f32_dpp v246, v246, v246 row_bcast:15 row_mask:0xa bank_mask:0xf
	s_nop 1
	v_add_f32_dpp v246, v246, v246 row_bcast:31 row_mask:0xc bank_mask:0xf
	s_nop 1
	v_readlane_b32 s0, v246, 63
	s_add_i32 s21, s37, 1024
	s_lshl_b32 s21, s21, 11
	s_add_u32 s10, s16, s21
	s_addc_u32 s11, s17, 0
	v_mov_b32_e32 v248, s0
	v_fmamk_f32 v248, v248, 0x3a800000, v143
	v_rsq_f32_e32 v248, v248
	s_nop 0
	v_pk_mul_f32 v[66:67], v[66:67], v[248:249] op_sel_hi:[1,0]
	v_pk_add_f32 v[98:99], v[98:99], 1.0 op_sel_hi:[1,0]
	v_pk_mul_f32 v[66:67], v[2:3], v[66:67]
	v_pk_fma_f32 v[66:67], v[98:99], v[66:67], v[82:83]
	v_pk_mul_f32 v[68:69], v[68:69], v[248:249] op_sel_hi:[1,0]
	v_pk_add_f32 v[100:101], v[100:101], 1.0 op_sel_hi:[1,0]
	v_pk_mul_f32 v[68:69], v[4:5], v[68:69]
	v_pk_fma_f32 v[68:69], v[100:101], v[68:69], v[84:85]
	v_cvt_pk_bf16_f32 v82, v66, v67
	v_cvt_pk_bf16_f32 v83, v68, v69
	global_store_dwordx2 v245, v[82:83], s[10:11]
	v_pk_mul_f32 v[70:71], v[70:71], v[248:249] op_sel_hi:[1,0]
	v_pk_add_f32 v[102:103], v[102:103], 1.0 op_sel_hi:[1,0]
	v_pk_mul_f32 v[70:71], v[6:7], v[70:71]
	v_pk_fma_f32 v[70:71], v[102:103], v[70:71], v[86:87]
	v_pk_mul_f32 v[72:73], v[72:73], v[248:249] op_sel_hi:[1,0]
	v_pk_add_f32 v[104:105], v[104:105], 1.0 op_sel_hi:[1,0]
	v_pk_mul_f32 v[72:73], v[8:9], v[72:73]
	v_pk_fma_f32 v[72:73], v[104:105], v[72:73], v[88:89]
	v_cvt_pk_bf16_f32 v86, v70, v71
	v_cvt_pk_bf16_f32 v87, v72, v73
	global_store_dwordx2 v245, v[86:87], s[10:11] offset:512
	v_pk_mul_f32 v[74:75], v[74:75], v[248:249] op_sel_hi:[1,0]
	v_pk_add_f32 v[106:107], v[106:107], 1.0 op_sel_hi:[1,0]
	v_pk_mul_f32 v[74:75], v[10:11], v[74:75]
	v_pk_fma_f32 v[74:75], v[106:107], v[74:75], v[90:91]
	v_pk_mul_f32 v[76:77], v[76:77], v[248:249] op_sel_hi:[1,0]
	v_pk_add_f32 v[108:109], v[108:109], 1.0 op_sel_hi:[1,0]
	v_pk_mul_f32 v[76:77], v[12:13], v[76:77]
	v_pk_fma_f32 v[76:77], v[108:109], v[76:77], v[92:93]
	v_cvt_pk_bf16_f32 v90, v74, v75
	v_cvt_pk_bf16_f32 v91, v76, v77
	global_store_dwordx2 v245, v[90:91], s[10:11] offset:1024
	v_pk_mul_f32 v[78:79], v[78:79], v[248:249] op_sel_hi:[1,0]
	v_pk_add_f32 v[118:119], v[118:119], 1.0 op_sel_hi:[1,0]
	v_pk_mul_f32 v[78:79], v[14:15], v[78:79]
	v_pk_fma_f32 v[78:79], v[118:119], v[78:79], v[94:95]
	v_pk_mul_f32 v[80:81], v[80:81], v[248:249] op_sel_hi:[1,0]
	v_pk_add_f32 v[120:121], v[120:121], 1.0 op_sel_hi:[1,0]
	v_pk_mul_f32 v[80:81], v[16:17], v[80:81]
	v_pk_fma_f32 v[80:81], v[120:121], v[80:81], v[96:97]
	v_cvt_pk_bf16_f32 v94, v78, v79
	v_cvt_pk_bf16_f32 v95, v80, v81
	global_store_dwordx2 v245, v[94:95], s[10:11] offset:1536
	s_add_i32 s21, s37, 1792
	s_mul_hi_u32 s7, s21, 0x38e38e39
	s_lshr_b32 s7, s7, 9
	s_mul_i32 s8, s7, 0x900
	s_sub_i32 s8, s21, s8
	s_lshl_b32 s9, s7, 11
	s_add_i32 s9, s9, s8
	s_add_i32 s9, s9, 0xffffff00
	s_lshl_b32 s10, s7, 8
	s_add_i32 s10, s10, s8
	s_cmpk_gt_i32 s8, 0xff
	s_cselect_b32 s9, s9, s10
	s_cselect_b32 s26, s12, s14
	s_cselect_b32 s27, s13, s15
	s_cselect_b32 s10, s7, 8
	s_lshl_b32 s9, s9, 12
	s_add_u32 s26, s26, s9
	s_addc_u32 s27, s27, 0
	s_add_i32 s10, s10, s82
	s_mul_i32 s10, s10, s24
	s_add_u32 s28, s58, s10
	s_addc_u32 s29, s59, 0
	s_add_u32 s28, s28, 0x0
	s_addc_u32 s29, s29, 0
	s_add_u32 s0, s28, 0x1000
	s_addc_u32 s1, s29, 0
	global_load_dwordx4 v[66:69], v244, s[26:27]
	global_load_dwordx4 v[70:73], v244, s[26:27] offset:1024
	global_load_dwordx4 v[74:77], v244, s[26:27] offset:2048
	global_load_dwordx4 v[78:81], v244, s[26:27] offset:3072
	global_load_dwordx4 v[82:85], v244, s[28:29]
	global_load_dwordx4 v[86:89], v244, s[28:29] offset:1024
	global_load_dwordx4 v[90:93], v244, s[28:29] offset:2048
	global_load_dwordx4 v[94:97], v244, s[28:29] offset:3072
	global_load_dwordx4 v[98:101], v244, s[0:1]
	global_load_dwordx4 v[102:105], v244, s[0:1] offset:1024
	global_load_dwordx4 v[106:109], v244, s[0:1] offset:2048
	global_load_dwordx4 v[118:121], v244, s[0:1] offset:3072
	s_waitcnt vmcnt(32)
; DI unsigned pk_bf16(float lo, float hi) { f32x2 v = {lo, hi}; bf16v2 b = __builtin_convertvector(v, bf16v2); return __builtin_bit_cast(unsigned, b); }
; DI float red64(float x) { for (int o = 32; o > 0; o >>= 1) x += __shfl_xor(x, o); return x; }
; DI void modnorm_rows(const Params& p, int l, int which  , bool from_inputs, bool skip_ctx, int w0, int wstride, int lane) {
;     ...
;   for (; i < nrows; i += wstride) {
;     const int row = rowof(i); const int b = row / TB, s = row % TB;
;     f32x4 v[4];
; #pragma unroll
;     for (int q = 0; q < 4; ++q) v[q] = vn[q];
;     if (i + wstride < nrows) {
;       const int rn = rowof(i + wstride); const float* src = xsrc_row(p, from_inputs, rn / TB, rn % TB);
; #pragma unroll
;       for (int q = 0; q < 4; ++q) vn[q] = *(const f32x4*)(src + q * 256 + lane * 4);
;     }
;     const float* mod = p.MOD + (size_t)(l * 9 + (s < NCTX ? 8 : b)) * 6144 + (which ? 3 * 1024 : 0);
;     f32x4 sh[4], sc[4];
; #pragma unroll
;     for (int q = 0; q < 4; ++q) { sh[q] = *(const f32x4*)(mod + q * 256 + lane * 4); sc[q] = *(const f32x4*)(mod + 1024 + q * 256 + lane * 4); }
;     float ss = 0.f;
; #pragma unroll
;     for (int q = 0; q < 4; ++q) ss += v[q][0] * v[q][0] + v[q][1] * v[q][1] + v[q][2] * v[q][2] + v[q][3] * v[q][3];
;     ss = red64(ss);
;     const float rs = rsqrtf(ss * (1.f / 1024.f) + EPSF);
;     bf16_t* dst = p.HY + (size_t)row * DM;
; #pragma unroll
;     for (int q = 0; q < 4; ++q) {
;       float o[4];
; #pragma unroll
;       for (int j = 0; j < 4; ++j) o[j] = (v[q][j] * rs * gg[q][j]) * (1.f + sc[q][j]) + sh[q][j];
;       u32x2 w = {pk_bf16(o[0], o[1]), pk_bf16(o[2], o[3])};
;       *(u32x2*)(dst + q * 256 + lane * 4) = w;
;     }
;   }
	v_pk_mul_f32 v[246:247], v[122:123], v[122:123]
	v_pk_fma_f32 v[246:247], v[124:125], v[124:125], v[246:247]
	v_pk_fma_f32 v[246:247], v[126:127], v[126:127], v[246:247]
	v_pk_fma_f32 v[246:247], v[128:129], v[128:129], v[246:247]
	v_pk_fma_f32 v[246:247], v[130:131], v[130:131], v[246:247]
	v_pk_fma_f32 v[246:247], v[132:133], v[132:133], v[246:247]
	v_pk_fma_f32 v[246:247], v[134:135], v[134:135], v[246:247]
	v_pk_fma_f32 v[246:247], v[136:137], v[136:137], v[246:247]
	s_nop 0
	v_add_f32_e32 v246, v246, v247
	s_nop 1
	v_add_f32_dpp v246, v246, v246 quad_perm:[1,0,3,2] row_mask:0xf bank_mask:0xf
	s_nop 1
	v_add_f32_dpp v246, v246, v246 quad_perm:[2,3,0,1] row_mask:0xf bank_mask:0xf
	s_nop 1
	v_add_f32_dpp v246, v246, v246 row_half_mirror row_mask:0xf bank_mask:0xf
	s_nop 1
	v_add_f32_dpp v246, v246, v246 row_mirror row_mask:0xf bank_mask:0xf
	s_nop 1
	v_add_f32_dpp v246, v246, v246 row_bcast:15 row_mask:0xa bank_mask:0xf
	s_nop 1
	v_add_f32_dpp v246, v246, v246 row_bcast:31 row_mask:0xc bank_mask:0xf
	s_nop 1
	v_readlane_b32 s0, v246, 63
	s_add_i32 s21, s37, 1280
	s_lshl_b32 s21, s21, 11
	s_add_u32 s10, s16, s21
	s_addc_u32 s11, s17, 0
	v_mov_b32_e32 v248, s0
	v_fmamk_f32 v248, v248, 0x3a800000, v143
	v_rsq_f32_e32 v248, v248
	s_nop 0
	v_pk_mul_f32 v[122:123], v[122:123], v[248:249] op_sel_hi:[1,0]
	v_pk_add_f32 v[176:177], v[176:177], 1.0 op_sel_hi:[1,0]
	v_pk_mul_f32 v[122:123], v[2:3], v[122:123]
	v_pk_fma_f32 v[122:123], v[176:177], v[122:123], v[160:161]
	v_pk_mul_f32 v[124:125], v[124:125], v[248:249] op_sel_hi:[1,0]
	v_pk_add_f32 v[178:179], v[178:179], 1.0 op_sel_hi:[1,0]
	v_pk_mul_f32 v[124:125], v[4:5], v[124:125]
	v_pk_fma_f32 v[124:125], v[178:179], v[124:125], v[162:163]
	v_cvt_pk_bf16_f32 v160, v122, v123
	v_cvt_pk_bf16_f32 v161, v124, v125
	global_store_dwordx2 v245, v[160:161], s[10:11]
	v_pk_mul_f32 v[126:127], v[126:127], v[248:249] op_sel_hi:[1,0]
	v_pk_add_f32 v[180:181], v[180:181], 1.0 op_sel_hi:[1,0]
	v_pk_mul_f32 v[126:127], v[6:7], v[126:127]
	v_pk_fma_f32 v[126:127], v[180:181], v[126:127], v[164:165]
	v_pk_mul_f32 v[128:129], v[128:129], v[248:249] op_sel_hi:[1,0]
	v_pk_add_f32 v[182:183], v[182:183], 1.0 op_sel_hi:[1,0]
	v_pk_mul_f32 v[128:129], v[8:9], v[128:129]
	v_pk_fma_f32 v[128:129], v[182:183], v[128:129], v[166:167]
	v_cvt_pk_bf16_f32 v164, v126, v127
	v_cvt_pk_bf16_f32 v165, v128, v129
	global_store_dwordx2 v245, v[164:165], s[10:11] offset:512
	v_pk_mul_f32 v[130:131], v[130:131], v[248:249] op_sel_hi:[1,0]
	v_pk_add_f32 v[184:185], v[184:185], 1.0 op_sel_hi:[1,0]
	v_pk_mul_f32 v[130:131], v[10:11], v[130:131]
	v_pk_fma_f32 v[130:131], v[184:185], v[130:131], v[168:169]
	v_pk_mul_f32 v[132:133], v[132:133], v[248:249] op_sel_hi:[1,0]
	v_pk_add_f32 v[186:187], v[186:187], 1.0 op_sel_hi:[1,0]
	v_pk_mul_f32 v[132:133], v[12:13], v[132:133]
	v_pk_fma_f32 v[132:133], v[186:187], v[132:133], v[170:171]
	v_cvt_pk_bf16_f32 v168, v130, v131
	v_cvt_pk_bf16_f32 v169, v132, v133
	global_store_dwordx2 v245, v[168:169], s[10:11] offset:1024
	v_pk_mul_f32 v[134:135], v[134:135], v[248:249] op_sel_hi:[1,0]
	v_pk_add_f32 v[188:189], v[188:189], 1.0 op_sel_hi:[1,0]
	v_pk_mul_f32 v[134:135], v[14:15], v[134:135]
	v_pk_fma_f32 v[134:135], v[188:189], v[134:135], v[172:173]
	v_pk_mul_f32 v[136:137], v[136:137], v[248:249] op_sel_hi:[1,0]
	v_pk_add_f32 v[190:191], v[190:191], 1.0 op_sel_hi:[1,0]
	v_pk_mul_f32 v[136:137], v[16:17], v[136:137]
	v_pk_fma_f32 v[136:137], v[190:191], v[136:137], v[174:175]
	v_cvt_pk_bf16_f32 v172, v134, v135
	v_cvt_pk_bf16_f32 v173, v136, v137
	global_store_dwordx2 v245, v[172:173], s[10:11] offset:1536
	s_add_i32 s21, s37, 2048
	s_mul_hi_u32 s7, s21, 0x38e38e39
	s_lshr_b32 s7, s7, 9
	s_mul_i32 s8, s7, 0x900
	s_sub_i32 s8, s21, s8
	s_lshl_b32 s9, s7, 11
	s_add_i32 s9, s9, s8
	s_add_i32 s9, s9, 0xffffff00
	s_lshl_b32 s10, s7, 8
	s_add_i32 s10, s10, s8
	s_cmpk_gt_i32 s8, 0xff
	s_cselect_b32 s9, s9, s10
	s_cselect_b32 s26, s12, s14
	s_cselect_b32 s27, s13, s15
	s_cselect_b32 s10, s7, 8
	s_lshl_b32 s9, s9, 12
	s_add_u32 s26, s26, s9
	s_addc_u32 s27, s27, 0
	s_add_i32 s10, s10, s82
	s_mul_i32 s10, s10, s24
	s_add_u32 s28, s58, s10
	s_addc_u32 s29, s59, 0
	s_add_u32 s28, s28, 0x0
	s_addc_u32 s29, s29, 0
	s_add_u32 s0, s28, 0x1000
	s_addc_u32 s1, s29, 0
	global_load_dwordx4 v[122:125], v244, s[26:27]
	global_load_dwordx4 v[126:129], v244, s[26:27] offset:1024
	global_load_dwordx4 v[130:133], v244, s[26:27] offset:2048
	global_load_dwordx4 v[134:137], v244, s[26:27] offset:3072
	global_load_dwordx4 v[160:163], v244, s[28:29]
	global_load_dwordx4 v[164:167], v244, s[28:29] offset:1024
	global_load_dwordx4 v[168:171], v244, s[28:29] offset:2048
	global_load_dwordx4 v[172:175], v244, s[28:29] offset:3072
	global_load_dwordx4 v[176:179], v244, s[0:1]
	global_load_dwordx4 v[180:183], v244, s[0:1] offset:1024
	global_load_dwordx4 v[184:187], v244, s[0:1] offset:2048
	global_load_dwordx4 v[188:191], v244, s[0:1] offset:3072
	s_waitcnt vmcnt(32)
; DI unsigned pk_bf16(float lo, float hi) { f32x2 v = {lo, hi}; bf16v2 b = __builtin_convertvector(v, bf16v2); return __builtin_bit_cast(unsigned, b); }
; DI float red64(float x) { for (int o = 32; o > 0; o >>= 1) x += __shfl_xor(x, o); return x; }
; DI void modnorm_rows(const Params& p, int l, int which  , bool from_inputs, bool skip_ctx, int w0, int wstride, int lane) {
;     ...
;   for (; i < nrows; i += wstride) {
;     const int row = rowof(i); const int b = row / TB, s = row % TB;
;     f32x4 v[4];
; #pragma unroll
;     for (int q = 0; q < 4; ++q) v[q] = vn[q];
;     if (i + wstride < nrows) {
;       const int rn = rowof(i + wstride); const float* src = xsrc_row(p, from_inputs, rn / TB, rn % TB);
; #pragma unroll
;       for (int q = 0; q < 4; ++q) vn[q] = *(const f32x4*)(src + q * 256 + lane * 4);
;     }
;     const float* mod = p.MOD + (size_t)(l * 9 + (s < NCTX ? 8 : b)) * 6144 + (which ? 3 * 1024 : 0);
;     f32x4 sh[4], sc[4];
; #pragma unroll
;     for (int q = 0; q < 4; ++q) { sh[q] = *(const f32x4*)(mod + q * 256 + lane * 4); sc[q] = *(const f32x4*)(mod + 1024 + q * 256 + lane * 4); }
;     float ss = 0.f;
; #pragma unroll
;     for (int q = 0; q < 4; ++q) ss += v[q][0] * v[q][0] + v[q][1] * v[q][1] + v[q][2] * v[q][2] + v[q][3] * v[q][3];
;     ss = red64(ss);
;     const float rs = rsqrtf(ss * (1.f / 1024.f) + EPSF);
;     bf16_t* dst = p.HY + (size_t)row * DM;
; #pragma unroll
;     for (int q = 0; q < 4; ++q) {
;       float o[4];
; #pragma unroll
;       for (int j = 0; j < 4; ++j) o[j] = (v[q][j] * rs * gg[q][j]) * (1.f + sc[q][j]) + sh[q][j];
;       u32x2 w = {pk_bf16(o[0], o[1]), pk_bf16(o[2], o[3])};
;       *(u32x2*)(dst + q * 256 + lane * 4) = w;
;     }
;   }
	v_pk_mul_f32 v[246:247], v[18:19], v[18:19]
	v_pk_fma_f32 v[246:247], v[20:21], v[20:21], v[246:247]
	v_pk_fma_f32 v[246:247], v[22:23], v[22:23], v[246:247]
	v_pk_fma_f32 v[246:247], v[24:25], v[24:25], v[246:247]
	v_pk_fma_f32 v[246:247], v[26:27], v[26:27], v[246:247]
	v_pk_fma_f32 v[246:247], v[28:29], v[28:29], v[246:247]
	v_pk_fma_f32 v[246:247], v[30:31], v[30:31], v[246:247]
	v_pk_fma_f32 v[246:247], v[32:33], v[32:33], v[246:247]
	s_nop 0
	v_add_f32_e32 v246, v246, v247
	s_nop 1
	v_add_f32_dpp v246, v246, v246 quad_perm:[1,0,3,2] row_mask:0xf bank_mask:0xf
	s_nop 1
	v_add_f32_dpp v246, v246, v246 quad_perm:[2,3,0,1] row_mask:0xf bank_mask:0xf
	s_nop 1
	v_add_f32_dpp v246, v246, v246 row_half_mirror row_mask:0xf bank_mask:0xf
	s_nop 1
	v_add_f32_dpp v246, v246, v246 row_mirror row_mask:0xf bank_mask:0xf
	s_nop 1
	v_add_f32_dpp v246, v246, v246 row_bcast:15 row_mask:0xa bank_mask:0xf
	s_nop 1
	v_add_f32_dpp v246, v246, v246 row_bcast:31 row_mask:0xc bank_mask:0xf
	s_nop 1
	v_readlane_b32 s0, v246, 63
	s_add_i32 s21, s37, 1536
	s_lshl_b32 s21, s21, 11
	s_add_u32 s10, s16, s21
	s_addc_u32 s11, s17, 0
	v_mov_b32_e32 v248, s0
	v_fmamk_f32 v248, v248, 0x3a800000, v143
	v_rsq_f32_e32 v248, v248
	s_nop 0
	v_pk_mul_f32 v[18:19], v[18:19], v[248:249] op_sel_hi:[1,0]
	v_pk_add_f32 v[50:51], v[50:51], 1.0 op_sel_hi:[1,0]
	v_pk_mul_f32 v[18:19], v[2:3], v[18:19]
	v_pk_fma_f32 v[18:19], v[50:51], v[18:19], v[34:35]
	v_pk_mul_f32 v[20:21], v[20:21], v[248:249] op_sel_hi:[1,0]
	v_pk_add_f32 v[52:53], v[52:53], 1.0 op_sel_hi:[1,0]
	v_pk_mul_f32 v[20:21], v[4:5], v[20:21]
	v_pk_fma_f32 v[20:21], v[52:53], v[20:21], v[36:37]
	v_cvt_pk_bf16_f32 v34, v18, v19
	v_cvt_pk_bf16_f32 v35, v20, v21
	global_store_dwordx2 v245, v[34:35], s[10:11]
	v_pk_mul_f32 v[22:23], v[22:23], v[248:249] op_sel_hi:[1,0]
	v_pk_add_f32 v[54:55], v[54:55], 1.0 op_sel_hi:[1,0]
	v_pk_mul_f32 v[22:23], v[6:7], v[22:23]
	v_pk_fma_f32 v[22:23], v[54:55], v[22:23], v[38:39]
	v_pk_mul_f32 v[24:25], v[24:25], v[248:249] op_sel_hi:[1,0]
	v_pk_add_f32 v[56:57], v[56:57], 1.0 op_sel_hi:[1,0]
	v_pk_mul_f32 v[24:25], v[8:9], v[24:25]
	v_pk_fma_f32 v[24:25], v[56:57], v[24:25], v[40:41]
	v_cvt_pk_bf16_f32 v38, v22, v23
	v_cvt_pk_bf16_f32 v39, v24, v25
	global_store_dwordx2 v245, v[38:39], s[10:11] offset:512
	v_pk_mul_f32 v[26:27], v[26:27], v[248:249] op_sel_hi:[1,0]
	v_pk_add_f32 v[58:59], v[58:59], 1.0 op_sel_hi:[1,0]
	v_pk_mul_f32 v[26:27], v[10:11], v[26:27]
	v_pk_fma_f32 v[26:27], v[58:59], v[26:27], v[42:43]
	v_pk_mul_f32 v[28:29], v[28:29], v[248:249] op_sel_hi:[1,0]
	v_pk_add_f32 v[60:61], v[60:61], 1.0 op_sel_hi:[1,0]
	v_pk_mul_f32 v[28:29], v[12:13], v[28:29]
	v_pk_fma_f32 v[28:29], v[60:61], v[28:29], v[44:45]
	v_cvt_pk_bf16_f32 v42, v26, v27
	v_cvt_pk_bf16_f32 v43, v28, v29
	global_store_dwordx2 v245, v[42:43], s[10:11] offset:1024
	v_pk_mul_f32 v[30:31], v[30:31], v[248:249] op_sel_hi:[1,0]
	v_pk_add_f32 v[62:63], v[62:63], 1.0 op_sel_hi:[1,0]
	v_pk_mul_f32 v[30:31], v[14:15], v[30:31]
	v_pk_fma_f32 v[30:31], v[62:63], v[30:31], v[46:47]
	v_pk_mul_f32 v[32:33], v[32:33], v[248:249] op_sel_hi:[1,0]
	v_pk_add_f32 v[64:65], v[64:65], 1.0 op_sel_hi:[1,0]
	v_pk_mul_f32 v[32:33], v[16:17], v[32:33]
	v_pk_fma_f32 v[32:33], v[64:65], v[32:33], v[48:49]
	v_cvt_pk_bf16_f32 v46, v30, v31
	v_cvt_pk_bf16_f32 v47, v32, v33
	global_store_dwordx2 v245, v[46:47], s[10:11] offset:1536
	s_waitcnt vmcnt(20)
	v_pk_mul_f32 v[246:247], v[66:67], v[66:67]
	v_pk_fma_f32 v[246:247], v[68:69], v[68:69], v[246:247]
	v_pk_fma_f32 v[246:247], v[70:71], v[70:71], v[246:247]
	v_pk_fma_f32 v[246:247], v[72:73], v[72:73], v[246:247]
	v_pk_fma_f32 v[246:247], v[74:75], v[74:75], v[246:247]
	v_pk_fma_f32 v[246:247], v[76:77], v[76:77], v[246:247]
	v_pk_fma_f32 v[246:247], v[78:79], v[78:79], v[246:247]
	v_pk_fma_f32 v[246:247], v[80:81], v[80:81], v[246:247]
	s_nop 0
	v_add_f32_e32 v246, v246, v247
	s_nop 1
	v_add_f32_dpp v246, v246, v246 quad_perm:[1,0,3,2] row_mask:0xf bank_mask:0xf
	s_nop 1
	v_add_f32_dpp v246, v246, v246 quad_perm:[2,3,0,1] row_mask:0xf bank_mask:0xf
	s_nop 1
	v_add_f32_dpp v246, v246, v246 row_half_mirror row_mask:0xf bank_mask:0xf
	s_nop 1
	v_add_f32_dpp v246, v246, v246 row_mirror row_mask:0xf bank_mask:0xf
	s_nop 1
	v_add_f32_dpp v246, v246, v246 row_bcast:15 row_mask:0xa bank_mask:0xf
	s_nop 1
	v_add_f32_dpp v246, v246, v246 row_bcast:31 row_mask:0xc bank_mask:0xf
	s_nop 1
	v_readlane_b32 s0, v246, 63
	s_add_i32 s21, s37, 1792
	s_lshl_b32 s21, s21, 11
	s_add_u32 s10, s16, s21
	s_addc_u32 s11, s17, 0
	v_mov_b32_e32 v248, s0
	v_fmamk_f32 v248, v248, 0x3a800000, v143
	v_rsq_f32_e32 v248, v248
	s_nop 0
	v_pk_mul_f32 v[66:67], v[66:67], v[248:249] op_sel_hi:[1,0]
	v_pk_add_f32 v[98:99], v[98:99], 1.0 op_sel_hi:[1,0]
	v_pk_mul_f32 v[66:67], v[2:3], v[66:67]
	v_pk_fma_f32 v[66:67], v[98:99], v[66:67], v[82:83]
	v_pk_mul_f32 v[68:69], v[68:69], v[248:249] op_sel_hi:[1,0]
	v_pk_add_f32 v[100:101], v[100:101], 1.0 op_sel_hi:[1,0]
	v_pk_mul_f32 v[68:69], v[4:5], v[68:69]
	v_pk_fma_f32 v[68:69], v[100:101], v[68:69], v[84:85]
	v_cvt_pk_bf16_f32 v82, v66, v67
	v_cvt_pk_bf16_f32 v83, v68, v69
	global_store_dwordx2 v245, v[82:83], s[10:11]
	v_pk_mul_f32 v[70:71], v[70:71], v[248:249] op_sel_hi:[1,0]
	v_pk_add_f32 v[102:103], v[102:103], 1.0 op_sel_hi:[1,0]
	v_pk_mul_f32 v[70:71], v[6:7], v[70:71]
	v_pk_fma_f32 v[70:71], v[102:103], v[70:71], v[86:87]
	v_pk_mul_f32 v[72:73], v[72:73], v[248:249] op_sel_hi:[1,0]
	v_pk_add_f32 v[104:105], v[104:105], 1.0 op_sel_hi:[1,0]
	v_pk_mul_f32 v[72:73], v[8:9], v[72:73]
	v_pk_fma_f32 v[72:73], v[104:105], v[72:73], v[88:89]
	v_cvt_pk_bf16_f32 v86, v70, v71
	v_cvt_pk_bf16_f32 v87, v72, v73
	global_store_dwordx2 v245, v[86:87], s[10:11] offset:512
	v_pk_mul_f32 v[74:75], v[74:75], v[248:249] op_sel_hi:[1,0]
	v_pk_add_f32 v[106:107], v[106:107], 1.0 op_sel_hi:[1,0]
	v_pk_mul_f32 v[74:75], v[10:11], v[74:75]
	v_pk_fma_f32 v[74:75], v[106:107], v[74:75], v[90:91]
	v_pk_mul_f32 v[76:77], v[76:77], v[248:249] op_sel_hi:[1,0]
	v_pk_add_f32 v[108:109], v[108:109], 1.0 op_sel_hi:[1,0]
	v_pk_mul_f32 v[76:77], v[12:13], v[76:77]
	v_pk_fma_f32 v[76:77], v[108:109], v[76:77], v[92:93]
	v_cvt_pk_bf16_f32 v90, v74, v75
	v_cvt_pk_bf16_f32 v91, v76, v77
	global_store_dwordx2 v245, v[90:91], s[10:11] offset:1024
	v_pk_mul_f32 v[78:79], v[78:79], v[248:249] op_sel_hi:[1,0]
	v_pk_add_f32 v[118:119], v[118:119], 1.0 op_sel_hi:[1,0]
	v_pk_mul_f32 v[78:79], v[14:15], v[78:79]
	v_pk_fma_f32 v[78:79], v[118:119], v[78:79], v[94:95]
	v_pk_mul_f32 v[80:81], v[80:81], v[248:249] op_sel_hi:[1,0]
	v_pk_add_f32 v[120:121], v[120:121], 1.0 op_sel_hi:[1,0]
	v_pk_mul_f32 v[80:81], v[16:17], v[80:81]
	v_pk_fma_f32 v[80:81], v[120:121], v[80:81], v[96:97]
	v_cvt_pk_bf16_f32 v94, v78, v79
	v_cvt_pk_bf16_f32 v95, v80, v81
	global_store_dwordx2 v245, v[94:95], s[10:11] offset:1536
	s_waitcnt vmcnt(8)
; DI unsigned pk_bf16(float lo, float hi) { f32x2 v = {lo, hi}; bf16v2 b = __builtin_convertvector(v, bf16v2); return __builtin_bit_cast(unsigned, b); }
; DI float red64(float x) { for (int o = 32; o > 0; o >>= 1) x += __shfl_xor(x, o); return x; }
; DI void modnorm_rows(const Params& p, int l, int which  , bool from_inputs, bool skip_ctx, int w0, int wstride, int lane) {
;     ...
;   for (; i < nrows; i += wstride) {
;     const int row = rowof(i); const int b = row / TB, s = row % TB;
;     f32x4 v[4];
; #pragma unroll
;     for (int q = 0; q < 4; ++q) v[q] = vn[q];
;     if (i + wstride < nrows) {
;       const int rn = rowof(i + wstride); const float* src = xsrc_row(p, from_inputs, rn / TB, rn % TB);
; #pragma unroll
;       for (int q = 0; q < 4; ++q) vn[q] = *(const f32x4*)(src + q * 256 + lane * 4);
;     }
;     const float* mod = p.MOD + (size_t)(l * 9 + (s < NCTX ? 8 : b)) * 6144 + (which ? 3 * 1024 : 0);
;     f32x4 sh[4], sc[4];
; #pragma unroll
;     for (int q = 0; q < 4; ++q) { sh[q] = *(const f32x4*)(mod + q * 256 + lane * 4); sc[q] = *(const f32x4*)(mod + 1024 + q * 256 + lane * 4); }
;     float ss = 0.f;
; #pragma unroll
;     for (int q = 0; q < 4; ++q) ss += v[q][0] * v[q][0] + v[q][1] * v[q][1] + v[q][2] * v[q][2] + v[q][3] * v[q][3];
;     ss = red64(ss);
;     const float rs = rsqrtf(ss * (1.f / 1024.f) + EPSF);
;     bf16_t* dst = p.HY + (size_t)row * DM;
; #pragma unroll
;     for (int q = 0; q < 4; ++q) {
;       float o[4];
; #pragma unroll
;       for (int j = 0; j < 4; ++j) o[j] = (v[q][j] * rs * gg[q][j]) * (1.f + sc[q][j]) + sh[q][j];
;       u32x2 w = {pk_bf16(o[0], o[1]), pk_bf16(o[2], o[3])};
;       *(u32x2*)(dst + q * 256 + lane * 4) = w;
;     }
;   }
	v_pk_mul_f32 v[246:247], v[122:123], v[122:123]
	v_pk_fma_f32 v[246:247], v[124:125], v[124:125], v[246:247]
	v_pk_fma_f32 v[246:247], v[126:127], v[126:127], v[246:247]
	v_pk_fma_f32 v[246:247], v[128:129], v[128:129], v[246:247]
	v_pk_fma_f32 v[246:247], v[130:131], v[130:131], v[246:247]
	v_pk_fma_f32 v[246:247], v[132:133], v[132:133], v[246:247]
	v_pk_fma_f32 v[246:247], v[134:135], v[134:135], v[246:247]
	v_pk_fma_f32 v[246:247], v[136:137], v[136:137], v[246:247]
	s_nop 0
	v_add_f32_e32 v246, v246, v247
	s_nop 1
	v_add_f32_dpp v246, v246, v246 quad_perm:[1,0,3,2] row_mask:0xf bank_mask:0xf
	s_nop 1
	v_add_f32_dpp v246, v246, v246 quad_perm:[2,3,0,1] row_mask:0xf bank_mask:0xf
	s_nop 1
	v_add_f32_dpp v246, v246, v246 row_half_mirror row_mask:0xf bank_mask:0xf
	s_nop 1
	v_add_f32_dpp v246, v246, v246 row_mirror row_mask:0xf bank_mask:0xf
	s_nop 1
	v_add_f32_dpp v246, v246, v246 row_bcast:15 row_mask:0xa bank_mask:0xf
	s_nop 1
	v_add_f32_dpp v246, v246, v246 row_bcast:31 row_mask:0xc bank_mask:0xf
	s_nop 1
	v_readlane_b32 s0, v246, 63
	s_add_i32 s21, s37, 2048
	s_lshl_b32 s21, s21, 11
	s_add_u32 s10, s16, s21
	s_addc_u32 s11, s17, 0
	v_mov_b32_e32 v248, s0
	v_fmamk_f32 v248, v248, 0x3a800000, v143
	v_rsq_f32_e32 v248, v248
	s_nop 0
	v_pk_mul_f32 v[122:123], v[122:123], v[248:249] op_sel_hi:[1,0]
	v_pk_add_f32 v[176:177], v[176:177], 1.0 op_sel_hi:[1,0]
	v_pk_mul_f32 v[122:123], v[2:3], v[122:123]
	v_pk_fma_f32 v[122:123], v[176:177], v[122:123], v[160:161]
	v_pk_mul_f32 v[124:125], v[124:125], v[248:249] op_sel_hi:[1,0]
	v_pk_add_f32 v[178:179], v[178:179], 1.0 op_sel_hi:[1,0]
	v_pk_mul_f32 v[124:125], v[4:5], v[124:125]
	v_pk_fma_f32 v[124:125], v[178:179], v[124:125], v[162:163]
	v_cvt_pk_bf16_f32 v160, v122, v123
	v_cvt_pk_bf16_f32 v161, v124, v125
	global_store_dwordx2 v245, v[160:161], s[10:11]
	v_pk_mul_f32 v[126:127], v[126:127], v[248:249] op_sel_hi:[1,0]
	v_pk_add_f32 v[180:181], v[180:181], 1.0 op_sel_hi:[1,0]
	v_pk_mul_f32 v[126:127], v[6:7], v[126:127]
	v_pk_fma_f32 v[126:127], v[180:181], v[126:127], v[164:165]
	v_pk_mul_f32 v[128:129], v[128:129], v[248:249] op_sel_hi:[1,0]
	v_pk_add_f32 v[182:183], v[182:183], 1.0 op_sel_hi:[1,0]
	v_pk_mul_f32 v[128:129], v[8:9], v[128:129]
	v_pk_fma_f32 v[128:129], v[182:183], v[128:129], v[166:167]
	v_cvt_pk_bf16_f32 v164, v126, v127
	v_cvt_pk_bf16_f32 v165, v128, v129
	global_store_dwordx2 v245, v[164:165], s[10:11] offset:512
	v_pk_mul_f32 v[130:131], v[130:131], v[248:249] op_sel_hi:[1,0]
	v_pk_add_f32 v[184:185], v[184:185], 1.0 op_sel_hi:[1,0]
	v_pk_mul_f32 v[130:131], v[10:11], v[130:131]
	v_pk_fma_f32 v[130:131], v[184:185], v[130:131], v[168:169]
	v_pk_mul_f32 v[132:133], v[132:133], v[248:249] op_sel_hi:[1,0]
	v_pk_add_f32 v[186:187], v[186:187], 1.0 op_sel_hi:[1,0]
	v_pk_mul_f32 v[132:133], v[12:13], v[132:133]
	v_pk_fma_f32 v[132:133], v[186:187], v[132:133], v[170:171]
	v_cvt_pk_bf16_f32 v168, v130, v131
	v_cvt_pk_bf16_f32 v169, v132, v133
	global_store_dwordx2 v245, v[168:169], s[10:11] offset:1024
	v_pk_mul_f32 v[134:135], v[134:135], v[248:249] op_sel_hi:[1,0]
	v_pk_add_f32 v[188:189], v[188:189], 1.0 op_sel_hi:[1,0]
	v_pk_mul_f32 v[134:135], v[14:15], v[134:135]
	v_pk_fma_f32 v[134:135], v[188:189], v[134:135], v[172:173]
	v_pk_mul_f32 v[136:137], v[136:137], v[248:249] op_sel_hi:[1,0]
	v_pk_add_f32 v[190:191], v[190:191], 1.0 op_sel_hi:[1,0]
	v_pk_mul_f32 v[136:137], v[16:17], v[136:137]
	v_pk_fma_f32 v[136:137], v[190:191], v[136:137], v[174:175]
	v_cvt_pk_bf16_f32 v172, v134, v135
	v_cvt_pk_bf16_f32 v173, v136, v137
	global_store_dwordx2 v245, v[172:173], s[10:11] offset:1536
	s_branch .Lnorm1_done
